# K loops: setprio 1 hoisted above the pre-MFMA barrier, setprio 0 sunk below the post-MFMA barrier, duplicate lgkmcnt(0) dropped
# speedup vs baseline: 1.0303x; 1.0116x over previous
.Lpz_P2b:
	s_and_b64 s[6:7], s[6:7], exec
	s_cselect_b32 s37, s41, s45
	s_cselect_b32 s39, s40, s44
	s_cselect_b32 s51, s43, s47
	s_cselect_b32 s65, s42, s46
	s_add_u32 s66, s46, 0x100
	s_addc_u32 s67, s47, 0
	s_mov_b32 s46, 0
	ds_read_b128 v[144:147], v166
	ds_read_b128 v[148:151], v166 offset:1024
	ds_read_b128 v[152:155], v166 offset:2048
	ds_read_b128 v[156:159], v166 offset:3072
	s_add_i32 s68, s46, 2
	s_add_u32 s6, s44, 0x100
	s_addc_u32 s7, s45, 0
	s_cmp_eq_u32 s60, s46
	s_cselect_b32 s46, s65, s66
	s_cselect_b32 s49, s37, s7
	s_cselect_b32 s48, s39, s6
	s_cselect_b32 s47, s51, s67
	v_lshl_add_u64 v[160:161], s[44:45], 0, v[136:137]
	s_add_i32 m0, s35, 0xc000
	ds_read_b128 v[170:173], v167
	ds_read_b128 v[174:177], v167 offset:1024
	ds_read_b128 v[178:181], v167 offset:2048
	ds_read_b128 v[182:185], v167 offset:3072
	ds_read_b128 v[186:189], v167 offset:4096
	ds_read_b128 v[190:193], v167 offset:5120
	ds_read_b128 v[194:197], v167 offset:6144
	ds_read_b128 v[198:201], v167 offset:7168
	global_load_lds_dwordx4 v[160:161], off
	v_lshl_add_u64 v[160:161], s[44:45], 0, v[138:139]
	s_add_i32 m0, s35, 0xe000
	s_nop 0
	global_load_lds_dwordx4 v[160:161], off
	s_waitcnt lgkmcnt(8)
	s_setprio 1
	s_barrier
	s_waitcnt lgkmcnt(0)
	v_mfma_f32_16x16x32_bf16 v[100:103], v[144:147], v[170:173], 0
	v_mfma_f32_16x16x32_bf16 v[88:91], v[152:155], v[170:173], 0
	v_mfma_f32_16x16x32_bf16 v[96:99], v[144:147], v[178:181], 0
	v_mfma_f32_16x16x32_bf16 v[80:83], v[152:155], v[178:181], 0
	v_mfma_f32_16x16x32_bf16 v[72:75], v[144:147], v[186:189], 0
	v_mfma_f32_16x16x32_bf16 v[60:63], v[152:155], v[186:189], 0
	v_mfma_f32_16x16x32_bf16 v[56:59], v[144:147], v[194:197], 0
	v_mfma_f32_16x16x32_bf16 v[48:51], v[152:155], v[194:197], 0
	v_mfma_f32_16x16x32_bf16 v[100:103], v[148:151], v[174:177], v[100:103]
	v_mfma_f32_16x16x32_bf16 v[88:91], v[156:159], v[174:177], v[88:91]
	v_mfma_f32_16x16x32_bf16 v[96:99], v[148:151], v[182:185], v[96:99]
	v_mfma_f32_16x16x32_bf16 v[80:83], v[156:159], v[182:185], v[80:83]
	v_mfma_f32_16x16x32_bf16 v[72:75], v[148:151], v[190:193], v[72:75]
	v_mfma_f32_16x16x32_bf16 v[60:63], v[156:159], v[190:193], v[60:63]
	v_mfma_f32_16x16x32_bf16 v[56:59], v[148:151], v[198:201], v[56:59]
	v_mfma_f32_16x16x32_bf16 v[48:51], v[156:159], v[198:201], v[48:51]
	s_barrier
	s_setprio 0
	s_add_i32 s44, s62, s52
	v_lshl_add_u64 v[160:161], s[46:47], 0, v[132:133]
	s_mov_b32 m0, s44
	ds_read_b128 v[202:205], v168
	ds_read_b128 v[206:209], v168 offset:1024
	ds_read_b128 v[210:213], v168 offset:2048
	ds_read_b128 v[214:217], v168 offset:3072
	global_load_lds_dwordx4 v[160:161], off
	v_lshl_add_u64 v[218:219], s[46:47], 0, v[128:129]
	s_add_i32 m0, s44, 0x2000
	s_nop 0
	global_load_lds_dwordx4 v[218:219], off
	s_setprio 1
	s_barrier
	s_waitcnt lgkmcnt(0)
	v_mfma_f32_16x16x32_bf16 v[92:95], v[202:205], v[170:173], 0
	v_mfma_f32_16x16x32_bf16 v[108:111], v[210:213], v[170:173], 0
	v_mfma_f32_16x16x32_bf16 v[84:87], v[202:205], v[178:181], 0
	v_mfma_f32_16x16x32_bf16 v[104:107], v[210:213], v[178:181], 0
	v_mfma_f32_16x16x32_bf16 v[64:67], v[202:205], v[186:189], 0
	v_mfma_f32_16x16x32_bf16 v[76:79], v[210:213], v[186:189], 0
	v_mfma_f32_16x16x32_bf16 v[52:55], v[202:205], v[194:197], 0
	v_mfma_f32_16x16x32_bf16 v[68:71], v[210:213], v[194:197], 0
	v_mfma_f32_16x16x32_bf16 v[92:95], v[206:209], v[174:177], v[92:95]
	v_mfma_f32_16x16x32_bf16 v[108:111], v[214:217], v[174:177], v[108:111]
	v_mfma_f32_16x16x32_bf16 v[84:87], v[206:209], v[182:185], v[84:87]
	v_mfma_f32_16x16x32_bf16 v[104:107], v[214:217], v[182:185], v[104:107]
	v_mfma_f32_16x16x32_bf16 v[64:67], v[206:209], v[190:193], v[64:67]
	v_mfma_f32_16x16x32_bf16 v[76:79], v[214:217], v[190:193], v[76:79]
	v_mfma_f32_16x16x32_bf16 v[52:55], v[206:209], v[198:201], v[52:55]
	v_mfma_f32_16x16x32_bf16 v[68:71], v[214:217], v[198:201], v[68:71]
	s_mov_b32 m0, s35
	v_lshl_add_u64 v[220:221], s[48:49], 0, v[134:135]
	s_barrier
	s_setprio 0
	ds_read_b128 v[170:173], v167 offset:16384
	ds_read_b128 v[174:177], v167 offset:17408
	ds_read_b128 v[178:181], v167 offset:18432
	ds_read_b128 v[182:185], v167 offset:19456
	ds_read_b128 v[186:189], v167 offset:20480
	ds_read_b128 v[190:193], v167 offset:21504
	ds_read_b128 v[194:197], v167 offset:22528
	ds_read_b128 v[198:201], v167 offset:23552
	global_load_lds_dwordx4 v[220:221], off
	v_lshl_add_u64 v[224:225], s[48:49], 0, v[130:131]
	s_mov_b32 m0, s53
	s_nop 0
	global_load_lds_dwordx4 v[224:225], off
	s_setprio 1
	s_barrier
	s_waitcnt lgkmcnt(0)
	v_mfma_f32_16x16x32_bf16 v[40:43], v[144:147], v[170:173], 0
	v_mfma_f32_16x16x32_bf16 v[32:35], v[152:155], v[170:173], 0
	v_mfma_f32_16x16x32_bf16 v[24:27], v[144:147], v[178:181], 0
	v_mfma_f32_16x16x32_bf16 v[20:23], v[152:155], v[178:181], 0
	v_mfma_f32_16x16x32_bf16 v[4:7], v[144:147], v[186:189], 0
	v_mfma_f32_16x16x32_bf16 v[124:127], v[152:155], v[186:189], 0
	v_mfma_f32_16x16x32_bf16 v[0:3], v[144:147], v[194:197], 0
	v_mfma_f32_16x16x32_bf16 v[116:119], v[152:155], v[194:197], 0
	v_mfma_f32_16x16x32_bf16 v[40:43], v[148:151], v[174:177], v[40:43]
	v_mfma_f32_16x16x32_bf16 v[32:35], v[156:159], v[174:177], v[32:35]
	v_mfma_f32_16x16x32_bf16 v[24:27], v[148:151], v[182:185], v[24:27]
	v_mfma_f32_16x16x32_bf16 v[20:23], v[156:159], v[182:185], v[20:23]
	v_mfma_f32_16x16x32_bf16 v[4:7], v[148:151], v[190:193], v[4:7]
	v_mfma_f32_16x16x32_bf16 v[124:127], v[156:159], v[190:193], v[124:127]
	v_mfma_f32_16x16x32_bf16 v[0:3], v[148:151], v[198:201], v[0:3]
	v_mfma_f32_16x16x32_bf16 v[116:119], v[156:159], v[198:201], v[116:119]
	s_barrier
	s_setprio 0
	s_add_u32 s44, s46, 0x40000
	s_addc_u32 s45, s47, 0
	s_add_i32 s69, s64, s52
	v_lshl_add_u64 v[144:145], s[44:45], 0, v[132:133]
	s_mov_b32 m0, s69
	s_nop 0
	global_load_lds_dwordx4 v[144:145], off
	v_lshl_add_u64 v[144:145], s[44:45], 0, v[128:129]
	s_add_i32 m0, s69, 0x2000
	s_nop 0
	global_load_lds_dwordx4 v[144:145], off
	s_waitcnt vmcnt(6)
	s_setprio 1
	s_barrier
	v_mfma_f32_16x16x32_bf16 v[28:31], v[202:205], v[170:173], 0
	v_mfma_f32_16x16x32_bf16 v[44:47], v[210:213], v[170:173], 0
	v_mfma_f32_16x16x32_bf16 v[16:19], v[202:205], v[178:181], 0
	v_mfma_f32_16x16x32_bf16 v[36:39], v[210:213], v[178:181], 0
	v_mfma_f32_16x16x32_bf16 v[120:123], v[202:205], v[186:189], 0
	v_mfma_f32_16x16x32_bf16 v[12:15], v[210:213], v[186:189], 0
	v_mfma_f32_16x16x32_bf16 v[112:115], v[202:205], v[194:197], 0
	v_mfma_f32_16x16x32_bf16 v[8:11], v[210:213], v[194:197], 0
	v_mfma_f32_16x16x32_bf16 v[28:31], v[206:209], v[174:177], v[28:31]
	v_mfma_f32_16x16x32_bf16 v[44:47], v[214:217], v[174:177], v[44:47]
	v_mfma_f32_16x16x32_bf16 v[16:19], v[206:209], v[182:185], v[16:19]
	v_mfma_f32_16x16x32_bf16 v[36:39], v[214:217], v[182:185], v[36:39]
	v_mfma_f32_16x16x32_bf16 v[120:123], v[206:209], v[190:193], v[120:123]
	v_mfma_f32_16x16x32_bf16 v[12:15], v[214:217], v[190:193], v[12:15]
	v_mfma_f32_16x16x32_bf16 v[112:115], v[206:209], v[198:201], v[112:115]
	v_mfma_f32_16x16x32_bf16 v[8:11], v[214:217], v[198:201], v[8:11]
	s_add_i32 s69, 0, 0x18000
	v_add_u32_e32 v156, s69, v163
	s_barrier
	s_setprio 0
	ds_read_b128 v[144:147], v156
	ds_read_b128 v[148:151], v156 offset:1024
	ds_read_b128 v[152:155], v156 offset:2048
	ds_read_b128 v[156:159], v156 offset:3072
	s_add_u32 s44, s48, 0x2000
	s_addc_u32 s45, s49, 0
	s_mov_b32 m0, s54
	v_lshl_add_u64 v[202:203], s[44:45], 0, v[134:135]
	ds_read_b128 v[170:173], v167 offset:32768
	ds_read_b128 v[174:177], v167 offset:33792
	ds_read_b128 v[178:181], v167 offset:34816
	ds_read_b128 v[182:185], v167 offset:35840
	ds_read_b128 v[186:189], v167 offset:36864
	ds_read_b128 v[190:193], v167 offset:37888
	ds_read_b128 v[194:197], v167 offset:38912
	ds_read_b128 v[198:201], v167 offset:39936
	global_load_lds_dwordx4 v[202:203], off
	v_lshl_add_u64 v[202:203], s[44:45], 0, v[130:131]
	s_mov_b32 m0, s55
	s_nop 0
	global_load_lds_dwordx4 v[202:203], off
	s_waitcnt lgkmcnt(8)
	s_setprio 1
	s_barrier
	s_waitcnt lgkmcnt(0)
	v_mfma_f32_16x16x32_bf16 v[100:103], v[144:147], v[170:173], v[100:103]
	v_mfma_f32_16x16x32_bf16 v[88:91], v[152:155], v[170:173], v[88:91]
	v_mfma_f32_16x16x32_bf16 v[96:99], v[144:147], v[178:181], v[96:99]
	v_mfma_f32_16x16x32_bf16 v[80:83], v[152:155], v[178:181], v[80:83]
	v_mfma_f32_16x16x32_bf16 v[72:75], v[144:147], v[186:189], v[72:75]
	v_mfma_f32_16x16x32_bf16 v[60:63], v[152:155], v[186:189], v[60:63]
	v_mfma_f32_16x16x32_bf16 v[56:59], v[144:147], v[194:197], v[56:59]
	v_mfma_f32_16x16x32_bf16 v[48:51], v[152:155], v[194:197], v[48:51]
	v_mfma_f32_16x16x32_bf16 v[100:103], v[148:151], v[174:177], v[100:103]
	v_mfma_f32_16x16x32_bf16 v[88:91], v[156:159], v[174:177], v[88:91]
	v_mfma_f32_16x16x32_bf16 v[96:99], v[148:151], v[182:185], v[96:99]
	v_mfma_f32_16x16x32_bf16 v[80:83], v[156:159], v[182:185], v[80:83]
	v_mfma_f32_16x16x32_bf16 v[72:75], v[148:151], v[190:193], v[72:75]
	v_mfma_f32_16x16x32_bf16 v[60:63], v[156:159], v[190:193], v[60:63]
	v_mfma_f32_16x16x32_bf16 v[56:59], v[148:151], v[198:201], v[56:59]
	v_mfma_f32_16x16x32_bf16 v[48:51], v[156:159], v[198:201], v[48:51]
	s_barrier
	s_setprio 0
	s_add_i32 s48, 0, 0x1c000
	s_add_i32 s44, s69, s52
	v_add_u32_e32 v169, s48, v163
	v_lshl_add_u64 v[160:161], v[160:161], 0, s[20:21]
	s_mov_b32 m0, s44
	ds_read_b128 v[202:205], v169
	ds_read_b128 v[206:209], v169 offset:1024
	ds_read_b128 v[210:213], v169 offset:2048
	ds_read_b128 v[214:217], v169 offset:3072
	global_load_lds_dwordx4 v[160:161], off
	v_lshl_add_u64 v[160:161], v[218:219], 0, s[20:21]
	s_add_i32 m0, s44, 0x2000
	s_nop 0
	global_load_lds_dwordx4 v[160:161], off
	s_setprio 1
	s_barrier
	s_waitcnt lgkmcnt(0)
	v_mfma_f32_16x16x32_bf16 v[92:95], v[202:205], v[170:173], v[92:95]
	v_mfma_f32_16x16x32_bf16 v[108:111], v[210:213], v[170:173], v[108:111]
	v_mfma_f32_16x16x32_bf16 v[84:87], v[202:205], v[178:181], v[84:87]
	v_mfma_f32_16x16x32_bf16 v[104:107], v[210:213], v[178:181], v[104:107]
	v_mfma_f32_16x16x32_bf16 v[64:67], v[202:205], v[186:189], v[64:67]
	v_mfma_f32_16x16x32_bf16 v[76:79], v[210:213], v[186:189], v[76:79]
	v_mfma_f32_16x16x32_bf16 v[52:55], v[202:205], v[194:197], v[52:55]
	v_mfma_f32_16x16x32_bf16 v[68:71], v[210:213], v[194:197], v[68:71]
	v_mfma_f32_16x16x32_bf16 v[92:95], v[206:209], v[174:177], v[92:95]
	v_mfma_f32_16x16x32_bf16 v[108:111], v[214:217], v[174:177], v[108:111]
	v_mfma_f32_16x16x32_bf16 v[84:87], v[206:209], v[182:185], v[84:87]
	v_mfma_f32_16x16x32_bf16 v[104:107], v[214:217], v[182:185], v[104:107]
	v_mfma_f32_16x16x32_bf16 v[64:67], v[206:209], v[190:193], v[64:67]
	v_mfma_f32_16x16x32_bf16 v[76:79], v[214:217], v[190:193], v[76:79]
	v_mfma_f32_16x16x32_bf16 v[52:55], v[206:209], v[198:201], v[52:55]
	v_mfma_f32_16x16x32_bf16 v[68:71], v[214:217], v[198:201], v[68:71]
	s_mov_b32 m0, s57
	v_lshl_add_u64 v[160:161], v[220:221], 0, s[20:21]
	s_barrier
	s_setprio 0
	ds_read_b128 v[170:173], v167 offset:49152
	ds_read_b128 v[174:177], v167 offset:50176
	ds_read_b128 v[178:181], v167 offset:51200
	ds_read_b128 v[182:185], v167 offset:52224
	ds_read_b128 v[186:189], v167 offset:53248
	ds_read_b128 v[190:193], v167 offset:54272
	ds_read_b128 v[194:197], v167 offset:55296
	ds_read_b128 v[198:201], v167 offset:56320
	global_load_lds_dwordx4 v[160:161], off
	v_lshl_add_u64 v[160:161], v[224:225], 0, s[20:21]
	s_mov_b32 m0, s58
	s_nop 0
	global_load_lds_dwordx4 v[160:161], off
	s_setprio 1
	s_barrier
	s_waitcnt lgkmcnt(0)
	v_mfma_f32_16x16x32_bf16 v[40:43], v[144:147], v[170:173], v[40:43]
	v_mfma_f32_16x16x32_bf16 v[32:35], v[152:155], v[170:173], v[32:35]
	v_mfma_f32_16x16x32_bf16 v[24:27], v[144:147], v[178:181], v[24:27]
	v_mfma_f32_16x16x32_bf16 v[20:23], v[152:155], v[178:181], v[20:23]
	v_mfma_f32_16x16x32_bf16 v[4:7], v[144:147], v[186:189], v[4:7]
	v_mfma_f32_16x16x32_bf16 v[124:127], v[152:155], v[186:189], v[124:127]
	v_mfma_f32_16x16x32_bf16 v[0:3], v[144:147], v[194:197], v[0:3]
	v_mfma_f32_16x16x32_bf16 v[116:119], v[152:155], v[194:197], v[116:119]
	v_mfma_f32_16x16x32_bf16 v[40:43], v[148:151], v[174:177], v[40:43]
	v_mfma_f32_16x16x32_bf16 v[32:35], v[156:159], v[174:177], v[32:35]
	v_mfma_f32_16x16x32_bf16 v[24:27], v[148:151], v[182:185], v[24:27]
	v_mfma_f32_16x16x32_bf16 v[20:23], v[156:159], v[182:185], v[20:23]
	v_mfma_f32_16x16x32_bf16 v[4:7], v[148:151], v[190:193], v[4:7]
	v_mfma_f32_16x16x32_bf16 v[124:127], v[156:159], v[190:193], v[124:127]
	v_mfma_f32_16x16x32_bf16 v[0:3], v[148:151], v[198:201], v[0:3]
	v_mfma_f32_16x16x32_bf16 v[116:119], v[156:159], v[198:201], v[116:119]
	s_barrier
	s_setprio 0
	s_add_u32 s44, s46, 0x40080
	s_addc_u32 s45, s47, 0
	s_add_i32 s46, s48, s52
	v_lshl_add_u64 v[144:145], s[44:45], 0, v[132:133]
	s_mov_b32 m0, s46
	s_nop 0
	global_load_lds_dwordx4 v[144:145], off
	v_lshl_add_u64 v[144:145], s[44:45], 0, v[128:129]
	s_add_i32 m0, s46, 0x2000
	s_nop 0
	global_load_lds_dwordx4 v[144:145], off
	s_waitcnt vmcnt(6)
	s_setprio 1
	s_barrier
	v_mfma_f32_16x16x32_bf16 v[28:31], v[202:205], v[170:173], v[28:31]
	v_mfma_f32_16x16x32_bf16 v[44:47], v[210:213], v[170:173], v[44:47]
	v_mfma_f32_16x16x32_bf16 v[16:19], v[202:205], v[178:181], v[16:19]
	v_mfma_f32_16x16x32_bf16 v[36:39], v[210:213], v[178:181], v[36:39]
	v_mfma_f32_16x16x32_bf16 v[120:123], v[202:205], v[186:189], v[120:123]
	v_mfma_f32_16x16x32_bf16 v[12:15], v[210:213], v[186:189], v[12:15]
	v_mfma_f32_16x16x32_bf16 v[112:115], v[202:205], v[194:197], v[112:115]
	v_mfma_f32_16x16x32_bf16 v[8:11], v[210:213], v[194:197], v[8:11]
	v_mfma_f32_16x16x32_bf16 v[28:31], v[206:209], v[174:177], v[28:31]
	v_mfma_f32_16x16x32_bf16 v[44:47], v[214:217], v[174:177], v[44:47]
	v_mfma_f32_16x16x32_bf16 v[16:19], v[206:209], v[182:185], v[16:19]
	v_mfma_f32_16x16x32_bf16 v[36:39], v[214:217], v[182:185], v[36:39]
	v_mfma_f32_16x16x32_bf16 v[120:123], v[206:209], v[190:193], v[120:123]
	v_mfma_f32_16x16x32_bf16 v[12:15], v[214:217], v[190:193], v[12:15]
	v_mfma_f32_16x16x32_bf16 v[112:115], v[206:209], v[198:201], v[112:115]
	v_mfma_f32_16x16x32_bf16 v[8:11], v[214:217], v[198:201], v[8:11]
	s_add_u32 s66, s66, 0x100
	s_addc_u32 s67, s67, 0
	s_cmp_lt_i32 s68, s56
	s_mov_b64 s[44:45], s[6:7]
	s_mov_b32 s46, s68
	s_barrier
	s_setprio 0
	s_cbranch_scc0 .Lpeel_done_P2b
.LBB0_312:
	ds_read_b128 v[144:147], v166
	ds_read_b128 v[148:151], v166 offset:1024
	ds_read_b128 v[152:155], v166 offset:2048
	ds_read_b128 v[156:159], v166 offset:3072
	s_add_i32 s68, s46, 2
	s_add_u32 s6, s44, 0x100
	s_addc_u32 s7, s45, 0
	s_cmp_eq_u32 s60, s46
	s_cselect_b32 s46, s65, s66
	s_cselect_b32 s49, s37, s7
	s_cselect_b32 s48, s39, s6
	s_cselect_b32 s47, s51, s67
	v_lshl_add_u64 v[160:161], s[44:45], 0, v[136:137]
	s_add_i32 m0, s35, 0xc000
	ds_read_b128 v[170:173], v167
	ds_read_b128 v[174:177], v167 offset:1024
	ds_read_b128 v[178:181], v167 offset:2048
	ds_read_b128 v[182:185], v167 offset:3072
	ds_read_b128 v[186:189], v167 offset:4096
	ds_read_b128 v[190:193], v167 offset:5120
	ds_read_b128 v[194:197], v167 offset:6144
	ds_read_b128 v[198:201], v167 offset:7168
	global_load_lds_dwordx4 v[160:161], off
	v_lshl_add_u64 v[160:161], s[44:45], 0, v[138:139]
	s_add_i32 m0, s35, 0xe000
	s_nop 0
	global_load_lds_dwordx4 v[160:161], off
	s_waitcnt lgkmcnt(8)
	s_setprio 1
	s_barrier
	s_waitcnt lgkmcnt(0)
	v_mfma_f32_16x16x32_bf16 v[100:103], v[144:147], v[170:173], v[100:103]
	v_mfma_f32_16x16x32_bf16 v[88:91], v[152:155], v[170:173], v[88:91]
	v_mfma_f32_16x16x32_bf16 v[96:99], v[144:147], v[178:181], v[96:99]
	v_mfma_f32_16x16x32_bf16 v[80:83], v[152:155], v[178:181], v[80:83]
	v_mfma_f32_16x16x32_bf16 v[72:75], v[144:147], v[186:189], v[72:75]
	v_mfma_f32_16x16x32_bf16 v[60:63], v[152:155], v[186:189], v[60:63]
	v_mfma_f32_16x16x32_bf16 v[56:59], v[144:147], v[194:197], v[56:59]
	v_mfma_f32_16x16x32_bf16 v[48:51], v[152:155], v[194:197], v[48:51]
	v_mfma_f32_16x16x32_bf16 v[100:103], v[148:151], v[174:177], v[100:103]
	v_mfma_f32_16x16x32_bf16 v[88:91], v[156:159], v[174:177], v[88:91]
	v_mfma_f32_16x16x32_bf16 v[96:99], v[148:151], v[182:185], v[96:99]
	v_mfma_f32_16x16x32_bf16 v[80:83], v[156:159], v[182:185], v[80:83]
	v_mfma_f32_16x16x32_bf16 v[72:75], v[148:151], v[190:193], v[72:75]
	v_mfma_f32_16x16x32_bf16 v[60:63], v[156:159], v[190:193], v[60:63]
	v_mfma_f32_16x16x32_bf16 v[56:59], v[148:151], v[198:201], v[56:59]
	v_mfma_f32_16x16x32_bf16 v[48:51], v[156:159], v[198:201], v[48:51]
	s_barrier
	s_setprio 0
	s_add_i32 s44, s62, s52
	v_lshl_add_u64 v[160:161], s[46:47], 0, v[132:133]
	s_mov_b32 m0, s44
	ds_read_b128 v[202:205], v168
	ds_read_b128 v[206:209], v168 offset:1024
	ds_read_b128 v[210:213], v168 offset:2048
	ds_read_b128 v[214:217], v168 offset:3072
	global_load_lds_dwordx4 v[160:161], off
	v_lshl_add_u64 v[218:219], s[46:47], 0, v[128:129]
	s_add_i32 m0, s44, 0x2000
	s_nop 0
	global_load_lds_dwordx4 v[218:219], off
	s_setprio 1
	s_barrier
	s_waitcnt lgkmcnt(0)
	v_mfma_f32_16x16x32_bf16 v[92:95], v[202:205], v[170:173], v[92:95]
	v_mfma_f32_16x16x32_bf16 v[108:111], v[210:213], v[170:173], v[108:111]
	v_mfma_f32_16x16x32_bf16 v[84:87], v[202:205], v[178:181], v[84:87]
	v_mfma_f32_16x16x32_bf16 v[104:107], v[210:213], v[178:181], v[104:107]
	v_mfma_f32_16x16x32_bf16 v[64:67], v[202:205], v[186:189], v[64:67]
	v_mfma_f32_16x16x32_bf16 v[76:79], v[210:213], v[186:189], v[76:79]
	v_mfma_f32_16x16x32_bf16 v[52:55], v[202:205], v[194:197], v[52:55]
	v_mfma_f32_16x16x32_bf16 v[68:71], v[210:213], v[194:197], v[68:71]
	v_mfma_f32_16x16x32_bf16 v[92:95], v[206:209], v[174:177], v[92:95]
	v_mfma_f32_16x16x32_bf16 v[108:111], v[214:217], v[174:177], v[108:111]
	v_mfma_f32_16x16x32_bf16 v[84:87], v[206:209], v[182:185], v[84:87]
	v_mfma_f32_16x16x32_bf16 v[104:107], v[214:217], v[182:185], v[104:107]
	v_mfma_f32_16x16x32_bf16 v[64:67], v[206:209], v[190:193], v[64:67]
	v_mfma_f32_16x16x32_bf16 v[76:79], v[214:217], v[190:193], v[76:79]
	v_mfma_f32_16x16x32_bf16 v[52:55], v[206:209], v[198:201], v[52:55]
	v_mfma_f32_16x16x32_bf16 v[68:71], v[214:217], v[198:201], v[68:71]
	s_mov_b32 m0, s35
	v_lshl_add_u64 v[220:221], s[48:49], 0, v[134:135]
	s_barrier
	s_setprio 0
	ds_read_b128 v[170:173], v167 offset:16384
	ds_read_b128 v[174:177], v167 offset:17408
	ds_read_b128 v[178:181], v167 offset:18432
	ds_read_b128 v[182:185], v167 offset:19456
	ds_read_b128 v[186:189], v167 offset:20480
	ds_read_b128 v[190:193], v167 offset:21504
	ds_read_b128 v[194:197], v167 offset:22528
	ds_read_b128 v[198:201], v167 offset:23552
	global_load_lds_dwordx4 v[220:221], off
	v_lshl_add_u64 v[224:225], s[48:49], 0, v[130:131]
	s_mov_b32 m0, s53
	s_nop 0
	global_load_lds_dwordx4 v[224:225], off
	s_setprio 1
	s_barrier
	s_waitcnt lgkmcnt(0)
	v_mfma_f32_16x16x32_bf16 v[40:43], v[144:147], v[170:173], v[40:43]
	v_mfma_f32_16x16x32_bf16 v[32:35], v[152:155], v[170:173], v[32:35]
	v_mfma_f32_16x16x32_bf16 v[24:27], v[144:147], v[178:181], v[24:27]
	v_mfma_f32_16x16x32_bf16 v[20:23], v[152:155], v[178:181], v[20:23]
	v_mfma_f32_16x16x32_bf16 v[4:7], v[144:147], v[186:189], v[4:7]
	v_mfma_f32_16x16x32_bf16 v[124:127], v[152:155], v[186:189], v[124:127]
	v_mfma_f32_16x16x32_bf16 v[0:3], v[144:147], v[194:197], v[0:3]
	v_mfma_f32_16x16x32_bf16 v[116:119], v[152:155], v[194:197], v[116:119]
	v_mfma_f32_16x16x32_bf16 v[40:43], v[148:151], v[174:177], v[40:43]
	v_mfma_f32_16x16x32_bf16 v[32:35], v[156:159], v[174:177], v[32:35]
	v_mfma_f32_16x16x32_bf16 v[24:27], v[148:151], v[182:185], v[24:27]
	v_mfma_f32_16x16x32_bf16 v[20:23], v[156:159], v[182:185], v[20:23]
	v_mfma_f32_16x16x32_bf16 v[4:7], v[148:151], v[190:193], v[4:7]
	v_mfma_f32_16x16x32_bf16 v[124:127], v[156:159], v[190:193], v[124:127]
	v_mfma_f32_16x16x32_bf16 v[0:3], v[148:151], v[198:201], v[0:3]
	v_mfma_f32_16x16x32_bf16 v[116:119], v[156:159], v[198:201], v[116:119]
	s_barrier
	s_setprio 0
	s_add_u32 s44, s46, 0x40000
	s_addc_u32 s45, s47, 0
	s_add_i32 s69, s64, s52
	v_lshl_add_u64 v[144:145], s[44:45], 0, v[132:133]
	s_mov_b32 m0, s69
	s_nop 0
	global_load_lds_dwordx4 v[144:145], off
	v_lshl_add_u64 v[144:145], s[44:45], 0, v[128:129]
	s_add_i32 m0, s69, 0x2000
	s_nop 0
	global_load_lds_dwordx4 v[144:145], off
	s_waitcnt vmcnt(6)
	s_setprio 1
	s_barrier
	v_mfma_f32_16x16x32_bf16 v[28:31], v[202:205], v[170:173], v[28:31]
	v_mfma_f32_16x16x32_bf16 v[44:47], v[210:213], v[170:173], v[44:47]
	v_mfma_f32_16x16x32_bf16 v[16:19], v[202:205], v[178:181], v[16:19]
	v_mfma_f32_16x16x32_bf16 v[36:39], v[210:213], v[178:181], v[36:39]
	v_mfma_f32_16x16x32_bf16 v[120:123], v[202:205], v[186:189], v[120:123]
	v_mfma_f32_16x16x32_bf16 v[12:15], v[210:213], v[186:189], v[12:15]
	v_mfma_f32_16x16x32_bf16 v[112:115], v[202:205], v[194:197], v[112:115]
	v_mfma_f32_16x16x32_bf16 v[8:11], v[210:213], v[194:197], v[8:11]
	v_mfma_f32_16x16x32_bf16 v[28:31], v[206:209], v[174:177], v[28:31]
	v_mfma_f32_16x16x32_bf16 v[44:47], v[214:217], v[174:177], v[44:47]
	v_mfma_f32_16x16x32_bf16 v[16:19], v[206:209], v[182:185], v[16:19]
	v_mfma_f32_16x16x32_bf16 v[36:39], v[214:217], v[182:185], v[36:39]
	v_mfma_f32_16x16x32_bf16 v[120:123], v[206:209], v[190:193], v[120:123]
	v_mfma_f32_16x16x32_bf16 v[12:15], v[214:217], v[190:193], v[12:15]
	v_mfma_f32_16x16x32_bf16 v[112:115], v[206:209], v[198:201], v[112:115]
	v_mfma_f32_16x16x32_bf16 v[8:11], v[214:217], v[198:201], v[8:11]
	s_add_i32 s69, 0, 0x18000
	v_add_u32_e32 v156, s69, v163
	s_barrier
	s_setprio 0
	ds_read_b128 v[144:147], v156
	ds_read_b128 v[148:151], v156 offset:1024
	ds_read_b128 v[152:155], v156 offset:2048
	ds_read_b128 v[156:159], v156 offset:3072
	s_add_u32 s44, s48, 0x2000
	s_addc_u32 s45, s49, 0
	s_mov_b32 m0, s54
	v_lshl_add_u64 v[202:203], s[44:45], 0, v[134:135]
	ds_read_b128 v[170:173], v167 offset:32768
	ds_read_b128 v[174:177], v167 offset:33792
	ds_read_b128 v[178:181], v167 offset:34816
	ds_read_b128 v[182:185], v167 offset:35840
	ds_read_b128 v[186:189], v167 offset:36864
	ds_read_b128 v[190:193], v167 offset:37888
	ds_read_b128 v[194:197], v167 offset:38912
	ds_read_b128 v[198:201], v167 offset:39936
	global_load_lds_dwordx4 v[202:203], off
	v_lshl_add_u64 v[202:203], s[44:45], 0, v[130:131]
	s_mov_b32 m0, s55
	s_nop 0
	global_load_lds_dwordx4 v[202:203], off
	s_waitcnt lgkmcnt(8)
	s_setprio 1
	s_barrier
	s_waitcnt lgkmcnt(0)
	v_mfma_f32_16x16x32_bf16 v[100:103], v[144:147], v[170:173], v[100:103]
	v_mfma_f32_16x16x32_bf16 v[88:91], v[152:155], v[170:173], v[88:91]
	v_mfma_f32_16x16x32_bf16 v[96:99], v[144:147], v[178:181], v[96:99]
	v_mfma_f32_16x16x32_bf16 v[80:83], v[152:155], v[178:181], v[80:83]
	v_mfma_f32_16x16x32_bf16 v[72:75], v[144:147], v[186:189], v[72:75]
	v_mfma_f32_16x16x32_bf16 v[60:63], v[152:155], v[186:189], v[60:63]
	v_mfma_f32_16x16x32_bf16 v[56:59], v[144:147], v[194:197], v[56:59]
	v_mfma_f32_16x16x32_bf16 v[48:51], v[152:155], v[194:197], v[48:51]
	v_mfma_f32_16x16x32_bf16 v[100:103], v[148:151], v[174:177], v[100:103]
	v_mfma_f32_16x16x32_bf16 v[88:91], v[156:159], v[174:177], v[88:91]
	v_mfma_f32_16x16x32_bf16 v[96:99], v[148:151], v[182:185], v[96:99]
	v_mfma_f32_16x16x32_bf16 v[80:83], v[156:159], v[182:185], v[80:83]
	v_mfma_f32_16x16x32_bf16 v[72:75], v[148:151], v[190:193], v[72:75]
	v_mfma_f32_16x16x32_bf16 v[60:63], v[156:159], v[190:193], v[60:63]
	v_mfma_f32_16x16x32_bf16 v[56:59], v[148:151], v[198:201], v[56:59]
	v_mfma_f32_16x16x32_bf16 v[48:51], v[156:159], v[198:201], v[48:51]
	s_barrier
	s_setprio 0
	s_add_i32 s48, 0, 0x1c000
	s_add_i32 s44, s69, s52
	v_add_u32_e32 v169, s48, v163
	v_lshl_add_u64 v[160:161], v[160:161], 0, s[20:21]
	s_mov_b32 m0, s44
	ds_read_b128 v[202:205], v169
	ds_read_b128 v[206:209], v169 offset:1024
	ds_read_b128 v[210:213], v169 offset:2048
	ds_read_b128 v[214:217], v169 offset:3072
	global_load_lds_dwordx4 v[160:161], off
	v_lshl_add_u64 v[160:161], v[218:219], 0, s[20:21]
	s_add_i32 m0, s44, 0x2000
	s_nop 0
	global_load_lds_dwordx4 v[160:161], off
	s_setprio 1
	s_barrier
	s_waitcnt lgkmcnt(0)
	v_mfma_f32_16x16x32_bf16 v[92:95], v[202:205], v[170:173], v[92:95]
	v_mfma_f32_16x16x32_bf16 v[108:111], v[210:213], v[170:173], v[108:111]
	v_mfma_f32_16x16x32_bf16 v[84:87], v[202:205], v[178:181], v[84:87]
	v_mfma_f32_16x16x32_bf16 v[104:107], v[210:213], v[178:181], v[104:107]
	v_mfma_f32_16x16x32_bf16 v[64:67], v[202:205], v[186:189], v[64:67]
	v_mfma_f32_16x16x32_bf16 v[76:79], v[210:213], v[186:189], v[76:79]
	v_mfma_f32_16x16x32_bf16 v[52:55], v[202:205], v[194:197], v[52:55]
	v_mfma_f32_16x16x32_bf16 v[68:71], v[210:213], v[194:197], v[68:71]
	v_mfma_f32_16x16x32_bf16 v[92:95], v[206:209], v[174:177], v[92:95]
	v_mfma_f32_16x16x32_bf16 v[108:111], v[214:217], v[174:177], v[108:111]
	v_mfma_f32_16x16x32_bf16 v[84:87], v[206:209], v[182:185], v[84:87]
	v_mfma_f32_16x16x32_bf16 v[104:107], v[214:217], v[182:185], v[104:107]
	v_mfma_f32_16x16x32_bf16 v[64:67], v[206:209], v[190:193], v[64:67]
	v_mfma_f32_16x16x32_bf16 v[76:79], v[214:217], v[190:193], v[76:79]
	v_mfma_f32_16x16x32_bf16 v[52:55], v[206:209], v[198:201], v[52:55]
	v_mfma_f32_16x16x32_bf16 v[68:71], v[214:217], v[198:201], v[68:71]
	s_mov_b32 m0, s57
	v_lshl_add_u64 v[160:161], v[220:221], 0, s[20:21]
	s_barrier
	s_setprio 0
	ds_read_b128 v[170:173], v167 offset:49152
	ds_read_b128 v[174:177], v167 offset:50176
	ds_read_b128 v[178:181], v167 offset:51200
	ds_read_b128 v[182:185], v167 offset:52224
	ds_read_b128 v[186:189], v167 offset:53248
	ds_read_b128 v[190:193], v167 offset:54272
	ds_read_b128 v[194:197], v167 offset:55296
	ds_read_b128 v[198:201], v167 offset:56320
	global_load_lds_dwordx4 v[160:161], off
	v_lshl_add_u64 v[160:161], v[224:225], 0, s[20:21]
	s_mov_b32 m0, s58
	s_nop 0
	global_load_lds_dwordx4 v[160:161], off
	s_setprio 1
	s_barrier
	s_waitcnt lgkmcnt(0)
	v_mfma_f32_16x16x32_bf16 v[40:43], v[144:147], v[170:173], v[40:43]
	v_mfma_f32_16x16x32_bf16 v[32:35], v[152:155], v[170:173], v[32:35]
	v_mfma_f32_16x16x32_bf16 v[24:27], v[144:147], v[178:181], v[24:27]
	v_mfma_f32_16x16x32_bf16 v[20:23], v[152:155], v[178:181], v[20:23]
	v_mfma_f32_16x16x32_bf16 v[4:7], v[144:147], v[186:189], v[4:7]
	v_mfma_f32_16x16x32_bf16 v[124:127], v[152:155], v[186:189], v[124:127]
	v_mfma_f32_16x16x32_bf16 v[0:3], v[144:147], v[194:197], v[0:3]
	v_mfma_f32_16x16x32_bf16 v[116:119], v[152:155], v[194:197], v[116:119]
	v_mfma_f32_16x16x32_bf16 v[40:43], v[148:151], v[174:177], v[40:43]
	v_mfma_f32_16x16x32_bf16 v[32:35], v[156:159], v[174:177], v[32:35]
	v_mfma_f32_16x16x32_bf16 v[24:27], v[148:151], v[182:185], v[24:27]
	v_mfma_f32_16x16x32_bf16 v[20:23], v[156:159], v[182:185], v[20:23]
	v_mfma_f32_16x16x32_bf16 v[4:7], v[148:151], v[190:193], v[4:7]
	v_mfma_f32_16x16x32_bf16 v[124:127], v[156:159], v[190:193], v[124:127]
	v_mfma_f32_16x16x32_bf16 v[0:3], v[148:151], v[198:201], v[0:3]
	v_mfma_f32_16x16x32_bf16 v[116:119], v[156:159], v[198:201], v[116:119]
	s_barrier
	s_setprio 0
	s_add_u32 s44, s46, 0x40080
	s_addc_u32 s45, s47, 0
	s_add_i32 s46, s48, s52
	v_lshl_add_u64 v[144:145], s[44:45], 0, v[132:133]
	s_mov_b32 m0, s46
	s_nop 0
	global_load_lds_dwordx4 v[144:145], off
	v_lshl_add_u64 v[144:145], s[44:45], 0, v[128:129]
	s_add_i32 m0, s46, 0x2000
	s_nop 0
	global_load_lds_dwordx4 v[144:145], off
	s_waitcnt vmcnt(6)
	s_setprio 1
	s_barrier
	v_mfma_f32_16x16x32_bf16 v[28:31], v[202:205], v[170:173], v[28:31]
	v_mfma_f32_16x16x32_bf16 v[44:47], v[210:213], v[170:173], v[44:47]
	v_mfma_f32_16x16x32_bf16 v[16:19], v[202:205], v[178:181], v[16:19]
	v_mfma_f32_16x16x32_bf16 v[36:39], v[210:213], v[178:181], v[36:39]
	v_mfma_f32_16x16x32_bf16 v[120:123], v[202:205], v[186:189], v[120:123]
	v_mfma_f32_16x16x32_bf16 v[12:15], v[210:213], v[186:189], v[12:15]
	v_mfma_f32_16x16x32_bf16 v[112:115], v[202:205], v[194:197], v[112:115]
	v_mfma_f32_16x16x32_bf16 v[8:11], v[210:213], v[194:197], v[8:11]
	v_mfma_f32_16x16x32_bf16 v[28:31], v[206:209], v[174:177], v[28:31]
	v_mfma_f32_16x16x32_bf16 v[44:47], v[214:217], v[174:177], v[44:47]
	v_mfma_f32_16x16x32_bf16 v[16:19], v[206:209], v[182:185], v[16:19]
	v_mfma_f32_16x16x32_bf16 v[36:39], v[214:217], v[182:185], v[36:39]
	v_mfma_f32_16x16x32_bf16 v[120:123], v[206:209], v[190:193], v[120:123]
	v_mfma_f32_16x16x32_bf16 v[12:15], v[214:217], v[190:193], v[12:15]
	v_mfma_f32_16x16x32_bf16 v[112:115], v[206:209], v[198:201], v[112:115]
	v_mfma_f32_16x16x32_bf16 v[8:11], v[214:217], v[198:201], v[8:11]
	s_add_u32 s66, s66, 0x100
	s_addc_u32 s67, s67, 0
	s_cmp_lt_i32 s68, s56
	s_mov_b64 s[44:45], s[6:7]
	s_mov_b32 s46, s68
	s_barrier
	s_setprio 0
	s_cbranch_scc1 .LBB0_312

.Lzskip_P2g:
	s_and_b64 s[6:7], s[6:7], exec
	s_cselect_b32 s45, s49, s57
	s_cselect_b32 s47, s48, s56
	s_cselect_b32 s71, s51, s55
	s_cselect_b32 s72, s50, s54
	s_add_u32 s6, s56, 0x20080
	s_addc_u32 s7, s57, 0
	s_add_u32 s73, s54, 0x100
	s_addc_u32 s74, s55, 0
	s_mov_b32 s54, 0
	v_add_u32_e32 v154, s64, v195
	ds_read_b128 v[142:145], v154
	ds_read_b128 v[146:149], v154 offset:1024
	ds_read_b128 v[150:153], v154 offset:2048
	ds_read_b128 v[154:157], v154 offset:3072
	s_add_i32 s75, s54, 2
	s_add_u32 s55, s6, 0xfffe0080
	s_addc_u32 s56, s7, -1
	s_cmp_eq_u32 s63, s54
	s_cselect_b32 s54, s72, s73
	s_cselect_b32 s57, s45, s56
	s_cselect_b32 s56, s47, s55
	s_cselect_b32 s55, s71, s74
	v_lshl_add_u64 v[190:191], s[6:7], 0, v[134:135]
	s_add_i32 m0, s19, 0xc000
	ds_read_b128 v[158:161], v201
	ds_read_b128 v[162:165], v201 offset:1024
	ds_read_b128 v[166:169], v201 offset:2048
	ds_read_b128 v[170:173], v201 offset:3072
	ds_read_b128 v[174:177], v201 offset:4096
	ds_read_b128 v[178:181], v201 offset:5120
	ds_read_b128 v[182:185], v201 offset:6144
	ds_read_b128 v[186:189], v201 offset:7168
	global_load_lds_dwordx4 v[190:191], off
	v_lshl_add_u64 v[190:191], s[6:7], 0, v[136:137]
	s_add_i32 m0, s19, 0xe000
	s_nop 0
	global_load_lds_dwordx4 v[190:191], off
	s_waitcnt lgkmcnt(8)
	s_setprio 1
	s_barrier
	s_waitcnt lgkmcnt(0)
	v_mfma_i32_16x16x64_i8 v[124:127], v[142:145], v[158:161], 0
	v_mfma_i32_16x16x64_i8 v[120:123], v[150:153], v[158:161], 0
	v_mfma_i32_16x16x64_i8 v[116:119], v[142:145], v[166:169], 0
	v_mfma_i32_16x16x64_i8 v[112:115], v[150:153], v[166:169], 0
	v_mfma_i32_16x16x64_i8 v[108:111], v[142:145], v[174:177], 0
	v_mfma_i32_16x16x64_i8 v[104:107], v[150:153], v[174:177], 0
	v_mfma_i32_16x16x64_i8 v[100:103], v[142:145], v[182:185], 0
	v_mfma_i32_16x16x64_i8 v[96:99], v[150:153], v[182:185], 0
	v_mfma_i32_16x16x64_i8 v[124:127], v[146:149], v[162:165], v[124:127]
	v_mfma_i32_16x16x64_i8 v[120:123], v[154:157], v[162:165], v[120:123]
	v_mfma_i32_16x16x64_i8 v[116:119], v[146:149], v[170:173], v[116:119]
	v_mfma_i32_16x16x64_i8 v[112:115], v[154:157], v[170:173], v[112:115]
	v_mfma_i32_16x16x64_i8 v[108:111], v[146:149], v[178:181], v[108:111]
	v_mfma_i32_16x16x64_i8 v[104:107], v[154:157], v[178:181], v[104:107]
	v_mfma_i32_16x16x64_i8 v[100:103], v[146:149], v[186:189], v[100:103]
	v_mfma_i32_16x16x64_i8 v[96:99], v[154:157], v[186:189], v[96:99]
	s_barrier
	s_setprio 0
	v_add_u32_e32 v190, s65, v195
	s_add_i32 s76, s64, s18
	ds_read_b128 v[204:207], v190
	ds_read_b128 v[208:211], v190 offset:1024
	ds_read_b128 v[212:215], v190 offset:2048
	ds_read_b128 v[216:219], v190 offset:3072
	v_lshl_add_u64 v[190:191], s[54:55], 0, v[130:131]
	s_mov_b32 m0, s76
	v_lshl_add_u64 v[220:221], s[54:55], 0, v[128:129]
	global_load_lds_dwordx4 v[190:191], off
	s_add_i32 m0, s76, 0x2000
	s_nop 0
	global_load_lds_dwordx4 v[220:221], off
	s_setprio 1
	s_barrier
	s_waitcnt lgkmcnt(0)
	v_mfma_i32_16x16x64_i8 v[92:95], v[204:207], v[158:161], 0
	v_mfma_i32_16x16x64_i8 v[88:91], v[212:215], v[158:161], 0
	v_mfma_i32_16x16x64_i8 v[84:87], v[204:207], v[166:169], 0
	v_mfma_i32_16x16x64_i8 v[80:83], v[212:215], v[166:169], 0
	v_mfma_i32_16x16x64_i8 v[76:79], v[204:207], v[174:177], 0
	v_mfma_i32_16x16x64_i8 v[72:75], v[212:215], v[174:177], 0
	v_mfma_i32_16x16x64_i8 v[68:71], v[204:207], v[182:185], 0
	v_mfma_i32_16x16x64_i8 v[64:67], v[212:215], v[182:185], 0
	v_mfma_i32_16x16x64_i8 v[92:95], v[208:211], v[162:165], v[92:95]
	v_mfma_i32_16x16x64_i8 v[88:91], v[216:219], v[162:165], v[88:91]
	v_mfma_i32_16x16x64_i8 v[84:87], v[208:211], v[170:173], v[84:87]
	v_mfma_i32_16x16x64_i8 v[80:83], v[216:219], v[170:173], v[80:83]
	v_mfma_i32_16x16x64_i8 v[76:79], v[208:211], v[178:181], v[76:79]
	v_mfma_i32_16x16x64_i8 v[72:75], v[216:219], v[178:181], v[72:75]
	v_mfma_i32_16x16x64_i8 v[68:71], v[208:211], v[186:189], v[68:71]
	v_mfma_i32_16x16x64_i8 v[64:67], v[216:219], v[186:189], v[64:67]
	s_mov_b32 m0, s19
	v_lshl_add_u64 v[224:225], s[56:57], 0, v[130:131]
	s_barrier
	s_setprio 0
	ds_read_b128 v[158:161], v201 offset:16384
	ds_read_b128 v[162:165], v201 offset:17408
	ds_read_b128 v[166:169], v201 offset:18432
	ds_read_b128 v[170:173], v201 offset:19456
	ds_read_b128 v[174:177], v201 offset:20480
	ds_read_b128 v[178:181], v201 offset:21504
	ds_read_b128 v[182:185], v201 offset:22528
	ds_read_b128 v[186:189], v201 offset:23552
	global_load_lds_dwordx4 v[224:225], off
	v_lshl_add_u64 v[228:229], s[56:57], 0, v[128:129]
	s_mov_b32 m0, s53
	s_nop 0
	global_load_lds_dwordx4 v[228:229], off
	s_setprio 1
	s_barrier
	s_waitcnt lgkmcnt(0)
	v_mfma_i32_16x16x64_i8 v[60:63], v[142:145], v[158:161], 0
	v_mfma_i32_16x16x64_i8 v[56:59], v[150:153], v[158:161], 0
	v_mfma_i32_16x16x64_i8 v[52:55], v[142:145], v[166:169], 0
	v_mfma_i32_16x16x64_i8 v[48:51], v[150:153], v[166:169], 0
	v_mfma_i32_16x16x64_i8 v[44:47], v[142:145], v[174:177], 0
	v_mfma_i32_16x16x64_i8 v[40:43], v[150:153], v[174:177], 0
	v_mfma_i32_16x16x64_i8 v[36:39], v[142:145], v[182:185], 0
	v_mfma_i32_16x16x64_i8 v[32:35], v[150:153], v[182:185], 0
	v_mfma_i32_16x16x64_i8 v[60:63], v[146:149], v[162:165], v[60:63]
	v_mfma_i32_16x16x64_i8 v[56:59], v[154:157], v[162:165], v[56:59]
	v_mfma_i32_16x16x64_i8 v[52:55], v[146:149], v[170:173], v[52:55]
	v_mfma_i32_16x16x64_i8 v[48:51], v[154:157], v[170:173], v[48:51]
	v_mfma_i32_16x16x64_i8 v[44:47], v[146:149], v[178:181], v[44:47]
	v_mfma_i32_16x16x64_i8 v[40:43], v[154:157], v[178:181], v[40:43]
	v_mfma_i32_16x16x64_i8 v[36:39], v[146:149], v[186:189], v[36:39]
	v_mfma_i32_16x16x64_i8 v[32:35], v[154:157], v[186:189], v[32:35]
	s_barrier
	s_setprio 0
	s_add_u32 s76, s54, 0x20000
	s_addc_u32 s77, s55, 0
	s_add_i32 s78, s65, s18
	v_lshl_add_u64 v[142:143], s[76:77], 0, v[130:131]
	s_mov_b32 m0, s78
	s_nop 0
	global_load_lds_dwordx4 v[142:143], off
	v_lshl_add_u64 v[142:143], s[76:77], 0, v[128:129]
	s_add_i32 m0, s78, 0x2000
	s_nop 0
	global_load_lds_dwordx4 v[142:143], off
	s_waitcnt vmcnt(6)
	s_setprio 1
	s_barrier
	v_mfma_i32_16x16x64_i8 v[28:31], v[204:207], v[158:161], 0
	v_mfma_i32_16x16x64_i8 v[24:27], v[212:215], v[158:161], 0
	v_mfma_i32_16x16x64_i8 v[20:23], v[204:207], v[166:169], 0
	v_mfma_i32_16x16x64_i8 v[16:19], v[212:215], v[166:169], 0
	v_mfma_i32_16x16x64_i8 v[12:15], v[204:207], v[174:177], 0
	v_mfma_i32_16x16x64_i8 v[8:11], v[212:215], v[174:177], 0
	v_mfma_i32_16x16x64_i8 v[4:7], v[204:207], v[182:185], 0
	v_mfma_i32_16x16x64_i8 v[0:3], v[212:215], v[182:185], 0
	v_mfma_i32_16x16x64_i8 v[28:31], v[208:211], v[162:165], v[28:31]
	v_mfma_i32_16x16x64_i8 v[24:27], v[216:219], v[162:165], v[24:27]
	v_mfma_i32_16x16x64_i8 v[20:23], v[208:211], v[170:173], v[20:23]
	v_mfma_i32_16x16x64_i8 v[16:19], v[216:219], v[170:173], v[16:19]
	v_mfma_i32_16x16x64_i8 v[12:15], v[208:211], v[178:181], v[12:15]
	v_mfma_i32_16x16x64_i8 v[8:11], v[216:219], v[178:181], v[8:11]
	v_mfma_i32_16x16x64_i8 v[4:7], v[208:211], v[186:189], v[4:7]
	v_mfma_i32_16x16x64_i8 v[0:3], v[216:219], v[186:189], v[0:3]
	s_add_i32 s76, 0, 0x18000
	v_add_u32_e32 v154, s76, v195
	s_barrier
	s_setprio 0
	ds_read_b128 v[142:145], v154
	ds_read_b128 v[146:149], v154 offset:1024
	ds_read_b128 v[150:153], v154 offset:2048
	ds_read_b128 v[154:157], v154 offset:3072
	s_add_u32 s56, s56, 0x20000
	s_addc_u32 s57, s57, 0
	s_mov_b32 m0, s58
	v_lshl_add_u64 v[204:205], s[56:57], 0, v[130:131]
	ds_read_b128 v[158:161], v201 offset:32768
	ds_read_b128 v[162:165], v201 offset:33792
	ds_read_b128 v[166:169], v201 offset:34816
	ds_read_b128 v[170:173], v201 offset:35840
	ds_read_b128 v[174:177], v201 offset:36864
	ds_read_b128 v[178:181], v201 offset:37888
	ds_read_b128 v[182:185], v201 offset:38912
	ds_read_b128 v[186:189], v201 offset:39936
	global_load_lds_dwordx4 v[204:205], off
	v_lshl_add_u64 v[204:205], s[56:57], 0, v[128:129]
	s_mov_b32 m0, s59
	s_nop 0
	global_load_lds_dwordx4 v[204:205], off
	s_waitcnt lgkmcnt(8)
	s_setprio 1
	s_barrier
	s_waitcnt lgkmcnt(0)
	v_mfma_i32_16x16x64_i8 v[124:127], v[142:145], v[158:161], v[124:127]
	v_mfma_i32_16x16x64_i8 v[120:123], v[150:153], v[158:161], v[120:123]
	v_mfma_i32_16x16x64_i8 v[116:119], v[142:145], v[166:169], v[116:119]
	v_mfma_i32_16x16x64_i8 v[112:115], v[150:153], v[166:169], v[112:115]
	v_mfma_i32_16x16x64_i8 v[108:111], v[142:145], v[174:177], v[108:111]
	v_mfma_i32_16x16x64_i8 v[104:107], v[150:153], v[174:177], v[104:107]
	v_mfma_i32_16x16x64_i8 v[100:103], v[142:145], v[182:185], v[100:103]
	v_mfma_i32_16x16x64_i8 v[96:99], v[150:153], v[182:185], v[96:99]
	v_mfma_i32_16x16x64_i8 v[124:127], v[146:149], v[162:165], v[124:127]
	v_mfma_i32_16x16x64_i8 v[120:123], v[154:157], v[162:165], v[120:123]
	v_mfma_i32_16x16x64_i8 v[116:119], v[146:149], v[170:173], v[116:119]
	v_mfma_i32_16x16x64_i8 v[112:115], v[154:157], v[170:173], v[112:115]
	v_mfma_i32_16x16x64_i8 v[108:111], v[146:149], v[178:181], v[108:111]
	v_mfma_i32_16x16x64_i8 v[104:107], v[154:157], v[178:181], v[104:107]
	v_mfma_i32_16x16x64_i8 v[100:103], v[146:149], v[186:189], v[100:103]
	v_mfma_i32_16x16x64_i8 v[96:99], v[154:157], v[186:189], v[96:99]
	s_barrier
	s_setprio 0
	s_add_i32 s56, 0, 0x1c000
	s_add_i32 s57, s76, s18
	v_add_u32_e32 v192, s56, v195
	v_lshl_add_u64 v[190:191], v[190:191], 0, s[30:31]
	s_mov_b32 m0, s57
	ds_read_b128 v[204:207], v192
	ds_read_b128 v[208:211], v192 offset:1024
	ds_read_b128 v[212:215], v192 offset:2048
	ds_read_b128 v[216:219], v192 offset:3072
	global_load_lds_dwordx4 v[190:191], off
	v_lshl_add_u64 v[190:191], v[220:221], 0, s[30:31]
	s_add_i32 m0, s57, 0x2000
	s_nop 0
	global_load_lds_dwordx4 v[190:191], off
	s_setprio 1
	s_barrier
	s_waitcnt lgkmcnt(0)
	v_mfma_i32_16x16x64_i8 v[92:95], v[204:207], v[158:161], v[92:95]
	v_mfma_i32_16x16x64_i8 v[88:91], v[212:215], v[158:161], v[88:91]
	v_mfma_i32_16x16x64_i8 v[84:87], v[204:207], v[166:169], v[84:87]
	v_mfma_i32_16x16x64_i8 v[80:83], v[212:215], v[166:169], v[80:83]
	v_mfma_i32_16x16x64_i8 v[76:79], v[204:207], v[174:177], v[76:79]
	v_mfma_i32_16x16x64_i8 v[72:75], v[212:215], v[174:177], v[72:75]
	v_mfma_i32_16x16x64_i8 v[68:71], v[204:207], v[182:185], v[68:71]
	v_mfma_i32_16x16x64_i8 v[64:67], v[212:215], v[182:185], v[64:67]
	v_mfma_i32_16x16x64_i8 v[92:95], v[208:211], v[162:165], v[92:95]
	v_mfma_i32_16x16x64_i8 v[88:91], v[216:219], v[162:165], v[88:91]
	v_mfma_i32_16x16x64_i8 v[84:87], v[208:211], v[170:173], v[84:87]
	v_mfma_i32_16x16x64_i8 v[80:83], v[216:219], v[170:173], v[80:83]
	v_mfma_i32_16x16x64_i8 v[76:79], v[208:211], v[178:181], v[76:79]
	v_mfma_i32_16x16x64_i8 v[72:75], v[216:219], v[178:181], v[72:75]
	v_mfma_i32_16x16x64_i8 v[68:71], v[208:211], v[186:189], v[68:71]
	v_mfma_i32_16x16x64_i8 v[64:67], v[216:219], v[186:189], v[64:67]
	s_mov_b32 m0, s61
	v_lshl_add_u64 v[190:191], v[224:225], 0, s[30:31]
	s_barrier
	s_setprio 0
	ds_read_b128 v[158:161], v201 offset:49152
	ds_read_b128 v[162:165], v201 offset:50176
	ds_read_b128 v[166:169], v201 offset:51200
	ds_read_b128 v[170:173], v201 offset:52224
	ds_read_b128 v[174:177], v201 offset:53248
	ds_read_b128 v[178:181], v201 offset:54272
	ds_read_b128 v[182:185], v201 offset:55296
	ds_read_b128 v[186:189], v201 offset:56320
	global_load_lds_dwordx4 v[190:191], off
	v_lshl_add_u64 v[190:191], v[228:229], 0, s[30:31]
	s_mov_b32 m0, s62
	s_nop 0
	global_load_lds_dwordx4 v[190:191], off
	s_setprio 1
	s_barrier
	s_waitcnt lgkmcnt(0)
	v_mfma_i32_16x16x64_i8 v[60:63], v[142:145], v[158:161], v[60:63]
	v_mfma_i32_16x16x64_i8 v[56:59], v[150:153], v[158:161], v[56:59]
	v_mfma_i32_16x16x64_i8 v[52:55], v[142:145], v[166:169], v[52:55]
	v_mfma_i32_16x16x64_i8 v[48:51], v[150:153], v[166:169], v[48:51]
	v_mfma_i32_16x16x64_i8 v[44:47], v[142:145], v[174:177], v[44:47]
	v_mfma_i32_16x16x64_i8 v[40:43], v[150:153], v[174:177], v[40:43]
	v_mfma_i32_16x16x64_i8 v[36:39], v[142:145], v[182:185], v[36:39]
	v_mfma_i32_16x16x64_i8 v[32:35], v[150:153], v[182:185], v[32:35]
	v_mfma_i32_16x16x64_i8 v[60:63], v[146:149], v[162:165], v[60:63]
	v_mfma_i32_16x16x64_i8 v[56:59], v[154:157], v[162:165], v[56:59]
	v_mfma_i32_16x16x64_i8 v[52:55], v[146:149], v[170:173], v[52:55]
	v_mfma_i32_16x16x64_i8 v[48:51], v[154:157], v[170:173], v[48:51]
	v_mfma_i32_16x16x64_i8 v[44:47], v[146:149], v[178:181], v[44:47]
	v_mfma_i32_16x16x64_i8 v[40:43], v[154:157], v[178:181], v[40:43]
	v_mfma_i32_16x16x64_i8 v[36:39], v[146:149], v[186:189], v[36:39]
	v_mfma_i32_16x16x64_i8 v[32:35], v[154:157], v[186:189], v[32:35]
	s_barrier
	s_setprio 0
	s_add_u32 s54, s54, 0x20080
	s_addc_u32 s55, s55, 0
	s_add_i32 s56, s56, s18
	v_lshl_add_u64 v[142:143], s[54:55], 0, v[130:131]
	s_mov_b32 m0, s56
	s_nop 0
	global_load_lds_dwordx4 v[142:143], off
	v_lshl_add_u64 v[142:143], s[54:55], 0, v[128:129]
	s_add_i32 m0, s56, 0x2000
	s_nop 0
	global_load_lds_dwordx4 v[142:143], off
	s_waitcnt vmcnt(6)
	s_setprio 1
	s_barrier
	v_mfma_i32_16x16x64_i8 v[28:31], v[204:207], v[158:161], v[28:31]
	v_mfma_i32_16x16x64_i8 v[24:27], v[212:215], v[158:161], v[24:27]
	v_mfma_i32_16x16x64_i8 v[20:23], v[204:207], v[166:169], v[20:23]
	v_mfma_i32_16x16x64_i8 v[16:19], v[212:215], v[166:169], v[16:19]
	v_mfma_i32_16x16x64_i8 v[12:15], v[204:207], v[174:177], v[12:15]
	v_mfma_i32_16x16x64_i8 v[8:11], v[212:215], v[174:177], v[8:11]
	v_mfma_i32_16x16x64_i8 v[4:7], v[204:207], v[182:185], v[4:7]
	v_mfma_i32_16x16x64_i8 v[0:3], v[212:215], v[182:185], v[0:3]
	v_mfma_i32_16x16x64_i8 v[28:31], v[208:211], v[162:165], v[28:31]
	v_mfma_i32_16x16x64_i8 v[24:27], v[216:219], v[162:165], v[24:27]
	v_mfma_i32_16x16x64_i8 v[20:23], v[208:211], v[170:173], v[20:23]
	v_mfma_i32_16x16x64_i8 v[16:19], v[216:219], v[170:173], v[16:19]
	v_mfma_i32_16x16x64_i8 v[12:15], v[208:211], v[178:181], v[12:15]
	v_mfma_i32_16x16x64_i8 v[8:11], v[216:219], v[178:181], v[8:11]
	v_mfma_i32_16x16x64_i8 v[4:7], v[208:211], v[186:189], v[4:7]
	v_mfma_i32_16x16x64_i8 v[0:3], v[216:219], v[186:189], v[0:3]
	s_add_u32 s6, s6, 0x100
	s_addc_u32 s7, s7, 0
	s_add_u32 s73, s73, 0x100
	s_addc_u32 s74, s74, 0
	s_cmp_ge_i32 s75, s60
	s_mov_b32 s54, s75
	s_barrier
	s_setprio 0
	s_cbranch_scc1 .Lpeel_done_P2g
.LBB0_341:
	v_add_u32_e32 v154, s64, v195
	ds_read_b128 v[142:145], v154
	ds_read_b128 v[146:149], v154 offset:1024
	ds_read_b128 v[150:153], v154 offset:2048
	ds_read_b128 v[154:157], v154 offset:3072
	s_add_i32 s75, s54, 2
	s_add_u32 s55, s6, 0xfffe0080
	s_addc_u32 s56, s7, -1
	s_cmp_eq_u32 s63, s54
	s_cselect_b32 s54, s72, s73
	s_cselect_b32 s57, s45, s56
	s_cselect_b32 s56, s47, s55
	s_cselect_b32 s55, s71, s74
	v_lshl_add_u64 v[190:191], s[6:7], 0, v[134:135]
	s_add_i32 m0, s19, 0xc000
	ds_read_b128 v[158:161], v201
	ds_read_b128 v[162:165], v201 offset:1024
	ds_read_b128 v[166:169], v201 offset:2048
	ds_read_b128 v[170:173], v201 offset:3072
	ds_read_b128 v[174:177], v201 offset:4096
	ds_read_b128 v[178:181], v201 offset:5120
	ds_read_b128 v[182:185], v201 offset:6144
	ds_read_b128 v[186:189], v201 offset:7168
	global_load_lds_dwordx4 v[190:191], off
	v_lshl_add_u64 v[190:191], s[6:7], 0, v[136:137]
	s_add_i32 m0, s19, 0xe000
	s_nop 0
	global_load_lds_dwordx4 v[190:191], off
	s_waitcnt lgkmcnt(8)
	s_setprio 1
	s_barrier
	s_waitcnt lgkmcnt(0)
	v_mfma_i32_16x16x64_i8 v[124:127], v[142:145], v[158:161], v[124:127]
	v_mfma_i32_16x16x64_i8 v[120:123], v[150:153], v[158:161], v[120:123]
	v_mfma_i32_16x16x64_i8 v[116:119], v[142:145], v[166:169], v[116:119]
	v_mfma_i32_16x16x64_i8 v[112:115], v[150:153], v[166:169], v[112:115]
	v_mfma_i32_16x16x64_i8 v[108:111], v[142:145], v[174:177], v[108:111]
	v_mfma_i32_16x16x64_i8 v[104:107], v[150:153], v[174:177], v[104:107]
	v_mfma_i32_16x16x64_i8 v[100:103], v[142:145], v[182:185], v[100:103]
	v_mfma_i32_16x16x64_i8 v[96:99], v[150:153], v[182:185], v[96:99]
	v_mfma_i32_16x16x64_i8 v[124:127], v[146:149], v[162:165], v[124:127]
	v_mfma_i32_16x16x64_i8 v[120:123], v[154:157], v[162:165], v[120:123]
	v_mfma_i32_16x16x64_i8 v[116:119], v[146:149], v[170:173], v[116:119]
	v_mfma_i32_16x16x64_i8 v[112:115], v[154:157], v[170:173], v[112:115]
	v_mfma_i32_16x16x64_i8 v[108:111], v[146:149], v[178:181], v[108:111]
	v_mfma_i32_16x16x64_i8 v[104:107], v[154:157], v[178:181], v[104:107]
	v_mfma_i32_16x16x64_i8 v[100:103], v[146:149], v[186:189], v[100:103]
	v_mfma_i32_16x16x64_i8 v[96:99], v[154:157], v[186:189], v[96:99]
	s_barrier
	s_setprio 0
	v_add_u32_e32 v190, s65, v195
	s_add_i32 s76, s64, s18
	ds_read_b128 v[204:207], v190
	ds_read_b128 v[208:211], v190 offset:1024
	ds_read_b128 v[212:215], v190 offset:2048
	ds_read_b128 v[216:219], v190 offset:3072
	v_lshl_add_u64 v[190:191], s[54:55], 0, v[130:131]
	s_mov_b32 m0, s76
	v_lshl_add_u64 v[220:221], s[54:55], 0, v[128:129]
	global_load_lds_dwordx4 v[190:191], off
	s_add_i32 m0, s76, 0x2000
	s_nop 0
	global_load_lds_dwordx4 v[220:221], off
	s_setprio 1
	s_barrier
	s_waitcnt lgkmcnt(0)
	v_mfma_i32_16x16x64_i8 v[92:95], v[204:207], v[158:161], v[92:95]
	v_mfma_i32_16x16x64_i8 v[88:91], v[212:215], v[158:161], v[88:91]
	v_mfma_i32_16x16x64_i8 v[84:87], v[204:207], v[166:169], v[84:87]
	v_mfma_i32_16x16x64_i8 v[80:83], v[212:215], v[166:169], v[80:83]
	v_mfma_i32_16x16x64_i8 v[76:79], v[204:207], v[174:177], v[76:79]
	v_mfma_i32_16x16x64_i8 v[72:75], v[212:215], v[174:177], v[72:75]
	v_mfma_i32_16x16x64_i8 v[68:71], v[204:207], v[182:185], v[68:71]
	v_mfma_i32_16x16x64_i8 v[64:67], v[212:215], v[182:185], v[64:67]
	v_mfma_i32_16x16x64_i8 v[92:95], v[208:211], v[162:165], v[92:95]
	v_mfma_i32_16x16x64_i8 v[88:91], v[216:219], v[162:165], v[88:91]
	v_mfma_i32_16x16x64_i8 v[84:87], v[208:211], v[170:173], v[84:87]
	v_mfma_i32_16x16x64_i8 v[80:83], v[216:219], v[170:173], v[80:83]
	v_mfma_i32_16x16x64_i8 v[76:79], v[208:211], v[178:181], v[76:79]
	v_mfma_i32_16x16x64_i8 v[72:75], v[216:219], v[178:181], v[72:75]
	v_mfma_i32_16x16x64_i8 v[68:71], v[208:211], v[186:189], v[68:71]
	v_mfma_i32_16x16x64_i8 v[64:67], v[216:219], v[186:189], v[64:67]
	s_mov_b32 m0, s19
	v_lshl_add_u64 v[224:225], s[56:57], 0, v[130:131]
	s_barrier
	s_setprio 0
	ds_read_b128 v[158:161], v201 offset:16384
	ds_read_b128 v[162:165], v201 offset:17408
	ds_read_b128 v[166:169], v201 offset:18432
	ds_read_b128 v[170:173], v201 offset:19456
	ds_read_b128 v[174:177], v201 offset:20480
	ds_read_b128 v[178:181], v201 offset:21504
	ds_read_b128 v[182:185], v201 offset:22528
	ds_read_b128 v[186:189], v201 offset:23552
	global_load_lds_dwordx4 v[224:225], off
	v_lshl_add_u64 v[228:229], s[56:57], 0, v[128:129]
	s_mov_b32 m0, s53
	s_nop 0
	global_load_lds_dwordx4 v[228:229], off
	s_setprio 1
	s_barrier
	s_waitcnt lgkmcnt(0)
	v_mfma_i32_16x16x64_i8 v[60:63], v[142:145], v[158:161], v[60:63]
	v_mfma_i32_16x16x64_i8 v[56:59], v[150:153], v[158:161], v[56:59]
	v_mfma_i32_16x16x64_i8 v[52:55], v[142:145], v[166:169], v[52:55]
	v_mfma_i32_16x16x64_i8 v[48:51], v[150:153], v[166:169], v[48:51]
	v_mfma_i32_16x16x64_i8 v[44:47], v[142:145], v[174:177], v[44:47]
	v_mfma_i32_16x16x64_i8 v[40:43], v[150:153], v[174:177], v[40:43]
	v_mfma_i32_16x16x64_i8 v[36:39], v[142:145], v[182:185], v[36:39]
	v_mfma_i32_16x16x64_i8 v[32:35], v[150:153], v[182:185], v[32:35]
	v_mfma_i32_16x16x64_i8 v[60:63], v[146:149], v[162:165], v[60:63]
	v_mfma_i32_16x16x64_i8 v[56:59], v[154:157], v[162:165], v[56:59]
	v_mfma_i32_16x16x64_i8 v[52:55], v[146:149], v[170:173], v[52:55]
	v_mfma_i32_16x16x64_i8 v[48:51], v[154:157], v[170:173], v[48:51]
	v_mfma_i32_16x16x64_i8 v[44:47], v[146:149], v[178:181], v[44:47]
	v_mfma_i32_16x16x64_i8 v[40:43], v[154:157], v[178:181], v[40:43]
	v_mfma_i32_16x16x64_i8 v[36:39], v[146:149], v[186:189], v[36:39]
	v_mfma_i32_16x16x64_i8 v[32:35], v[154:157], v[186:189], v[32:35]
	s_barrier
	s_setprio 0
	s_add_u32 s76, s54, 0x20000
	s_addc_u32 s77, s55, 0
	s_add_i32 s78, s65, s18
	v_lshl_add_u64 v[142:143], s[76:77], 0, v[130:131]
	s_mov_b32 m0, s78
	s_nop 0
	global_load_lds_dwordx4 v[142:143], off
	v_lshl_add_u64 v[142:143], s[76:77], 0, v[128:129]
	s_add_i32 m0, s78, 0x2000
	s_nop 0
	global_load_lds_dwordx4 v[142:143], off
	s_waitcnt vmcnt(6)
	s_setprio 1
	s_barrier
	v_mfma_i32_16x16x64_i8 v[28:31], v[204:207], v[158:161], v[28:31]
	v_mfma_i32_16x16x64_i8 v[24:27], v[212:215], v[158:161], v[24:27]
	v_mfma_i32_16x16x64_i8 v[20:23], v[204:207], v[166:169], v[20:23]
	v_mfma_i32_16x16x64_i8 v[16:19], v[212:215], v[166:169], v[16:19]
	v_mfma_i32_16x16x64_i8 v[12:15], v[204:207], v[174:177], v[12:15]
	v_mfma_i32_16x16x64_i8 v[8:11], v[212:215], v[174:177], v[8:11]
	v_mfma_i32_16x16x64_i8 v[4:7], v[204:207], v[182:185], v[4:7]
	v_mfma_i32_16x16x64_i8 v[0:3], v[212:215], v[182:185], v[0:3]
	v_mfma_i32_16x16x64_i8 v[28:31], v[208:211], v[162:165], v[28:31]
	v_mfma_i32_16x16x64_i8 v[24:27], v[216:219], v[162:165], v[24:27]
	v_mfma_i32_16x16x64_i8 v[20:23], v[208:211], v[170:173], v[20:23]
	v_mfma_i32_16x16x64_i8 v[16:19], v[216:219], v[170:173], v[16:19]
	v_mfma_i32_16x16x64_i8 v[12:15], v[208:211], v[178:181], v[12:15]
	v_mfma_i32_16x16x64_i8 v[8:11], v[216:219], v[178:181], v[8:11]
	v_mfma_i32_16x16x64_i8 v[4:7], v[208:211], v[186:189], v[4:7]
	v_mfma_i32_16x16x64_i8 v[0:3], v[216:219], v[186:189], v[0:3]
	s_add_i32 s76, 0, 0x18000
	v_add_u32_e32 v154, s76, v195
	s_barrier
	s_setprio 0
	ds_read_b128 v[142:145], v154
	ds_read_b128 v[146:149], v154 offset:1024
	ds_read_b128 v[150:153], v154 offset:2048
	ds_read_b128 v[154:157], v154 offset:3072
	s_add_u32 s56, s56, 0x20000
	s_addc_u32 s57, s57, 0
	s_mov_b32 m0, s58
	v_lshl_add_u64 v[204:205], s[56:57], 0, v[130:131]
	ds_read_b128 v[158:161], v201 offset:32768
	ds_read_b128 v[162:165], v201 offset:33792
	ds_read_b128 v[166:169], v201 offset:34816
	ds_read_b128 v[170:173], v201 offset:35840
	ds_read_b128 v[174:177], v201 offset:36864
	ds_read_b128 v[178:181], v201 offset:37888
	ds_read_b128 v[182:185], v201 offset:38912
	ds_read_b128 v[186:189], v201 offset:39936
	global_load_lds_dwordx4 v[204:205], off
	v_lshl_add_u64 v[204:205], s[56:57], 0, v[128:129]
	s_mov_b32 m0, s59
	s_nop 0
	global_load_lds_dwordx4 v[204:205], off
	s_waitcnt lgkmcnt(8)
	s_setprio 1
	s_barrier
	s_waitcnt lgkmcnt(0)
	v_mfma_i32_16x16x64_i8 v[124:127], v[142:145], v[158:161], v[124:127]
	v_mfma_i32_16x16x64_i8 v[120:123], v[150:153], v[158:161], v[120:123]
	v_mfma_i32_16x16x64_i8 v[116:119], v[142:145], v[166:169], v[116:119]
	v_mfma_i32_16x16x64_i8 v[112:115], v[150:153], v[166:169], v[112:115]
	v_mfma_i32_16x16x64_i8 v[108:111], v[142:145], v[174:177], v[108:111]
	v_mfma_i32_16x16x64_i8 v[104:107], v[150:153], v[174:177], v[104:107]
	v_mfma_i32_16x16x64_i8 v[100:103], v[142:145], v[182:185], v[100:103]
	v_mfma_i32_16x16x64_i8 v[96:99], v[150:153], v[182:185], v[96:99]
	v_mfma_i32_16x16x64_i8 v[124:127], v[146:149], v[162:165], v[124:127]
	v_mfma_i32_16x16x64_i8 v[120:123], v[154:157], v[162:165], v[120:123]
	v_mfma_i32_16x16x64_i8 v[116:119], v[146:149], v[170:173], v[116:119]
	v_mfma_i32_16x16x64_i8 v[112:115], v[154:157], v[170:173], v[112:115]
	v_mfma_i32_16x16x64_i8 v[108:111], v[146:149], v[178:181], v[108:111]
	v_mfma_i32_16x16x64_i8 v[104:107], v[154:157], v[178:181], v[104:107]
	v_mfma_i32_16x16x64_i8 v[100:103], v[146:149], v[186:189], v[100:103]
	v_mfma_i32_16x16x64_i8 v[96:99], v[154:157], v[186:189], v[96:99]
	s_barrier
	s_setprio 0
	s_add_i32 s56, 0, 0x1c000
	s_add_i32 s57, s76, s18
	v_add_u32_e32 v192, s56, v195
	v_lshl_add_u64 v[190:191], v[190:191], 0, s[30:31]
	s_mov_b32 m0, s57
	ds_read_b128 v[204:207], v192
	ds_read_b128 v[208:211], v192 offset:1024
	ds_read_b128 v[212:215], v192 offset:2048
	ds_read_b128 v[216:219], v192 offset:3072
	global_load_lds_dwordx4 v[190:191], off
	v_lshl_add_u64 v[190:191], v[220:221], 0, s[30:31]
	s_add_i32 m0, s57, 0x2000
	s_nop 0
	global_load_lds_dwordx4 v[190:191], off
	s_setprio 1
	s_barrier
	s_waitcnt lgkmcnt(0)
	v_mfma_i32_16x16x64_i8 v[92:95], v[204:207], v[158:161], v[92:95]
	v_mfma_i32_16x16x64_i8 v[88:91], v[212:215], v[158:161], v[88:91]
	v_mfma_i32_16x16x64_i8 v[84:87], v[204:207], v[166:169], v[84:87]
	v_mfma_i32_16x16x64_i8 v[80:83], v[212:215], v[166:169], v[80:83]
	v_mfma_i32_16x16x64_i8 v[76:79], v[204:207], v[174:177], v[76:79]
	v_mfma_i32_16x16x64_i8 v[72:75], v[212:215], v[174:177], v[72:75]
	v_mfma_i32_16x16x64_i8 v[68:71], v[204:207], v[182:185], v[68:71]
	v_mfma_i32_16x16x64_i8 v[64:67], v[212:215], v[182:185], v[64:67]
	v_mfma_i32_16x16x64_i8 v[92:95], v[208:211], v[162:165], v[92:95]
	v_mfma_i32_16x16x64_i8 v[88:91], v[216:219], v[162:165], v[88:91]
	v_mfma_i32_16x16x64_i8 v[84:87], v[208:211], v[170:173], v[84:87]
	v_mfma_i32_16x16x64_i8 v[80:83], v[216:219], v[170:173], v[80:83]
	v_mfma_i32_16x16x64_i8 v[76:79], v[208:211], v[178:181], v[76:79]
	v_mfma_i32_16x16x64_i8 v[72:75], v[216:219], v[178:181], v[72:75]
	v_mfma_i32_16x16x64_i8 v[68:71], v[208:211], v[186:189], v[68:71]
	v_mfma_i32_16x16x64_i8 v[64:67], v[216:219], v[186:189], v[64:67]
	s_mov_b32 m0, s61
	v_lshl_add_u64 v[190:191], v[224:225], 0, s[30:31]
	s_barrier
	s_setprio 0
	ds_read_b128 v[158:161], v201 offset:49152
	ds_read_b128 v[162:165], v201 offset:50176
	ds_read_b128 v[166:169], v201 offset:51200
	ds_read_b128 v[170:173], v201 offset:52224
	ds_read_b128 v[174:177], v201 offset:53248
	ds_read_b128 v[178:181], v201 offset:54272
	ds_read_b128 v[182:185], v201 offset:55296
	ds_read_b128 v[186:189], v201 offset:56320
	global_load_lds_dwordx4 v[190:191], off
	v_lshl_add_u64 v[190:191], v[228:229], 0, s[30:31]
	s_mov_b32 m0, s62
	s_nop 0
	global_load_lds_dwordx4 v[190:191], off
	s_setprio 1
	s_barrier
	s_waitcnt lgkmcnt(0)
	v_mfma_i32_16x16x64_i8 v[60:63], v[142:145], v[158:161], v[60:63]
	v_mfma_i32_16x16x64_i8 v[56:59], v[150:153], v[158:161], v[56:59]
	v_mfma_i32_16x16x64_i8 v[52:55], v[142:145], v[166:169], v[52:55]
	v_mfma_i32_16x16x64_i8 v[48:51], v[150:153], v[166:169], v[48:51]
	v_mfma_i32_16x16x64_i8 v[44:47], v[142:145], v[174:177], v[44:47]
	v_mfma_i32_16x16x64_i8 v[40:43], v[150:153], v[174:177], v[40:43]
	v_mfma_i32_16x16x64_i8 v[36:39], v[142:145], v[182:185], v[36:39]
	v_mfma_i32_16x16x64_i8 v[32:35], v[150:153], v[182:185], v[32:35]
	v_mfma_i32_16x16x64_i8 v[60:63], v[146:149], v[162:165], v[60:63]
	v_mfma_i32_16x16x64_i8 v[56:59], v[154:157], v[162:165], v[56:59]
	v_mfma_i32_16x16x64_i8 v[52:55], v[146:149], v[170:173], v[52:55]
	v_mfma_i32_16x16x64_i8 v[48:51], v[154:157], v[170:173], v[48:51]
	v_mfma_i32_16x16x64_i8 v[44:47], v[146:149], v[178:181], v[44:47]
	v_mfma_i32_16x16x64_i8 v[40:43], v[154:157], v[178:181], v[40:43]
	v_mfma_i32_16x16x64_i8 v[36:39], v[146:149], v[186:189], v[36:39]
	v_mfma_i32_16x16x64_i8 v[32:35], v[154:157], v[186:189], v[32:35]
	s_barrier
	s_setprio 0
	s_add_u32 s54, s54, 0x20080
	s_addc_u32 s55, s55, 0
	s_add_i32 s56, s56, s18
	v_lshl_add_u64 v[142:143], s[54:55], 0, v[130:131]
	s_mov_b32 m0, s56
	s_nop 0
	global_load_lds_dwordx4 v[142:143], off
	v_lshl_add_u64 v[142:143], s[54:55], 0, v[128:129]
	s_add_i32 m0, s56, 0x2000
	s_nop 0
	global_load_lds_dwordx4 v[142:143], off
	s_waitcnt vmcnt(6)
	s_setprio 1
	s_barrier
	v_mfma_i32_16x16x64_i8 v[28:31], v[204:207], v[158:161], v[28:31]
	v_mfma_i32_16x16x64_i8 v[24:27], v[212:215], v[158:161], v[24:27]
	v_mfma_i32_16x16x64_i8 v[20:23], v[204:207], v[166:169], v[20:23]
	v_mfma_i32_16x16x64_i8 v[16:19], v[212:215], v[166:169], v[16:19]
	v_mfma_i32_16x16x64_i8 v[12:15], v[204:207], v[174:177], v[12:15]
	v_mfma_i32_16x16x64_i8 v[8:11], v[212:215], v[174:177], v[8:11]
	v_mfma_i32_16x16x64_i8 v[4:7], v[204:207], v[182:185], v[4:7]
	v_mfma_i32_16x16x64_i8 v[0:3], v[212:215], v[182:185], v[0:3]
	v_mfma_i32_16x16x64_i8 v[28:31], v[208:211], v[162:165], v[28:31]
	v_mfma_i32_16x16x64_i8 v[24:27], v[216:219], v[162:165], v[24:27]
	v_mfma_i32_16x16x64_i8 v[20:23], v[208:211], v[170:173], v[20:23]
	v_mfma_i32_16x16x64_i8 v[16:19], v[216:219], v[170:173], v[16:19]
	v_mfma_i32_16x16x64_i8 v[12:15], v[208:211], v[178:181], v[12:15]
	v_mfma_i32_16x16x64_i8 v[8:11], v[216:219], v[178:181], v[8:11]
	v_mfma_i32_16x16x64_i8 v[4:7], v[208:211], v[186:189], v[4:7]
	v_mfma_i32_16x16x64_i8 v[0:3], v[216:219], v[186:189], v[0:3]
	s_add_u32 s6, s6, 0x100
	s_addc_u32 s7, s7, 0
	s_add_u32 s73, s73, 0x100
	s_addc_u32 s74, s74, 0
	s_cmp_ge_i32 s75, s60
	s_mov_b32 s54, s75
	s_barrier
	s_setprio 0
	s_cbranch_scc0 .LBB0_341

.Lzskip_P2r:
	s_and_b64 s[8:9], s[8:9], exec
	s_cselect_b32 s47, s51, s57
	s_cselect_b32 s49, s50, s56
	s_cselect_b32 s73, s53, s59
	s_cselect_b32 s74, s52, s58
	s_add_u32 s75, s58, 0x100
	s_addc_u32 s76, s59, 0
	s_mov_b32 s58, 0
	v_add_u32_e32 v156, s71, v224
	ds_read_b128 v[144:147], v156
	ds_read_b128 v[148:151], v156 offset:1024
	ds_read_b128 v[152:155], v156 offset:2048
	ds_read_b128 v[156:159], v156 offset:3072
	s_add_i32 s77, s58, 2
	s_add_u32 s8, s56, 0x100
	s_addc_u32 s9, s57, 0
	s_cmp_eq_u32 s70, s58
	s_cselect_b32 s58, s74, s75
	s_cselect_b32 s61, s47, s9
	s_cselect_b32 s60, s49, s8
	s_cselect_b32 s59, s73, s76
	v_lshl_add_u64 v[192:193], s[56:57], 0, v[136:137]
	s_add_i32 m0, s62, 0xc000
	ds_read_b128 v[160:163], v232
	ds_read_b128 v[164:167], v232 offset:1024
	ds_read_b128 v[168:171], v232 offset:2048
	ds_read_b128 v[172:175], v232 offset:3072
	ds_read_b128 v[176:179], v232 offset:4096
	ds_read_b128 v[180:183], v232 offset:5120
	ds_read_b128 v[184:187], v232 offset:6144
	ds_read_b128 v[188:191], v232 offset:7168
	global_load_lds_dwordx4 v[192:193], off
	v_lshl_add_u64 v[192:193], s[56:57], 0, v[138:139]
	s_add_i32 m0, s62, 0xe000
	s_nop 0
	global_load_lds_dwordx4 v[192:193], off
	s_waitcnt lgkmcnt(8)
	s_setprio 1
	s_barrier
	s_waitcnt lgkmcnt(0)
	v_mfma_i32_16x16x64_i8 v[124:127], v[144:147], v[160:163], 0
	v_mfma_i32_16x16x64_i8 v[112:115], v[152:155], v[160:163], 0
	v_mfma_i32_16x16x64_i8 v[120:123], v[144:147], v[168:171], 0
	v_mfma_i32_16x16x64_i8 v[104:107], v[152:155], v[168:171], 0
	v_mfma_i32_16x16x64_i8 v[116:119], v[144:147], v[176:179], 0
	v_mfma_i32_16x16x64_i8 v[100:103], v[152:155], v[176:179], 0
	v_mfma_i32_16x16x64_i8 v[108:111], v[144:147], v[184:187], 0
	v_mfma_i32_16x16x64_i8 v[96:99], v[152:155], v[184:187], 0
	v_mfma_i32_16x16x64_i8 v[124:127], v[148:151], v[164:167], v[124:127]
	v_mfma_i32_16x16x64_i8 v[112:115], v[156:159], v[164:167], v[112:115]
	v_mfma_i32_16x16x64_i8 v[120:123], v[148:151], v[172:175], v[120:123]
	v_mfma_i32_16x16x64_i8 v[104:107], v[156:159], v[172:175], v[104:107]
	v_mfma_i32_16x16x64_i8 v[116:119], v[148:151], v[180:183], v[116:119]
	v_mfma_i32_16x16x64_i8 v[100:103], v[156:159], v[180:183], v[100:103]
	v_mfma_i32_16x16x64_i8 v[108:111], v[148:151], v[188:191], v[108:111]
	v_mfma_i32_16x16x64_i8 v[96:99], v[156:159], v[188:191], v[96:99]
	s_barrier
	s_setprio 0
	s_add_i32 s20, s71, s19
	v_add_u32_e32 v204, s72, v224
	v_lshl_add_u64 v[208:209], s[58:59], 0, v[132:133]
	s_mov_b32 m0, s20
	ds_read_b128 v[192:195], v204
	ds_read_b128 v[196:199], v204 offset:1024
	ds_read_b128 v[200:203], v204 offset:2048
	ds_read_b128 v[204:207], v204 offset:3072
	global_load_lds_dwordx4 v[208:209], off
	v_lshl_add_u64 v[210:211], s[58:59], 0, v[128:129]
	s_add_i32 m0, s20, 0x2000
	s_nop 0
	global_load_lds_dwordx4 v[210:211], off
	s_setprio 1
	s_barrier
	s_waitcnt lgkmcnt(0)
	v_mfma_i32_16x16x64_i8 v[84:87], v[192:195], v[160:163], 0
	v_mfma_i32_16x16x64_i8 v[56:59], v[200:203], v[160:163], 0
	v_mfma_i32_16x16x64_i8 v[76:79], v[192:195], v[168:171], 0
	v_mfma_i32_16x16x64_i8 v[44:47], v[200:203], v[168:171], 0
	v_mfma_i32_16x16x64_i8 v[64:67], v[192:195], v[176:179], 0
	v_mfma_i32_16x16x64_i8 v[36:39], v[200:203], v[176:179], 0
	v_mfma_i32_16x16x64_i8 v[52:55], v[192:195], v[184:187], 0
	v_mfma_i32_16x16x64_i8 v[28:31], v[200:203], v[184:187], 0
	v_mfma_i32_16x16x64_i8 v[84:87], v[196:199], v[164:167], v[84:87]
	v_mfma_i32_16x16x64_i8 v[56:59], v[204:207], v[164:167], v[56:59]
	v_mfma_i32_16x16x64_i8 v[76:79], v[196:199], v[172:175], v[76:79]
	v_mfma_i32_16x16x64_i8 v[44:47], v[204:207], v[172:175], v[44:47]
	v_mfma_i32_16x16x64_i8 v[64:67], v[196:199], v[180:183], v[64:67]
	v_mfma_i32_16x16x64_i8 v[36:39], v[204:207], v[180:183], v[36:39]
	v_mfma_i32_16x16x64_i8 v[52:55], v[196:199], v[188:191], v[52:55]
	v_mfma_i32_16x16x64_i8 v[28:31], v[204:207], v[188:191], v[28:31]
	s_mov_b32 m0, s62
	v_lshl_add_u64 v[212:213], s[60:61], 0, v[134:135]
	s_barrier
	s_setprio 0
	ds_read_b128 v[160:163], v232 offset:16384
	ds_read_b128 v[164:167], v232 offset:17408
	ds_read_b128 v[168:171], v232 offset:18432
	ds_read_b128 v[172:175], v232 offset:19456
	ds_read_b128 v[176:179], v232 offset:20480
	ds_read_b128 v[180:183], v232 offset:21504
	ds_read_b128 v[184:187], v232 offset:22528
	ds_read_b128 v[188:191], v232 offset:23552
	global_load_lds_dwordx4 v[212:213], off
	v_lshl_add_u64 v[214:215], s[60:61], 0, v[130:131]
	s_mov_b32 m0, s63
	s_nop 0
	global_load_lds_dwordx4 v[214:215], off
	s_setprio 1
	s_barrier
	s_waitcnt lgkmcnt(0)
	v_mfma_i32_16x16x64_i8 v[92:95], v[144:147], v[160:163], 0
	v_mfma_i32_16x16x64_i8 v[72:75], v[152:155], v[160:163], 0
	v_mfma_i32_16x16x64_i8 v[88:91], v[144:147], v[168:171], 0
	v_mfma_i32_16x16x64_i8 v[60:63], v[152:155], v[168:171], 0
	v_mfma_i32_16x16x64_i8 v[80:83], v[144:147], v[176:179], 0
	v_mfma_i32_16x16x64_i8 v[48:51], v[152:155], v[176:179], 0
	v_mfma_i32_16x16x64_i8 v[68:71], v[144:147], v[184:187], 0
	v_mfma_i32_16x16x64_i8 v[40:43], v[152:155], v[184:187], 0
	v_mfma_i32_16x16x64_i8 v[92:95], v[148:151], v[164:167], v[92:95]
	v_mfma_i32_16x16x64_i8 v[72:75], v[156:159], v[164:167], v[72:75]
	v_mfma_i32_16x16x64_i8 v[88:91], v[148:151], v[172:175], v[88:91]
	v_mfma_i32_16x16x64_i8 v[60:63], v[156:159], v[172:175], v[60:63]
	v_mfma_i32_16x16x64_i8 v[80:83], v[148:151], v[180:183], v[80:83]
	v_mfma_i32_16x16x64_i8 v[48:51], v[156:159], v[180:183], v[48:51]
	v_mfma_i32_16x16x64_i8 v[68:71], v[148:151], v[188:191], v[68:71]
	v_mfma_i32_16x16x64_i8 v[40:43], v[156:159], v[188:191], v[40:43]
	s_barrier
	s_setprio 0
	s_add_u32 s20, s58, 0x20000
	s_addc_u32 s21, s59, 0
	s_add_i32 s56, s72, s19
	v_lshl_add_u64 v[144:145], s[20:21], 0, v[132:133]
	s_mov_b32 m0, s56
	s_nop 0
	global_load_lds_dwordx4 v[144:145], off
	v_lshl_add_u64 v[144:145], s[20:21], 0, v[128:129]
	s_add_i32 m0, s56, 0x2000
	s_nop 0
	global_load_lds_dwordx4 v[144:145], off
	s_waitcnt vmcnt(6)
	s_setprio 1
	s_barrier
	v_mfma_i32_16x16x64_i8 v[32:35], v[192:195], v[160:163], 0
	v_mfma_i32_16x16x64_i8 v[8:11], v[200:203], v[160:163], 0
	v_mfma_i32_16x16x64_i8 v[24:27], v[192:195], v[168:171], 0
	v_mfma_i32_16x16x64_i8 v[12:15], v[200:203], v[168:171], 0
	v_mfma_i32_16x16x64_i8 v[20:23], v[192:195], v[176:179], 0
	v_mfma_i32_16x16x64_i8 v[4:7], v[200:203], v[176:179], 0
	v_mfma_i32_16x16x64_i8 v[16:19], v[192:195], v[184:187], 0
	v_mfma_i32_16x16x64_i8 v[0:3], v[200:203], v[184:187], 0
	v_mfma_i32_16x16x64_i8 v[32:35], v[196:199], v[164:167], v[32:35]
	v_mfma_i32_16x16x64_i8 v[8:11], v[204:207], v[164:167], v[8:11]
	v_mfma_i32_16x16x64_i8 v[24:27], v[196:199], v[172:175], v[24:27]
	v_mfma_i32_16x16x64_i8 v[12:15], v[204:207], v[172:175], v[12:15]
	v_mfma_i32_16x16x64_i8 v[20:23], v[196:199], v[180:183], v[20:23]
	v_mfma_i32_16x16x64_i8 v[4:7], v[204:207], v[180:183], v[4:7]
	v_mfma_i32_16x16x64_i8 v[16:19], v[196:199], v[188:191], v[16:19]
	v_mfma_i32_16x16x64_i8 v[0:3], v[204:207], v[188:191], v[0:3]
	s_add_i32 s56, 0, 0x18000
	v_add_u32_e32 v156, s56, v224
	s_barrier
	s_setprio 0
	ds_read_b128 v[144:147], v156
	ds_read_b128 v[148:151], v156 offset:1024
	ds_read_b128 v[152:155], v156 offset:2048
	ds_read_b128 v[156:159], v156 offset:3072
	s_add_u32 s20, s60, 0x1000
	s_addc_u32 s21, s61, 0
	s_mov_b32 m0, s64
	v_lshl_add_u64 v[192:193], s[20:21], 0, v[134:135]
	ds_read_b128 v[160:163], v232 offset:32768
	ds_read_b128 v[164:167], v232 offset:33792
	ds_read_b128 v[168:171], v232 offset:34816
	ds_read_b128 v[172:175], v232 offset:35840
	ds_read_b128 v[176:179], v232 offset:36864
	ds_read_b128 v[180:183], v232 offset:37888
	ds_read_b128 v[184:187], v232 offset:38912
	ds_read_b128 v[188:191], v232 offset:39936
	global_load_lds_dwordx4 v[192:193], off
	v_lshl_add_u64 v[192:193], s[20:21], 0, v[130:131]
	s_mov_b32 m0, s65
	s_nop 0
	global_load_lds_dwordx4 v[192:193], off
	s_waitcnt lgkmcnt(8)
	s_setprio 1
	s_barrier
	s_waitcnt lgkmcnt(0)
	v_mfma_i32_16x16x64_i8 v[124:127], v[144:147], v[160:163], v[124:127]
	v_mfma_i32_16x16x64_i8 v[112:115], v[152:155], v[160:163], v[112:115]
	v_mfma_i32_16x16x64_i8 v[120:123], v[144:147], v[168:171], v[120:123]
	v_mfma_i32_16x16x64_i8 v[104:107], v[152:155], v[168:171], v[104:107]
	v_mfma_i32_16x16x64_i8 v[116:119], v[144:147], v[176:179], v[116:119]
	v_mfma_i32_16x16x64_i8 v[100:103], v[152:155], v[176:179], v[100:103]
	v_mfma_i32_16x16x64_i8 v[108:111], v[144:147], v[184:187], v[108:111]
	v_mfma_i32_16x16x64_i8 v[96:99], v[152:155], v[184:187], v[96:99]
	v_mfma_i32_16x16x64_i8 v[124:127], v[148:151], v[164:167], v[124:127]
	v_mfma_i32_16x16x64_i8 v[112:115], v[156:159], v[164:167], v[112:115]
	v_mfma_i32_16x16x64_i8 v[120:123], v[148:151], v[172:175], v[120:123]
	v_mfma_i32_16x16x64_i8 v[104:107], v[156:159], v[172:175], v[104:107]
	v_mfma_i32_16x16x64_i8 v[116:119], v[148:151], v[180:183], v[116:119]
	v_mfma_i32_16x16x64_i8 v[100:103], v[156:159], v[180:183], v[100:103]
	v_mfma_i32_16x16x64_i8 v[108:111], v[148:151], v[188:191], v[108:111]
	v_mfma_i32_16x16x64_i8 v[96:99], v[156:159], v[188:191], v[96:99]
	s_barrier
	s_setprio 0
	s_add_i32 s57, 0, 0x1c000
	s_add_i32 s20, s56, s19
	v_add_u32_e32 v204, s57, v224
	v_lshl_add_u64 v[208:209], v[208:209], 0, s[34:35]
	s_mov_b32 m0, s20
	ds_read_b128 v[192:195], v204
	ds_read_b128 v[196:199], v204 offset:1024
	ds_read_b128 v[200:203], v204 offset:2048
	ds_read_b128 v[204:207], v204 offset:3072
	global_load_lds_dwordx4 v[208:209], off
	v_lshl_add_u64 v[208:209], v[210:211], 0, s[34:35]
	s_add_i32 m0, s20, 0x2000
	s_nop 0
	global_load_lds_dwordx4 v[208:209], off
	s_setprio 1
	s_barrier
	s_waitcnt lgkmcnt(0)
	v_mfma_i32_16x16x64_i8 v[84:87], v[192:195], v[160:163], v[84:87]
	v_mfma_i32_16x16x64_i8 v[56:59], v[200:203], v[160:163], v[56:59]
	v_mfma_i32_16x16x64_i8 v[76:79], v[192:195], v[168:171], v[76:79]
	v_mfma_i32_16x16x64_i8 v[44:47], v[200:203], v[168:171], v[44:47]
	v_mfma_i32_16x16x64_i8 v[64:67], v[192:195], v[176:179], v[64:67]
	v_mfma_i32_16x16x64_i8 v[36:39], v[200:203], v[176:179], v[36:39]
	v_mfma_i32_16x16x64_i8 v[52:55], v[192:195], v[184:187], v[52:55]
	v_mfma_i32_16x16x64_i8 v[28:31], v[200:203], v[184:187], v[28:31]
	v_mfma_i32_16x16x64_i8 v[84:87], v[196:199], v[164:167], v[84:87]
	v_mfma_i32_16x16x64_i8 v[56:59], v[204:207], v[164:167], v[56:59]
	v_mfma_i32_16x16x64_i8 v[76:79], v[196:199], v[172:175], v[76:79]
	v_mfma_i32_16x16x64_i8 v[44:47], v[204:207], v[172:175], v[44:47]
	v_mfma_i32_16x16x64_i8 v[64:67], v[196:199], v[180:183], v[64:67]
	v_mfma_i32_16x16x64_i8 v[36:39], v[204:207], v[180:183], v[36:39]
	v_mfma_i32_16x16x64_i8 v[52:55], v[196:199], v[188:191], v[52:55]
	v_mfma_i32_16x16x64_i8 v[28:31], v[204:207], v[188:191], v[28:31]
	s_mov_b32 m0, s68
	v_lshl_add_u64 v[208:209], v[212:213], 0, s[34:35]
	s_barrier
	s_setprio 0
	ds_read_b128 v[160:163], v232 offset:49152
	ds_read_b128 v[164:167], v232 offset:50176
	ds_read_b128 v[168:171], v232 offset:51200
	ds_read_b128 v[172:175], v232 offset:52224
	ds_read_b128 v[176:179], v232 offset:53248
	ds_read_b128 v[180:183], v232 offset:54272
	ds_read_b128 v[184:187], v232 offset:55296
	ds_read_b128 v[188:191], v232 offset:56320
	global_load_lds_dwordx4 v[208:209], off
	v_lshl_add_u64 v[208:209], v[214:215], 0, s[34:35]
	s_mov_b32 m0, s69
	s_nop 0
	global_load_lds_dwordx4 v[208:209], off
	s_setprio 1
	s_barrier
	s_waitcnt lgkmcnt(0)
	v_mfma_i32_16x16x64_i8 v[92:95], v[144:147], v[160:163], v[92:95]
	v_mfma_i32_16x16x64_i8 v[72:75], v[152:155], v[160:163], v[72:75]
	v_mfma_i32_16x16x64_i8 v[88:91], v[144:147], v[168:171], v[88:91]
	v_mfma_i32_16x16x64_i8 v[60:63], v[152:155], v[168:171], v[60:63]
	v_mfma_i32_16x16x64_i8 v[80:83], v[144:147], v[176:179], v[80:83]
	v_mfma_i32_16x16x64_i8 v[48:51], v[152:155], v[176:179], v[48:51]
	v_mfma_i32_16x16x64_i8 v[68:71], v[144:147], v[184:187], v[68:71]
	v_mfma_i32_16x16x64_i8 v[40:43], v[152:155], v[184:187], v[40:43]
	v_mfma_i32_16x16x64_i8 v[92:95], v[148:151], v[164:167], v[92:95]
	v_mfma_i32_16x16x64_i8 v[72:75], v[156:159], v[164:167], v[72:75]
	v_mfma_i32_16x16x64_i8 v[88:91], v[148:151], v[172:175], v[88:91]
	v_mfma_i32_16x16x64_i8 v[60:63], v[156:159], v[172:175], v[60:63]
	v_mfma_i32_16x16x64_i8 v[80:83], v[148:151], v[180:183], v[80:83]
	v_mfma_i32_16x16x64_i8 v[48:51], v[156:159], v[180:183], v[48:51]
	v_mfma_i32_16x16x64_i8 v[68:71], v[148:151], v[188:191], v[68:71]
	v_mfma_i32_16x16x64_i8 v[40:43], v[156:159], v[188:191], v[40:43]
	s_barrier
	s_setprio 0
	s_add_u32 s20, s58, 0x20080
	s_addc_u32 s21, s59, 0
	s_add_i32 s56, s57, s19
	v_lshl_add_u64 v[144:145], s[20:21], 0, v[132:133]
	s_mov_b32 m0, s56
	s_nop 0
	global_load_lds_dwordx4 v[144:145], off
	v_lshl_add_u64 v[144:145], s[20:21], 0, v[128:129]
	s_add_i32 m0, s56, 0x2000
	s_nop 0
	global_load_lds_dwordx4 v[144:145], off
	s_waitcnt vmcnt(6)
	s_setprio 1
	s_barrier
	v_mfma_i32_16x16x64_i8 v[32:35], v[192:195], v[160:163], v[32:35]
	v_mfma_i32_16x16x64_i8 v[8:11], v[200:203], v[160:163], v[8:11]
	v_mfma_i32_16x16x64_i8 v[24:27], v[192:195], v[168:171], v[24:27]
	v_mfma_i32_16x16x64_i8 v[12:15], v[200:203], v[168:171], v[12:15]
	v_mfma_i32_16x16x64_i8 v[20:23], v[192:195], v[176:179], v[20:23]
	v_mfma_i32_16x16x64_i8 v[4:7], v[200:203], v[176:179], v[4:7]
	v_mfma_i32_16x16x64_i8 v[16:19], v[192:195], v[184:187], v[16:19]
	v_mfma_i32_16x16x64_i8 v[0:3], v[200:203], v[184:187], v[0:3]
	v_mfma_i32_16x16x64_i8 v[32:35], v[196:199], v[164:167], v[32:35]
	v_mfma_i32_16x16x64_i8 v[8:11], v[204:207], v[164:167], v[8:11]
	v_mfma_i32_16x16x64_i8 v[24:27], v[196:199], v[172:175], v[24:27]
	v_mfma_i32_16x16x64_i8 v[12:15], v[204:207], v[172:175], v[12:15]
	v_mfma_i32_16x16x64_i8 v[20:23], v[196:199], v[180:183], v[20:23]
	v_mfma_i32_16x16x64_i8 v[4:7], v[204:207], v[180:183], v[4:7]
	v_mfma_i32_16x16x64_i8 v[16:19], v[196:199], v[188:191], v[16:19]
	v_mfma_i32_16x16x64_i8 v[0:3], v[204:207], v[188:191], v[0:3]
	s_add_u32 s75, s75, 0x100
	s_addc_u32 s76, s76, 0
	s_cmp_ge_i32 s77, s67
	s_mov_b64 s[56:57], s[8:9]
	s_mov_b32 s58, s77
	s_barrier
	s_setprio 0
	s_cbranch_scc1 .Lpeel_done_P2r
.LBB0_371:
	v_add_u32_e32 v156, s71, v224
	ds_read_b128 v[144:147], v156
	ds_read_b128 v[148:151], v156 offset:1024
	ds_read_b128 v[152:155], v156 offset:2048
	ds_read_b128 v[156:159], v156 offset:3072
	s_add_i32 s77, s58, 2
	s_add_u32 s8, s56, 0x100
	s_addc_u32 s9, s57, 0
	s_cmp_eq_u32 s70, s58
	s_cselect_b32 s58, s74, s75
	s_cselect_b32 s61, s47, s9
	s_cselect_b32 s60, s49, s8
	s_cselect_b32 s59, s73, s76
	v_lshl_add_u64 v[192:193], s[56:57], 0, v[136:137]
	s_add_i32 m0, s62, 0xc000
	ds_read_b128 v[160:163], v232
	ds_read_b128 v[164:167], v232 offset:1024
	ds_read_b128 v[168:171], v232 offset:2048
	ds_read_b128 v[172:175], v232 offset:3072
	ds_read_b128 v[176:179], v232 offset:4096
	ds_read_b128 v[180:183], v232 offset:5120
	ds_read_b128 v[184:187], v232 offset:6144
	ds_read_b128 v[188:191], v232 offset:7168
	global_load_lds_dwordx4 v[192:193], off
	v_lshl_add_u64 v[192:193], s[56:57], 0, v[138:139]
	s_add_i32 m0, s62, 0xe000
	s_nop 0
	global_load_lds_dwordx4 v[192:193], off
	s_waitcnt lgkmcnt(8)
	s_setprio 1
	s_barrier
	s_waitcnt lgkmcnt(0)
	v_mfma_i32_16x16x64_i8 v[124:127], v[144:147], v[160:163], v[124:127]
	v_mfma_i32_16x16x64_i8 v[112:115], v[152:155], v[160:163], v[112:115]
	v_mfma_i32_16x16x64_i8 v[120:123], v[144:147], v[168:171], v[120:123]
	v_mfma_i32_16x16x64_i8 v[104:107], v[152:155], v[168:171], v[104:107]
	v_mfma_i32_16x16x64_i8 v[116:119], v[144:147], v[176:179], v[116:119]
	v_mfma_i32_16x16x64_i8 v[100:103], v[152:155], v[176:179], v[100:103]
	v_mfma_i32_16x16x64_i8 v[108:111], v[144:147], v[184:187], v[108:111]
	v_mfma_i32_16x16x64_i8 v[96:99], v[152:155], v[184:187], v[96:99]
	v_mfma_i32_16x16x64_i8 v[124:127], v[148:151], v[164:167], v[124:127]
	v_mfma_i32_16x16x64_i8 v[112:115], v[156:159], v[164:167], v[112:115]
	v_mfma_i32_16x16x64_i8 v[120:123], v[148:151], v[172:175], v[120:123]
	v_mfma_i32_16x16x64_i8 v[104:107], v[156:159], v[172:175], v[104:107]
	v_mfma_i32_16x16x64_i8 v[116:119], v[148:151], v[180:183], v[116:119]
	v_mfma_i32_16x16x64_i8 v[100:103], v[156:159], v[180:183], v[100:103]
	v_mfma_i32_16x16x64_i8 v[108:111], v[148:151], v[188:191], v[108:111]
	v_mfma_i32_16x16x64_i8 v[96:99], v[156:159], v[188:191], v[96:99]
	s_barrier
	s_setprio 0
	s_add_i32 s20, s71, s19
	v_add_u32_e32 v204, s72, v224
	v_lshl_add_u64 v[208:209], s[58:59], 0, v[132:133]
	s_mov_b32 m0, s20
	ds_read_b128 v[192:195], v204
	ds_read_b128 v[196:199], v204 offset:1024
	ds_read_b128 v[200:203], v204 offset:2048
	ds_read_b128 v[204:207], v204 offset:3072
	global_load_lds_dwordx4 v[208:209], off
	v_lshl_add_u64 v[210:211], s[58:59], 0, v[128:129]
	s_add_i32 m0, s20, 0x2000
	s_nop 0
	global_load_lds_dwordx4 v[210:211], off
	s_setprio 1
	s_barrier
	s_waitcnt lgkmcnt(0)
	v_mfma_i32_16x16x64_i8 v[84:87], v[192:195], v[160:163], v[84:87]
	v_mfma_i32_16x16x64_i8 v[56:59], v[200:203], v[160:163], v[56:59]
	v_mfma_i32_16x16x64_i8 v[76:79], v[192:195], v[168:171], v[76:79]
	v_mfma_i32_16x16x64_i8 v[44:47], v[200:203], v[168:171], v[44:47]
	v_mfma_i32_16x16x64_i8 v[64:67], v[192:195], v[176:179], v[64:67]
	v_mfma_i32_16x16x64_i8 v[36:39], v[200:203], v[176:179], v[36:39]
	v_mfma_i32_16x16x64_i8 v[52:55], v[192:195], v[184:187], v[52:55]
	v_mfma_i32_16x16x64_i8 v[28:31], v[200:203], v[184:187], v[28:31]
	v_mfma_i32_16x16x64_i8 v[84:87], v[196:199], v[164:167], v[84:87]
	v_mfma_i32_16x16x64_i8 v[56:59], v[204:207], v[164:167], v[56:59]
	v_mfma_i32_16x16x64_i8 v[76:79], v[196:199], v[172:175], v[76:79]
	v_mfma_i32_16x16x64_i8 v[44:47], v[204:207], v[172:175], v[44:47]
	v_mfma_i32_16x16x64_i8 v[64:67], v[196:199], v[180:183], v[64:67]
	v_mfma_i32_16x16x64_i8 v[36:39], v[204:207], v[180:183], v[36:39]
	v_mfma_i32_16x16x64_i8 v[52:55], v[196:199], v[188:191], v[52:55]
	v_mfma_i32_16x16x64_i8 v[28:31], v[204:207], v[188:191], v[28:31]
	s_mov_b32 m0, s62
	v_lshl_add_u64 v[212:213], s[60:61], 0, v[134:135]
	s_barrier
	s_setprio 0
	ds_read_b128 v[160:163], v232 offset:16384
	ds_read_b128 v[164:167], v232 offset:17408
	ds_read_b128 v[168:171], v232 offset:18432
	ds_read_b128 v[172:175], v232 offset:19456
	ds_read_b128 v[176:179], v232 offset:20480
	ds_read_b128 v[180:183], v232 offset:21504
	ds_read_b128 v[184:187], v232 offset:22528
	ds_read_b128 v[188:191], v232 offset:23552
	global_load_lds_dwordx4 v[212:213], off
	v_lshl_add_u64 v[214:215], s[60:61], 0, v[130:131]
	s_mov_b32 m0, s63
	s_nop 0
	global_load_lds_dwordx4 v[214:215], off
	s_setprio 1
	s_barrier
	s_waitcnt lgkmcnt(0)
	v_mfma_i32_16x16x64_i8 v[92:95], v[144:147], v[160:163], v[92:95]
	v_mfma_i32_16x16x64_i8 v[72:75], v[152:155], v[160:163], v[72:75]
	v_mfma_i32_16x16x64_i8 v[88:91], v[144:147], v[168:171], v[88:91]
	v_mfma_i32_16x16x64_i8 v[60:63], v[152:155], v[168:171], v[60:63]
	v_mfma_i32_16x16x64_i8 v[80:83], v[144:147], v[176:179], v[80:83]
	v_mfma_i32_16x16x64_i8 v[48:51], v[152:155], v[176:179], v[48:51]
	v_mfma_i32_16x16x64_i8 v[68:71], v[144:147], v[184:187], v[68:71]
	v_mfma_i32_16x16x64_i8 v[40:43], v[152:155], v[184:187], v[40:43]
	v_mfma_i32_16x16x64_i8 v[92:95], v[148:151], v[164:167], v[92:95]
	v_mfma_i32_16x16x64_i8 v[72:75], v[156:159], v[164:167], v[72:75]
	v_mfma_i32_16x16x64_i8 v[88:91], v[148:151], v[172:175], v[88:91]
	v_mfma_i32_16x16x64_i8 v[60:63], v[156:159], v[172:175], v[60:63]
	v_mfma_i32_16x16x64_i8 v[80:83], v[148:151], v[180:183], v[80:83]
	v_mfma_i32_16x16x64_i8 v[48:51], v[156:159], v[180:183], v[48:51]
	v_mfma_i32_16x16x64_i8 v[68:71], v[148:151], v[188:191], v[68:71]
	v_mfma_i32_16x16x64_i8 v[40:43], v[156:159], v[188:191], v[40:43]
	s_barrier
	s_setprio 0
	s_add_u32 s20, s58, 0x20000
	s_addc_u32 s21, s59, 0
	s_add_i32 s56, s72, s19
	v_lshl_add_u64 v[144:145], s[20:21], 0, v[132:133]
	s_mov_b32 m0, s56
	s_nop 0
	global_load_lds_dwordx4 v[144:145], off
	v_lshl_add_u64 v[144:145], s[20:21], 0, v[128:129]
	s_add_i32 m0, s56, 0x2000
	s_nop 0
	global_load_lds_dwordx4 v[144:145], off
	s_waitcnt vmcnt(6)
	s_setprio 1
	s_barrier
	v_mfma_i32_16x16x64_i8 v[32:35], v[192:195], v[160:163], v[32:35]
	v_mfma_i32_16x16x64_i8 v[8:11], v[200:203], v[160:163], v[8:11]
	v_mfma_i32_16x16x64_i8 v[24:27], v[192:195], v[168:171], v[24:27]
	v_mfma_i32_16x16x64_i8 v[12:15], v[200:203], v[168:171], v[12:15]
	v_mfma_i32_16x16x64_i8 v[20:23], v[192:195], v[176:179], v[20:23]
	v_mfma_i32_16x16x64_i8 v[4:7], v[200:203], v[176:179], v[4:7]
	v_mfma_i32_16x16x64_i8 v[16:19], v[192:195], v[184:187], v[16:19]
	v_mfma_i32_16x16x64_i8 v[0:3], v[200:203], v[184:187], v[0:3]
	v_mfma_i32_16x16x64_i8 v[32:35], v[196:199], v[164:167], v[32:35]
	v_mfma_i32_16x16x64_i8 v[8:11], v[204:207], v[164:167], v[8:11]
	v_mfma_i32_16x16x64_i8 v[24:27], v[196:199], v[172:175], v[24:27]
	v_mfma_i32_16x16x64_i8 v[12:15], v[204:207], v[172:175], v[12:15]
	v_mfma_i32_16x16x64_i8 v[20:23], v[196:199], v[180:183], v[20:23]
	v_mfma_i32_16x16x64_i8 v[4:7], v[204:207], v[180:183], v[4:7]
	v_mfma_i32_16x16x64_i8 v[16:19], v[196:199], v[188:191], v[16:19]
	v_mfma_i32_16x16x64_i8 v[0:3], v[204:207], v[188:191], v[0:3]
	s_add_i32 s56, 0, 0x18000
	v_add_u32_e32 v156, s56, v224
	s_barrier
	s_setprio 0
	ds_read_b128 v[144:147], v156
	ds_read_b128 v[148:151], v156 offset:1024
	ds_read_b128 v[152:155], v156 offset:2048
	ds_read_b128 v[156:159], v156 offset:3072
	s_add_u32 s20, s60, 0x1000
	s_addc_u32 s21, s61, 0
	s_mov_b32 m0, s64
	v_lshl_add_u64 v[192:193], s[20:21], 0, v[134:135]
	ds_read_b128 v[160:163], v232 offset:32768
	ds_read_b128 v[164:167], v232 offset:33792
	ds_read_b128 v[168:171], v232 offset:34816
	ds_read_b128 v[172:175], v232 offset:35840
	ds_read_b128 v[176:179], v232 offset:36864
	ds_read_b128 v[180:183], v232 offset:37888
	ds_read_b128 v[184:187], v232 offset:38912
	ds_read_b128 v[188:191], v232 offset:39936
	global_load_lds_dwordx4 v[192:193], off
	v_lshl_add_u64 v[192:193], s[20:21], 0, v[130:131]
	s_mov_b32 m0, s65
	s_nop 0
	global_load_lds_dwordx4 v[192:193], off
	s_waitcnt lgkmcnt(8)
	s_setprio 1
	s_barrier
	s_waitcnt lgkmcnt(0)
	v_mfma_i32_16x16x64_i8 v[124:127], v[144:147], v[160:163], v[124:127]
	v_mfma_i32_16x16x64_i8 v[112:115], v[152:155], v[160:163], v[112:115]
	v_mfma_i32_16x16x64_i8 v[120:123], v[144:147], v[168:171], v[120:123]
	v_mfma_i32_16x16x64_i8 v[104:107], v[152:155], v[168:171], v[104:107]
	v_mfma_i32_16x16x64_i8 v[116:119], v[144:147], v[176:179], v[116:119]
	v_mfma_i32_16x16x64_i8 v[100:103], v[152:155], v[176:179], v[100:103]
	v_mfma_i32_16x16x64_i8 v[108:111], v[144:147], v[184:187], v[108:111]
	v_mfma_i32_16x16x64_i8 v[96:99], v[152:155], v[184:187], v[96:99]
	v_mfma_i32_16x16x64_i8 v[124:127], v[148:151], v[164:167], v[124:127]
	v_mfma_i32_16x16x64_i8 v[112:115], v[156:159], v[164:167], v[112:115]
	v_mfma_i32_16x16x64_i8 v[120:123], v[148:151], v[172:175], v[120:123]
	v_mfma_i32_16x16x64_i8 v[104:107], v[156:159], v[172:175], v[104:107]
	v_mfma_i32_16x16x64_i8 v[116:119], v[148:151], v[180:183], v[116:119]
	v_mfma_i32_16x16x64_i8 v[100:103], v[156:159], v[180:183], v[100:103]
	v_mfma_i32_16x16x64_i8 v[108:111], v[148:151], v[188:191], v[108:111]
	v_mfma_i32_16x16x64_i8 v[96:99], v[156:159], v[188:191], v[96:99]
	s_barrier
	s_setprio 0
	s_add_i32 s57, 0, 0x1c000
	s_add_i32 s20, s56, s19
	v_add_u32_e32 v204, s57, v224
	v_lshl_add_u64 v[208:209], v[208:209], 0, s[34:35]
	s_mov_b32 m0, s20
	ds_read_b128 v[192:195], v204
	ds_read_b128 v[196:199], v204 offset:1024
	ds_read_b128 v[200:203], v204 offset:2048
	ds_read_b128 v[204:207], v204 offset:3072
	global_load_lds_dwordx4 v[208:209], off
	v_lshl_add_u64 v[208:209], v[210:211], 0, s[34:35]
	s_add_i32 m0, s20, 0x2000
	s_nop 0
	global_load_lds_dwordx4 v[208:209], off
	s_setprio 1
	s_barrier
	s_waitcnt lgkmcnt(0)
	v_mfma_i32_16x16x64_i8 v[84:87], v[192:195], v[160:163], v[84:87]
	v_mfma_i32_16x16x64_i8 v[56:59], v[200:203], v[160:163], v[56:59]
	v_mfma_i32_16x16x64_i8 v[76:79], v[192:195], v[168:171], v[76:79]
	v_mfma_i32_16x16x64_i8 v[44:47], v[200:203], v[168:171], v[44:47]
	v_mfma_i32_16x16x64_i8 v[64:67], v[192:195], v[176:179], v[64:67]
	v_mfma_i32_16x16x64_i8 v[36:39], v[200:203], v[176:179], v[36:39]
	v_mfma_i32_16x16x64_i8 v[52:55], v[192:195], v[184:187], v[52:55]
	v_mfma_i32_16x16x64_i8 v[28:31], v[200:203], v[184:187], v[28:31]
	v_mfma_i32_16x16x64_i8 v[84:87], v[196:199], v[164:167], v[84:87]
	v_mfma_i32_16x16x64_i8 v[56:59], v[204:207], v[164:167], v[56:59]
	v_mfma_i32_16x16x64_i8 v[76:79], v[196:199], v[172:175], v[76:79]
	v_mfma_i32_16x16x64_i8 v[44:47], v[204:207], v[172:175], v[44:47]
	v_mfma_i32_16x16x64_i8 v[64:67], v[196:199], v[180:183], v[64:67]
	v_mfma_i32_16x16x64_i8 v[36:39], v[204:207], v[180:183], v[36:39]
	v_mfma_i32_16x16x64_i8 v[52:55], v[196:199], v[188:191], v[52:55]
	v_mfma_i32_16x16x64_i8 v[28:31], v[204:207], v[188:191], v[28:31]
	s_mov_b32 m0, s68
	v_lshl_add_u64 v[208:209], v[212:213], 0, s[34:35]
	s_barrier
	s_setprio 0
	ds_read_b128 v[160:163], v232 offset:49152
	ds_read_b128 v[164:167], v232 offset:50176
	ds_read_b128 v[168:171], v232 offset:51200
	ds_read_b128 v[172:175], v232 offset:52224
	ds_read_b128 v[176:179], v232 offset:53248
	ds_read_b128 v[180:183], v232 offset:54272
	ds_read_b128 v[184:187], v232 offset:55296
	ds_read_b128 v[188:191], v232 offset:56320
	global_load_lds_dwordx4 v[208:209], off
	v_lshl_add_u64 v[208:209], v[214:215], 0, s[34:35]
	s_mov_b32 m0, s69
	s_nop 0
	global_load_lds_dwordx4 v[208:209], off
	s_setprio 1
	s_barrier
	s_waitcnt lgkmcnt(0)
	v_mfma_i32_16x16x64_i8 v[92:95], v[144:147], v[160:163], v[92:95]
	v_mfma_i32_16x16x64_i8 v[72:75], v[152:155], v[160:163], v[72:75]
	v_mfma_i32_16x16x64_i8 v[88:91], v[144:147], v[168:171], v[88:91]
	v_mfma_i32_16x16x64_i8 v[60:63], v[152:155], v[168:171], v[60:63]
	v_mfma_i32_16x16x64_i8 v[80:83], v[144:147], v[176:179], v[80:83]
	v_mfma_i32_16x16x64_i8 v[48:51], v[152:155], v[176:179], v[48:51]
	v_mfma_i32_16x16x64_i8 v[68:71], v[144:147], v[184:187], v[68:71]
	v_mfma_i32_16x16x64_i8 v[40:43], v[152:155], v[184:187], v[40:43]
	v_mfma_i32_16x16x64_i8 v[92:95], v[148:151], v[164:167], v[92:95]
	v_mfma_i32_16x16x64_i8 v[72:75], v[156:159], v[164:167], v[72:75]
	v_mfma_i32_16x16x64_i8 v[88:91], v[148:151], v[172:175], v[88:91]
	v_mfma_i32_16x16x64_i8 v[60:63], v[156:159], v[172:175], v[60:63]
	v_mfma_i32_16x16x64_i8 v[80:83], v[148:151], v[180:183], v[80:83]
	v_mfma_i32_16x16x64_i8 v[48:51], v[156:159], v[180:183], v[48:51]
	v_mfma_i32_16x16x64_i8 v[68:71], v[148:151], v[188:191], v[68:71]
	v_mfma_i32_16x16x64_i8 v[40:43], v[156:159], v[188:191], v[40:43]
	s_barrier
	s_setprio 0
	s_add_u32 s20, s58, 0x20080
	s_addc_u32 s21, s59, 0
	s_add_i32 s56, s57, s19
	v_lshl_add_u64 v[144:145], s[20:21], 0, v[132:133]
	s_mov_b32 m0, s56
	s_nop 0
	global_load_lds_dwordx4 v[144:145], off
	v_lshl_add_u64 v[144:145], s[20:21], 0, v[128:129]
	s_add_i32 m0, s56, 0x2000
	s_nop 0
	global_load_lds_dwordx4 v[144:145], off
	s_waitcnt vmcnt(6)
	s_setprio 1
	s_barrier
	v_mfma_i32_16x16x64_i8 v[32:35], v[192:195], v[160:163], v[32:35]
	v_mfma_i32_16x16x64_i8 v[8:11], v[200:203], v[160:163], v[8:11]
	v_mfma_i32_16x16x64_i8 v[24:27], v[192:195], v[168:171], v[24:27]
	v_mfma_i32_16x16x64_i8 v[12:15], v[200:203], v[168:171], v[12:15]
	v_mfma_i32_16x16x64_i8 v[20:23], v[192:195], v[176:179], v[20:23]
	v_mfma_i32_16x16x64_i8 v[4:7], v[200:203], v[176:179], v[4:7]
	v_mfma_i32_16x16x64_i8 v[16:19], v[192:195], v[184:187], v[16:19]
	v_mfma_i32_16x16x64_i8 v[0:3], v[200:203], v[184:187], v[0:3]
	v_mfma_i32_16x16x64_i8 v[32:35], v[196:199], v[164:167], v[32:35]
	v_mfma_i32_16x16x64_i8 v[8:11], v[204:207], v[164:167], v[8:11]
	v_mfma_i32_16x16x64_i8 v[24:27], v[196:199], v[172:175], v[24:27]
	v_mfma_i32_16x16x64_i8 v[12:15], v[204:207], v[172:175], v[12:15]
	v_mfma_i32_16x16x64_i8 v[20:23], v[196:199], v[180:183], v[20:23]
	v_mfma_i32_16x16x64_i8 v[4:7], v[204:207], v[180:183], v[4:7]
	v_mfma_i32_16x16x64_i8 v[16:19], v[196:199], v[188:191], v[16:19]
	v_mfma_i32_16x16x64_i8 v[0:3], v[204:207], v[188:191], v[0:3]
	s_add_u32 s75, s75, 0x100
	s_addc_u32 s76, s76, 0
	s_cmp_ge_i32 s77, s67
	s_mov_b64 s[56:57], s[8:9]
	s_mov_b32 s58, s77
	s_barrier
	s_setprio 0
	s_cbranch_scc0 .LBB0_371

.Lpz_P4:
	s_and_b64 s[4:5], s[4:5], exec
	s_cselect_b32 s53, s59, s9
	s_cselect_b32 s55, s58, s8
	s_add_u32 s64, s8, 0x100
	s_addc_u32 s65, s9, 0
	s_mov_b32 s8, 0
	ds_read_b128 v[92:95], v229
	ds_read_b128 v[112:115], v229 offset:1024
	ds_read_b128 v[132:135], v229 offset:2048
	ds_read_b128 v[140:143], v229 offset:3072
	s_add_i32 s66, s8, 2
	s_add_u32 s4, s6, 0x100
	s_addc_u32 s5, s7, 0
	s_cmp_eq_u32 s19, s8
	s_cselect_b32 s8, s55, s64
	s_cselect_b32 s61, s57, s5
	s_cselect_b32 s60, s56, s4
	s_cselect_b32 s9, s53, s65
	v_lshl_add_u64 v[190:191], s[6:7], 0, v[166:167]
	s_add_i32 m0, s93, 0xc000
	ds_read_b128 v[144:147], v230
	ds_read_b128 v[148:151], v230 offset:1024
	ds_read_b128 v[152:155], v230 offset:2048
	ds_read_b128 v[170:173], v230 offset:3072
	ds_read_b128 v[174:177], v230 offset:4096
	ds_read_b128 v[178:181], v230 offset:5120
	ds_read_b128 v[182:185], v230 offset:6144
	ds_read_b128 v[186:189], v230 offset:7168
	global_load_lds_dwordx4 v[190:191], off
	v_lshl_add_u64 v[190:191], s[6:7], 0, v[168:169]
	s_add_i32 m0, s93, 0xe000
	s_nop 0
	global_load_lds_dwordx4 v[190:191], off
	s_waitcnt lgkmcnt(8)
	s_setprio 1
	s_barrier
	s_waitcnt lgkmcnt(0)
	v_mfma_f32_16x16x32_bf16 v[136:139], v[92:95], v[144:147], 0
	v_mfma_f32_16x16x32_bf16 v[124:127], v[132:135], v[144:147], 0
	v_mfma_f32_16x16x32_bf16 v[116:119], v[92:95], v[152:155], 0
	v_mfma_f32_16x16x32_bf16 v[104:107], v[132:135], v[152:155], 0
	v_mfma_f32_16x16x32_bf16 v[96:99], v[92:95], v[174:177], 0
	v_mfma_f32_16x16x32_bf16 v[84:87], v[132:135], v[174:177], 0
	v_mfma_f32_16x16x32_bf16 v[76:79], v[92:95], v[182:185], 0
	v_mfma_f32_16x16x32_bf16 v[68:71], v[132:135], v[182:185], 0
	v_mfma_f32_16x16x32_bf16 v[136:139], v[112:115], v[148:151], v[136:139]
	v_mfma_f32_16x16x32_bf16 v[124:127], v[140:143], v[148:151], v[124:127]
	v_mfma_f32_16x16x32_bf16 v[116:119], v[112:115], v[170:173], v[116:119]
	v_mfma_f32_16x16x32_bf16 v[104:107], v[140:143], v[170:173], v[104:107]
	v_mfma_f32_16x16x32_bf16 v[96:99], v[112:115], v[178:181], v[96:99]
	v_mfma_f32_16x16x32_bf16 v[84:87], v[140:143], v[178:181], v[84:87]
	v_mfma_f32_16x16x32_bf16 v[76:79], v[112:115], v[186:189], v[76:79]
	v_mfma_f32_16x16x32_bf16 v[68:71], v[140:143], v[186:189], v[68:71]
	s_barrier
	s_setprio 0
	s_add_i32 s6, s88, s92
	v_lshl_add_u64 v[206:207], s[8:9], 0, v[158:159]
	s_mov_b32 m0, s6
	ds_read_b128 v[190:193], v231
	ds_read_b128 v[194:197], v231 offset:1024
	ds_read_b128 v[198:201], v231 offset:2048
	ds_read_b128 v[202:205], v231 offset:3072
	global_load_lds_dwordx4 v[206:207], off
	v_lshl_add_u64 v[208:209], s[8:9], 0, v[162:163]
	s_add_i32 m0, s6, 0x2000
	s_nop 0
	global_load_lds_dwordx4 v[208:209], off
	s_setprio 1
	s_barrier
	s_waitcnt lgkmcnt(0)
	v_mfma_f32_16x16x32_bf16 v[128:131], v[190:193], v[144:147], 0
	v_mfma_f32_16x16x32_bf16 v[120:123], v[198:201], v[144:147], 0
	v_mfma_f32_16x16x32_bf16 v[108:111], v[190:193], v[152:155], 0
	v_mfma_f32_16x16x32_bf16 v[100:103], v[198:201], v[152:155], 0
	v_mfma_f32_16x16x32_bf16 v[88:91], v[190:193], v[174:177], 0
	v_mfma_f32_16x16x32_bf16 v[80:83], v[198:201], v[174:177], 0
	v_mfma_f32_16x16x32_bf16 v[72:75], v[190:193], v[182:185], 0
	v_mfma_f32_16x16x32_bf16 v[64:67], v[198:201], v[182:185], 0
	v_mfma_f32_16x16x32_bf16 v[128:131], v[194:197], v[148:151], v[128:131]
	v_mfma_f32_16x16x32_bf16 v[120:123], v[202:205], v[148:151], v[120:123]
	v_mfma_f32_16x16x32_bf16 v[108:111], v[194:197], v[170:173], v[108:111]
	v_mfma_f32_16x16x32_bf16 v[100:103], v[202:205], v[170:173], v[100:103]
	v_mfma_f32_16x16x32_bf16 v[88:91], v[194:197], v[178:181], v[88:91]
	v_mfma_f32_16x16x32_bf16 v[80:83], v[202:205], v[178:181], v[80:83]
	v_mfma_f32_16x16x32_bf16 v[72:75], v[194:197], v[186:189], v[72:75]
	v_mfma_f32_16x16x32_bf16 v[64:67], v[202:205], v[186:189], v[64:67]
	s_mov_b32 m0, s93
	v_lshl_add_u64 v[210:211], s[60:61], 0, v[156:157]
	s_barrier
	s_setprio 0
	ds_read_b128 v[144:147], v230 offset:16384
	ds_read_b128 v[148:151], v230 offset:17408
	ds_read_b128 v[152:155], v230 offset:18432
	ds_read_b128 v[170:173], v230 offset:19456
	ds_read_b128 v[174:177], v230 offset:20480
	ds_read_b128 v[178:181], v230 offset:21504
	ds_read_b128 v[182:185], v230 offset:22528
	ds_read_b128 v[186:189], v230 offset:23552
	global_load_lds_dwordx4 v[210:211], off
	v_lshl_add_u64 v[212:213], s[60:61], 0, v[160:161]
	s_mov_b32 m0, s84
	s_nop 0
	global_load_lds_dwordx4 v[212:213], off
	s_setprio 1
	s_barrier
	s_waitcnt lgkmcnt(0)
	v_mfma_f32_16x16x32_bf16 v[60:63], v[92:95], v[144:147], 0
	v_mfma_f32_16x16x32_bf16 v[52:55], v[132:135], v[144:147], 0
	v_mfma_f32_16x16x32_bf16 v[44:47], v[92:95], v[152:155], 0
	v_mfma_f32_16x16x32_bf16 v[36:39], v[132:135], v[152:155], 0
	v_mfma_f32_16x16x32_bf16 v[28:31], v[92:95], v[174:177], 0
	v_mfma_f32_16x16x32_bf16 v[20:23], v[132:135], v[174:177], 0
	v_mfma_f32_16x16x32_bf16 v[12:15], v[92:95], v[182:185], 0
	v_mfma_f32_16x16x32_bf16 v[4:7], v[132:135], v[182:185], 0
	v_mfma_f32_16x16x32_bf16 v[60:63], v[112:115], v[148:151], v[60:63]
	v_mfma_f32_16x16x32_bf16 v[52:55], v[140:143], v[148:151], v[52:55]
	v_mfma_f32_16x16x32_bf16 v[44:47], v[112:115], v[170:173], v[44:47]
	v_mfma_f32_16x16x32_bf16 v[36:39], v[140:143], v[170:173], v[36:39]
	v_mfma_f32_16x16x32_bf16 v[28:31], v[112:115], v[178:181], v[28:31]
	v_mfma_f32_16x16x32_bf16 v[20:23], v[140:143], v[178:181], v[20:23]
	v_mfma_f32_16x16x32_bf16 v[12:15], v[112:115], v[186:189], v[12:15]
	v_mfma_f32_16x16x32_bf16 v[4:7], v[140:143], v[186:189], v[4:7]
	s_barrier
	s_setprio 0
	s_add_u32 s6, s8, 0x10000
	s_addc_u32 s7, s9, 0
	s_add_i32 s20, s89, s92
	v_lshl_add_u64 v[92:93], s[6:7], 0, v[158:159]
	s_mov_b32 m0, s20
	s_nop 0
	global_load_lds_dwordx4 v[92:93], off
	v_lshl_add_u64 v[92:93], s[6:7], 0, v[162:163]
	s_add_i32 m0, s20, 0x2000
	s_nop 0
	global_load_lds_dwordx4 v[92:93], off
	s_waitcnt vmcnt(6)
	s_setprio 1
	s_barrier
	v_mfma_f32_16x16x32_bf16 v[56:59], v[190:193], v[144:147], 0
	v_mfma_f32_16x16x32_bf16 v[48:51], v[198:201], v[144:147], 0
	v_mfma_f32_16x16x32_bf16 v[40:43], v[190:193], v[152:155], 0
	v_mfma_f32_16x16x32_bf16 v[32:35], v[198:201], v[152:155], 0
	v_mfma_f32_16x16x32_bf16 v[24:27], v[190:193], v[174:177], 0
	v_mfma_f32_16x16x32_bf16 v[16:19], v[198:201], v[174:177], 0
	v_mfma_f32_16x16x32_bf16 v[8:11], v[190:193], v[182:185], 0
	v_mfma_f32_16x16x32_bf16 v[0:3], v[198:201], v[182:185], 0
	v_mfma_f32_16x16x32_bf16 v[56:59], v[194:197], v[148:151], v[56:59]
	v_mfma_f32_16x16x32_bf16 v[48:51], v[202:205], v[148:151], v[48:51]
	v_mfma_f32_16x16x32_bf16 v[40:43], v[194:197], v[170:173], v[40:43]
	v_mfma_f32_16x16x32_bf16 v[32:35], v[202:205], v[170:173], v[32:35]
	v_mfma_f32_16x16x32_bf16 v[24:27], v[194:197], v[178:181], v[24:27]
	v_mfma_f32_16x16x32_bf16 v[16:19], v[202:205], v[178:181], v[16:19]
	v_mfma_f32_16x16x32_bf16 v[8:11], v[194:197], v[186:189], v[8:11]
	v_mfma_f32_16x16x32_bf16 v[0:3], v[202:205], v[186:189], v[0:3]
	s_add_i32 s20, 0, 0x18000
	v_add_u32_e32 v140, s20, v228
	s_barrier
	s_setprio 0
	ds_read_b128 v[92:95], v140
	ds_read_b128 v[112:115], v140 offset:1024
	ds_read_b128 v[132:135], v140 offset:2048
	ds_read_b128 v[140:143], v140 offset:3072
	s_add_u32 s6, s60, 0x2000
	s_addc_u32 s7, s61, 0
	s_mov_b32 m0, s86
	v_lshl_add_u64 v[190:191], s[6:7], 0, v[156:157]
	ds_read_b128 v[144:147], v230 offset:32768
	ds_read_b128 v[148:151], v230 offset:33792
	ds_read_b128 v[152:155], v230 offset:34816
	ds_read_b128 v[170:173], v230 offset:35840
	ds_read_b128 v[174:177], v230 offset:36864
	ds_read_b128 v[178:181], v230 offset:37888
	ds_read_b128 v[182:185], v230 offset:38912
	ds_read_b128 v[186:189], v230 offset:39936
	global_load_lds_dwordx4 v[190:191], off
	v_lshl_add_u64 v[190:191], s[6:7], 0, v[160:161]
	s_mov_b32 m0, s87
	s_nop 0
	global_load_lds_dwordx4 v[190:191], off
	s_waitcnt lgkmcnt(8)
	s_setprio 1
	s_barrier
	s_waitcnt lgkmcnt(0)
	v_mfma_f32_16x16x32_bf16 v[136:139], v[92:95], v[144:147], v[136:139]
	v_mfma_f32_16x16x32_bf16 v[124:127], v[132:135], v[144:147], v[124:127]
	v_mfma_f32_16x16x32_bf16 v[116:119], v[92:95], v[152:155], v[116:119]
	v_mfma_f32_16x16x32_bf16 v[104:107], v[132:135], v[152:155], v[104:107]
	v_mfma_f32_16x16x32_bf16 v[96:99], v[92:95], v[174:177], v[96:99]
	v_mfma_f32_16x16x32_bf16 v[84:87], v[132:135], v[174:177], v[84:87]
	v_mfma_f32_16x16x32_bf16 v[76:79], v[92:95], v[182:185], v[76:79]
	v_mfma_f32_16x16x32_bf16 v[68:71], v[132:135], v[182:185], v[68:71]
	v_mfma_f32_16x16x32_bf16 v[136:139], v[112:115], v[148:151], v[136:139]
	v_mfma_f32_16x16x32_bf16 v[124:127], v[140:143], v[148:151], v[124:127]
	v_mfma_f32_16x16x32_bf16 v[116:119], v[112:115], v[170:173], v[116:119]
	v_mfma_f32_16x16x32_bf16 v[104:107], v[140:143], v[170:173], v[104:107]
	v_mfma_f32_16x16x32_bf16 v[96:99], v[112:115], v[178:181], v[96:99]
	v_mfma_f32_16x16x32_bf16 v[84:87], v[140:143], v[178:181], v[84:87]
	v_mfma_f32_16x16x32_bf16 v[76:79], v[112:115], v[186:189], v[76:79]
	v_mfma_f32_16x16x32_bf16 v[68:71], v[140:143], v[186:189], v[68:71]
	s_barrier
	s_setprio 0
	s_add_i32 s21, 0, 0x1c000
	s_add_i32 s6, s20, s92
	v_add_u32_e32 v164, s21, v228
	v_lshl_add_u64 v[206:207], v[206:207], 0, s[42:43]
	s_mov_b32 m0, s6
	ds_read_b128 v[190:193], v164
	ds_read_b128 v[194:197], v164 offset:1024
	ds_read_b128 v[198:201], v164 offset:2048
	ds_read_b128 v[202:205], v164 offset:3072
	global_load_lds_dwordx4 v[206:207], off
	v_lshl_add_u64 v[206:207], v[208:209], 0, s[42:43]
	s_add_i32 m0, s6, 0x2000
	s_nop 0
	global_load_lds_dwordx4 v[206:207], off
	s_setprio 1
	s_barrier
	s_waitcnt lgkmcnt(0)
	v_mfma_f32_16x16x32_bf16 v[128:131], v[190:193], v[144:147], v[128:131]
	v_mfma_f32_16x16x32_bf16 v[120:123], v[198:201], v[144:147], v[120:123]
	v_mfma_f32_16x16x32_bf16 v[108:111], v[190:193], v[152:155], v[108:111]
	v_mfma_f32_16x16x32_bf16 v[100:103], v[198:201], v[152:155], v[100:103]
	v_mfma_f32_16x16x32_bf16 v[88:91], v[190:193], v[174:177], v[88:91]
	v_mfma_f32_16x16x32_bf16 v[80:83], v[198:201], v[174:177], v[80:83]
	v_mfma_f32_16x16x32_bf16 v[72:75], v[190:193], v[182:185], v[72:75]
	v_mfma_f32_16x16x32_bf16 v[64:67], v[198:201], v[182:185], v[64:67]
	v_mfma_f32_16x16x32_bf16 v[128:131], v[194:197], v[148:151], v[128:131]
	v_mfma_f32_16x16x32_bf16 v[120:123], v[202:205], v[148:151], v[120:123]
	v_mfma_f32_16x16x32_bf16 v[108:111], v[194:197], v[170:173], v[108:111]
	v_mfma_f32_16x16x32_bf16 v[100:103], v[202:205], v[170:173], v[100:103]
	v_mfma_f32_16x16x32_bf16 v[88:91], v[194:197], v[178:181], v[88:91]
	v_mfma_f32_16x16x32_bf16 v[80:83], v[202:205], v[178:181], v[80:83]
	v_mfma_f32_16x16x32_bf16 v[72:75], v[194:197], v[186:189], v[72:75]
	v_mfma_f32_16x16x32_bf16 v[64:67], v[202:205], v[186:189], v[64:67]
	s_mov_b32 m0, s97
	v_lshl_add_u64 v[206:207], v[210:211], 0, s[42:43]
	s_barrier
	s_setprio 0
	ds_read_b128 v[144:147], v230 offset:49152
	ds_read_b128 v[148:151], v230 offset:50176
	ds_read_b128 v[152:155], v230 offset:51200
	ds_read_b128 v[170:173], v230 offset:52224
	ds_read_b128 v[174:177], v230 offset:53248
	ds_read_b128 v[178:181], v230 offset:54272
	ds_read_b128 v[182:185], v230 offset:55296
	ds_read_b128 v[186:189], v230 offset:56320
	global_load_lds_dwordx4 v[206:207], off
	v_lshl_add_u64 v[206:207], v[212:213], 0, s[42:43]
	s_mov_b32 m0, s18
	s_nop 0
	global_load_lds_dwordx4 v[206:207], off
	s_setprio 1
	s_barrier
	s_waitcnt lgkmcnt(0)
	v_mfma_f32_16x16x32_bf16 v[60:63], v[92:95], v[144:147], v[60:63]
	v_mfma_f32_16x16x32_bf16 v[52:55], v[132:135], v[144:147], v[52:55]
	v_mfma_f32_16x16x32_bf16 v[44:47], v[92:95], v[152:155], v[44:47]
	v_mfma_f32_16x16x32_bf16 v[36:39], v[132:135], v[152:155], v[36:39]
	v_mfma_f32_16x16x32_bf16 v[28:31], v[92:95], v[174:177], v[28:31]
	v_mfma_f32_16x16x32_bf16 v[20:23], v[132:135], v[174:177], v[20:23]
	v_mfma_f32_16x16x32_bf16 v[12:15], v[92:95], v[182:185], v[12:15]
	v_mfma_f32_16x16x32_bf16 v[4:7], v[132:135], v[182:185], v[4:7]
	v_mfma_f32_16x16x32_bf16 v[60:63], v[112:115], v[148:151], v[60:63]
	v_mfma_f32_16x16x32_bf16 v[52:55], v[140:143], v[148:151], v[52:55]
	v_mfma_f32_16x16x32_bf16 v[44:47], v[112:115], v[170:173], v[44:47]
	v_mfma_f32_16x16x32_bf16 v[36:39], v[140:143], v[170:173], v[36:39]
	v_mfma_f32_16x16x32_bf16 v[28:31], v[112:115], v[178:181], v[28:31]
	v_mfma_f32_16x16x32_bf16 v[20:23], v[140:143], v[178:181], v[20:23]
	v_mfma_f32_16x16x32_bf16 v[12:15], v[112:115], v[186:189], v[12:15]
	v_mfma_f32_16x16x32_bf16 v[4:7], v[140:143], v[186:189], v[4:7]
	s_barrier
	s_setprio 0
	s_add_u32 s6, s8, 0x10080
	s_addc_u32 s7, s9, 0
	s_add_i32 s8, s21, s92
	v_lshl_add_u64 v[92:93], s[6:7], 0, v[158:159]
	s_mov_b32 m0, s8
	s_nop 0
	global_load_lds_dwordx4 v[92:93], off
	v_lshl_add_u64 v[92:93], s[6:7], 0, v[162:163]
	s_add_i32 m0, s8, 0x2000
	s_nop 0
	global_load_lds_dwordx4 v[92:93], off
	s_waitcnt vmcnt(6)
	s_setprio 1
	s_barrier
	v_mfma_f32_16x16x32_bf16 v[56:59], v[190:193], v[144:147], v[56:59]
	v_mfma_f32_16x16x32_bf16 v[48:51], v[198:201], v[144:147], v[48:51]
	v_mfma_f32_16x16x32_bf16 v[40:43], v[190:193], v[152:155], v[40:43]
	v_mfma_f32_16x16x32_bf16 v[32:35], v[198:201], v[152:155], v[32:35]
	v_mfma_f32_16x16x32_bf16 v[24:27], v[190:193], v[174:177], v[24:27]
	v_mfma_f32_16x16x32_bf16 v[16:19], v[198:201], v[174:177], v[16:19]
	v_mfma_f32_16x16x32_bf16 v[8:11], v[190:193], v[182:185], v[8:11]
	v_mfma_f32_16x16x32_bf16 v[0:3], v[198:201], v[182:185], v[0:3]
	v_mfma_f32_16x16x32_bf16 v[56:59], v[194:197], v[148:151], v[56:59]
	v_mfma_f32_16x16x32_bf16 v[48:51], v[202:205], v[148:151], v[48:51]
	v_mfma_f32_16x16x32_bf16 v[40:43], v[194:197], v[170:173], v[40:43]
	v_mfma_f32_16x16x32_bf16 v[32:35], v[202:205], v[170:173], v[32:35]
	v_mfma_f32_16x16x32_bf16 v[24:27], v[194:197], v[178:181], v[24:27]
	v_mfma_f32_16x16x32_bf16 v[16:19], v[202:205], v[178:181], v[16:19]
	v_mfma_f32_16x16x32_bf16 v[8:11], v[194:197], v[186:189], v[8:11]
	v_mfma_f32_16x16x32_bf16 v[0:3], v[202:205], v[186:189], v[0:3]
	s_add_u32 s64, s64, 0x100
	s_addc_u32 s65, s65, 0
	s_cmp_lt_i32 s66, s95
	s_mov_b64 s[6:7], s[4:5]
	s_mov_b32 s8, s66
	s_barrier
	s_setprio 0
	s_cbranch_scc0 .Lpeel_done_P4
.LBB0_461:
	ds_read_b128 v[92:95], v229
	ds_read_b128 v[112:115], v229 offset:1024
	ds_read_b128 v[132:135], v229 offset:2048
	ds_read_b128 v[140:143], v229 offset:3072
	s_add_i32 s66, s8, 2
	s_add_u32 s4, s6, 0x100
	s_addc_u32 s5, s7, 0
	s_cmp_eq_u32 s19, s8
	s_cselect_b32 s8, s55, s64
	s_cselect_b32 s61, s57, s5
	s_cselect_b32 s60, s56, s4
	s_cselect_b32 s9, s53, s65
	v_lshl_add_u64 v[190:191], s[6:7], 0, v[166:167]
	s_add_i32 m0, s93, 0xc000
	ds_read_b128 v[144:147], v230
	ds_read_b128 v[148:151], v230 offset:1024
	ds_read_b128 v[152:155], v230 offset:2048
	ds_read_b128 v[170:173], v230 offset:3072
	ds_read_b128 v[174:177], v230 offset:4096
	ds_read_b128 v[178:181], v230 offset:5120
	ds_read_b128 v[182:185], v230 offset:6144
	ds_read_b128 v[186:189], v230 offset:7168
	global_load_lds_dwordx4 v[190:191], off
	v_lshl_add_u64 v[190:191], s[6:7], 0, v[168:169]
	s_add_i32 m0, s93, 0xe000
	s_nop 0
	global_load_lds_dwordx4 v[190:191], off
	s_waitcnt lgkmcnt(8)
	s_setprio 1
	s_barrier
	s_waitcnt lgkmcnt(0)
	v_mfma_f32_16x16x32_bf16 v[136:139], v[92:95], v[144:147], v[136:139]
	v_mfma_f32_16x16x32_bf16 v[124:127], v[132:135], v[144:147], v[124:127]
	v_mfma_f32_16x16x32_bf16 v[116:119], v[92:95], v[152:155], v[116:119]
	v_mfma_f32_16x16x32_bf16 v[104:107], v[132:135], v[152:155], v[104:107]
	v_mfma_f32_16x16x32_bf16 v[96:99], v[92:95], v[174:177], v[96:99]
	v_mfma_f32_16x16x32_bf16 v[84:87], v[132:135], v[174:177], v[84:87]
	v_mfma_f32_16x16x32_bf16 v[76:79], v[92:95], v[182:185], v[76:79]
	v_mfma_f32_16x16x32_bf16 v[68:71], v[132:135], v[182:185], v[68:71]
	v_mfma_f32_16x16x32_bf16 v[136:139], v[112:115], v[148:151], v[136:139]
	v_mfma_f32_16x16x32_bf16 v[124:127], v[140:143], v[148:151], v[124:127]
	v_mfma_f32_16x16x32_bf16 v[116:119], v[112:115], v[170:173], v[116:119]
	v_mfma_f32_16x16x32_bf16 v[104:107], v[140:143], v[170:173], v[104:107]
	v_mfma_f32_16x16x32_bf16 v[96:99], v[112:115], v[178:181], v[96:99]
	v_mfma_f32_16x16x32_bf16 v[84:87], v[140:143], v[178:181], v[84:87]
	v_mfma_f32_16x16x32_bf16 v[76:79], v[112:115], v[186:189], v[76:79]
	v_mfma_f32_16x16x32_bf16 v[68:71], v[140:143], v[186:189], v[68:71]
	s_barrier
	s_setprio 0
	s_add_i32 s6, s88, s92
	v_lshl_add_u64 v[206:207], s[8:9], 0, v[158:159]
	s_mov_b32 m0, s6
	ds_read_b128 v[190:193], v231
	ds_read_b128 v[194:197], v231 offset:1024
	ds_read_b128 v[198:201], v231 offset:2048
	ds_read_b128 v[202:205], v231 offset:3072
	global_load_lds_dwordx4 v[206:207], off
	v_lshl_add_u64 v[208:209], s[8:9], 0, v[162:163]
	s_add_i32 m0, s6, 0x2000
	s_nop 0
	global_load_lds_dwordx4 v[208:209], off
	s_setprio 1
	s_barrier
	s_waitcnt lgkmcnt(0)
	v_mfma_f32_16x16x32_bf16 v[128:131], v[190:193], v[144:147], v[128:131]
	v_mfma_f32_16x16x32_bf16 v[120:123], v[198:201], v[144:147], v[120:123]
	v_mfma_f32_16x16x32_bf16 v[108:111], v[190:193], v[152:155], v[108:111]
	v_mfma_f32_16x16x32_bf16 v[100:103], v[198:201], v[152:155], v[100:103]
	v_mfma_f32_16x16x32_bf16 v[88:91], v[190:193], v[174:177], v[88:91]
	v_mfma_f32_16x16x32_bf16 v[80:83], v[198:201], v[174:177], v[80:83]
	v_mfma_f32_16x16x32_bf16 v[72:75], v[190:193], v[182:185], v[72:75]
	v_mfma_f32_16x16x32_bf16 v[64:67], v[198:201], v[182:185], v[64:67]
	v_mfma_f32_16x16x32_bf16 v[128:131], v[194:197], v[148:151], v[128:131]
	v_mfma_f32_16x16x32_bf16 v[120:123], v[202:205], v[148:151], v[120:123]
	v_mfma_f32_16x16x32_bf16 v[108:111], v[194:197], v[170:173], v[108:111]
	v_mfma_f32_16x16x32_bf16 v[100:103], v[202:205], v[170:173], v[100:103]
	v_mfma_f32_16x16x32_bf16 v[88:91], v[194:197], v[178:181], v[88:91]
	v_mfma_f32_16x16x32_bf16 v[80:83], v[202:205], v[178:181], v[80:83]
	v_mfma_f32_16x16x32_bf16 v[72:75], v[194:197], v[186:189], v[72:75]
	v_mfma_f32_16x16x32_bf16 v[64:67], v[202:205], v[186:189], v[64:67]
	s_mov_b32 m0, s93
	v_lshl_add_u64 v[210:211], s[60:61], 0, v[156:157]
	s_barrier
	s_setprio 0
	ds_read_b128 v[144:147], v230 offset:16384
	ds_read_b128 v[148:151], v230 offset:17408
	ds_read_b128 v[152:155], v230 offset:18432
	ds_read_b128 v[170:173], v230 offset:19456
	ds_read_b128 v[174:177], v230 offset:20480
	ds_read_b128 v[178:181], v230 offset:21504
	ds_read_b128 v[182:185], v230 offset:22528
	ds_read_b128 v[186:189], v230 offset:23552
	global_load_lds_dwordx4 v[210:211], off
	v_lshl_add_u64 v[212:213], s[60:61], 0, v[160:161]
	s_mov_b32 m0, s84
	s_nop 0
	global_load_lds_dwordx4 v[212:213], off
	s_setprio 1
	s_barrier
	s_waitcnt lgkmcnt(0)
	v_mfma_f32_16x16x32_bf16 v[60:63], v[92:95], v[144:147], v[60:63]
	v_mfma_f32_16x16x32_bf16 v[52:55], v[132:135], v[144:147], v[52:55]
	v_mfma_f32_16x16x32_bf16 v[44:47], v[92:95], v[152:155], v[44:47]
	v_mfma_f32_16x16x32_bf16 v[36:39], v[132:135], v[152:155], v[36:39]
	v_mfma_f32_16x16x32_bf16 v[28:31], v[92:95], v[174:177], v[28:31]
	v_mfma_f32_16x16x32_bf16 v[20:23], v[132:135], v[174:177], v[20:23]
	v_mfma_f32_16x16x32_bf16 v[12:15], v[92:95], v[182:185], v[12:15]
	v_mfma_f32_16x16x32_bf16 v[4:7], v[132:135], v[182:185], v[4:7]
	v_mfma_f32_16x16x32_bf16 v[60:63], v[112:115], v[148:151], v[60:63]
	v_mfma_f32_16x16x32_bf16 v[52:55], v[140:143], v[148:151], v[52:55]
	v_mfma_f32_16x16x32_bf16 v[44:47], v[112:115], v[170:173], v[44:47]
	v_mfma_f32_16x16x32_bf16 v[36:39], v[140:143], v[170:173], v[36:39]
	v_mfma_f32_16x16x32_bf16 v[28:31], v[112:115], v[178:181], v[28:31]
	v_mfma_f32_16x16x32_bf16 v[20:23], v[140:143], v[178:181], v[20:23]
	v_mfma_f32_16x16x32_bf16 v[12:15], v[112:115], v[186:189], v[12:15]
	v_mfma_f32_16x16x32_bf16 v[4:7], v[140:143], v[186:189], v[4:7]
	s_barrier
	s_setprio 0
	s_add_u32 s6, s8, 0x10000
	s_addc_u32 s7, s9, 0
	s_add_i32 s20, s89, s92
	v_lshl_add_u64 v[92:93], s[6:7], 0, v[158:159]
	s_mov_b32 m0, s20
	s_nop 0
	global_load_lds_dwordx4 v[92:93], off
	v_lshl_add_u64 v[92:93], s[6:7], 0, v[162:163]
	s_add_i32 m0, s20, 0x2000
	s_nop 0
	global_load_lds_dwordx4 v[92:93], off
	s_waitcnt vmcnt(6)
	s_setprio 1
	s_barrier
	v_mfma_f32_16x16x32_bf16 v[56:59], v[190:193], v[144:147], v[56:59]
	v_mfma_f32_16x16x32_bf16 v[48:51], v[198:201], v[144:147], v[48:51]
	v_mfma_f32_16x16x32_bf16 v[40:43], v[190:193], v[152:155], v[40:43]
	v_mfma_f32_16x16x32_bf16 v[32:35], v[198:201], v[152:155], v[32:35]
	v_mfma_f32_16x16x32_bf16 v[24:27], v[190:193], v[174:177], v[24:27]
	v_mfma_f32_16x16x32_bf16 v[16:19], v[198:201], v[174:177], v[16:19]
	v_mfma_f32_16x16x32_bf16 v[8:11], v[190:193], v[182:185], v[8:11]
	v_mfma_f32_16x16x32_bf16 v[0:3], v[198:201], v[182:185], v[0:3]
	v_mfma_f32_16x16x32_bf16 v[56:59], v[194:197], v[148:151], v[56:59]
	v_mfma_f32_16x16x32_bf16 v[48:51], v[202:205], v[148:151], v[48:51]
	v_mfma_f32_16x16x32_bf16 v[40:43], v[194:197], v[170:173], v[40:43]
	v_mfma_f32_16x16x32_bf16 v[32:35], v[202:205], v[170:173], v[32:35]
	v_mfma_f32_16x16x32_bf16 v[24:27], v[194:197], v[178:181], v[24:27]
	v_mfma_f32_16x16x32_bf16 v[16:19], v[202:205], v[178:181], v[16:19]
	v_mfma_f32_16x16x32_bf16 v[8:11], v[194:197], v[186:189], v[8:11]
	v_mfma_f32_16x16x32_bf16 v[0:3], v[202:205], v[186:189], v[0:3]
	s_add_i32 s20, 0, 0x18000
	v_add_u32_e32 v140, s20, v228
	s_barrier
	s_setprio 0
	ds_read_b128 v[92:95], v140
	ds_read_b128 v[112:115], v140 offset:1024
	ds_read_b128 v[132:135], v140 offset:2048
	ds_read_b128 v[140:143], v140 offset:3072
	s_add_u32 s6, s60, 0x2000
	s_addc_u32 s7, s61, 0
	s_mov_b32 m0, s86
	v_lshl_add_u64 v[190:191], s[6:7], 0, v[156:157]
	ds_read_b128 v[144:147], v230 offset:32768
	ds_read_b128 v[148:151], v230 offset:33792
	ds_read_b128 v[152:155], v230 offset:34816
	ds_read_b128 v[170:173], v230 offset:35840
	ds_read_b128 v[174:177], v230 offset:36864
	ds_read_b128 v[178:181], v230 offset:37888
	ds_read_b128 v[182:185], v230 offset:38912
	ds_read_b128 v[186:189], v230 offset:39936
	global_load_lds_dwordx4 v[190:191], off
	v_lshl_add_u64 v[190:191], s[6:7], 0, v[160:161]
	s_mov_b32 m0, s87
	s_nop 0
	global_load_lds_dwordx4 v[190:191], off
	s_waitcnt lgkmcnt(8)
	s_setprio 1
	s_barrier
	s_waitcnt lgkmcnt(0)
	v_mfma_f32_16x16x32_bf16 v[136:139], v[92:95], v[144:147], v[136:139]
	v_mfma_f32_16x16x32_bf16 v[124:127], v[132:135], v[144:147], v[124:127]
	v_mfma_f32_16x16x32_bf16 v[116:119], v[92:95], v[152:155], v[116:119]
	v_mfma_f32_16x16x32_bf16 v[104:107], v[132:135], v[152:155], v[104:107]
	v_mfma_f32_16x16x32_bf16 v[96:99], v[92:95], v[174:177], v[96:99]
	v_mfma_f32_16x16x32_bf16 v[84:87], v[132:135], v[174:177], v[84:87]
	v_mfma_f32_16x16x32_bf16 v[76:79], v[92:95], v[182:185], v[76:79]
	v_mfma_f32_16x16x32_bf16 v[68:71], v[132:135], v[182:185], v[68:71]
	v_mfma_f32_16x16x32_bf16 v[136:139], v[112:115], v[148:151], v[136:139]
	v_mfma_f32_16x16x32_bf16 v[124:127], v[140:143], v[148:151], v[124:127]
	v_mfma_f32_16x16x32_bf16 v[116:119], v[112:115], v[170:173], v[116:119]
	v_mfma_f32_16x16x32_bf16 v[104:107], v[140:143], v[170:173], v[104:107]
	v_mfma_f32_16x16x32_bf16 v[96:99], v[112:115], v[178:181], v[96:99]
	v_mfma_f32_16x16x32_bf16 v[84:87], v[140:143], v[178:181], v[84:87]
	v_mfma_f32_16x16x32_bf16 v[76:79], v[112:115], v[186:189], v[76:79]
	v_mfma_f32_16x16x32_bf16 v[68:71], v[140:143], v[186:189], v[68:71]
	s_barrier
	s_setprio 0
	s_add_i32 s21, 0, 0x1c000
	s_add_i32 s6, s20, s92
	v_add_u32_e32 v164, s21, v228
	v_lshl_add_u64 v[206:207], v[206:207], 0, s[42:43]
	s_mov_b32 m0, s6
	ds_read_b128 v[190:193], v164
	ds_read_b128 v[194:197], v164 offset:1024
	ds_read_b128 v[198:201], v164 offset:2048
	ds_read_b128 v[202:205], v164 offset:3072
	global_load_lds_dwordx4 v[206:207], off
	v_lshl_add_u64 v[206:207], v[208:209], 0, s[42:43]
	s_add_i32 m0, s6, 0x2000
	s_nop 0
	global_load_lds_dwordx4 v[206:207], off
	s_setprio 1
	s_barrier
	s_waitcnt lgkmcnt(0)
	v_mfma_f32_16x16x32_bf16 v[128:131], v[190:193], v[144:147], v[128:131]
	v_mfma_f32_16x16x32_bf16 v[120:123], v[198:201], v[144:147], v[120:123]
	v_mfma_f32_16x16x32_bf16 v[108:111], v[190:193], v[152:155], v[108:111]
	v_mfma_f32_16x16x32_bf16 v[100:103], v[198:201], v[152:155], v[100:103]
	v_mfma_f32_16x16x32_bf16 v[88:91], v[190:193], v[174:177], v[88:91]
	v_mfma_f32_16x16x32_bf16 v[80:83], v[198:201], v[174:177], v[80:83]
	v_mfma_f32_16x16x32_bf16 v[72:75], v[190:193], v[182:185], v[72:75]
	v_mfma_f32_16x16x32_bf16 v[64:67], v[198:201], v[182:185], v[64:67]
	v_mfma_f32_16x16x32_bf16 v[128:131], v[194:197], v[148:151], v[128:131]
	v_mfma_f32_16x16x32_bf16 v[120:123], v[202:205], v[148:151], v[120:123]
	v_mfma_f32_16x16x32_bf16 v[108:111], v[194:197], v[170:173], v[108:111]
	v_mfma_f32_16x16x32_bf16 v[100:103], v[202:205], v[170:173], v[100:103]
	v_mfma_f32_16x16x32_bf16 v[88:91], v[194:197], v[178:181], v[88:91]
	v_mfma_f32_16x16x32_bf16 v[80:83], v[202:205], v[178:181], v[80:83]
	v_mfma_f32_16x16x32_bf16 v[72:75], v[194:197], v[186:189], v[72:75]
	v_mfma_f32_16x16x32_bf16 v[64:67], v[202:205], v[186:189], v[64:67]
	s_mov_b32 m0, s97
	v_lshl_add_u64 v[206:207], v[210:211], 0, s[42:43]
	s_barrier
	s_setprio 0
	ds_read_b128 v[144:147], v230 offset:49152
	ds_read_b128 v[148:151], v230 offset:50176
	ds_read_b128 v[152:155], v230 offset:51200
	ds_read_b128 v[170:173], v230 offset:52224
	ds_read_b128 v[174:177], v230 offset:53248
	ds_read_b128 v[178:181], v230 offset:54272
	ds_read_b128 v[182:185], v230 offset:55296
	ds_read_b128 v[186:189], v230 offset:56320
	global_load_lds_dwordx4 v[206:207], off
	v_lshl_add_u64 v[206:207], v[212:213], 0, s[42:43]
	s_mov_b32 m0, s18
	s_nop 0
	global_load_lds_dwordx4 v[206:207], off
	s_setprio 1
	s_barrier
	s_waitcnt lgkmcnt(0)
	v_mfma_f32_16x16x32_bf16 v[60:63], v[92:95], v[144:147], v[60:63]
	v_mfma_f32_16x16x32_bf16 v[52:55], v[132:135], v[144:147], v[52:55]
	v_mfma_f32_16x16x32_bf16 v[44:47], v[92:95], v[152:155], v[44:47]
	v_mfma_f32_16x16x32_bf16 v[36:39], v[132:135], v[152:155], v[36:39]
	v_mfma_f32_16x16x32_bf16 v[28:31], v[92:95], v[174:177], v[28:31]
	v_mfma_f32_16x16x32_bf16 v[20:23], v[132:135], v[174:177], v[20:23]
	v_mfma_f32_16x16x32_bf16 v[12:15], v[92:95], v[182:185], v[12:15]
	v_mfma_f32_16x16x32_bf16 v[4:7], v[132:135], v[182:185], v[4:7]
	v_mfma_f32_16x16x32_bf16 v[60:63], v[112:115], v[148:151], v[60:63]
	v_mfma_f32_16x16x32_bf16 v[52:55], v[140:143], v[148:151], v[52:55]
	v_mfma_f32_16x16x32_bf16 v[44:47], v[112:115], v[170:173], v[44:47]
	v_mfma_f32_16x16x32_bf16 v[36:39], v[140:143], v[170:173], v[36:39]
	v_mfma_f32_16x16x32_bf16 v[28:31], v[112:115], v[178:181], v[28:31]
	v_mfma_f32_16x16x32_bf16 v[20:23], v[140:143], v[178:181], v[20:23]
	v_mfma_f32_16x16x32_bf16 v[12:15], v[112:115], v[186:189], v[12:15]
	v_mfma_f32_16x16x32_bf16 v[4:7], v[140:143], v[186:189], v[4:7]
	s_barrier
	s_setprio 0
	s_add_u32 s6, s8, 0x10080
	s_addc_u32 s7, s9, 0
	s_add_i32 s8, s21, s92
	v_lshl_add_u64 v[92:93], s[6:7], 0, v[158:159]
	s_mov_b32 m0, s8
	s_nop 0
	global_load_lds_dwordx4 v[92:93], off
	v_lshl_add_u64 v[92:93], s[6:7], 0, v[162:163]
	s_add_i32 m0, s8, 0x2000
	s_nop 0
	global_load_lds_dwordx4 v[92:93], off
	s_waitcnt vmcnt(6)
	s_setprio 1
	s_barrier
	v_mfma_f32_16x16x32_bf16 v[56:59], v[190:193], v[144:147], v[56:59]
	v_mfma_f32_16x16x32_bf16 v[48:51], v[198:201], v[144:147], v[48:51]
	v_mfma_f32_16x16x32_bf16 v[40:43], v[190:193], v[152:155], v[40:43]
	v_mfma_f32_16x16x32_bf16 v[32:35], v[198:201], v[152:155], v[32:35]
	v_mfma_f32_16x16x32_bf16 v[24:27], v[190:193], v[174:177], v[24:27]
	v_mfma_f32_16x16x32_bf16 v[16:19], v[198:201], v[174:177], v[16:19]
	v_mfma_f32_16x16x32_bf16 v[8:11], v[190:193], v[182:185], v[8:11]
	v_mfma_f32_16x16x32_bf16 v[0:3], v[198:201], v[182:185], v[0:3]
	v_mfma_f32_16x16x32_bf16 v[56:59], v[194:197], v[148:151], v[56:59]
	v_mfma_f32_16x16x32_bf16 v[48:51], v[202:205], v[148:151], v[48:51]
	v_mfma_f32_16x16x32_bf16 v[40:43], v[194:197], v[170:173], v[40:43]
	v_mfma_f32_16x16x32_bf16 v[32:35], v[202:205], v[170:173], v[32:35]
	v_mfma_f32_16x16x32_bf16 v[24:27], v[194:197], v[178:181], v[24:27]
	v_mfma_f32_16x16x32_bf16 v[16:19], v[202:205], v[178:181], v[16:19]
	v_mfma_f32_16x16x32_bf16 v[8:11], v[194:197], v[186:189], v[8:11]
	v_mfma_f32_16x16x32_bf16 v[0:3], v[202:205], v[186:189], v[0:3]
	s_add_u32 s64, s64, 0x100
	s_addc_u32 s65, s65, 0
	s_cmp_lt_i32 s66, s95
	s_mov_b64 s[6:7], s[4:5]
	s_mov_b32 s8, s66
	s_barrier
	s_setprio 0
	s_cbranch_scc1 .LBB0_461

.Lpz_P8:
	s_and_b64 s[12:13], s[12:13], exec
	s_cselect_b32 s3, s61, s67
	s_cselect_b32 s15, s60, s66
	s_cselect_b32 s16, s63, s65
	s_cselect_b32 s17, s62, s64
	s_add_u32 s12, s66, 0x40080
	s_addc_u32 s13, s67, 0
	s_add_u32 s18, s64, 0x100
	s_addc_u32 s19, s65, 0
	s_mov_b32 s57, 0
	ds_read_b128 v[0:3], v233
	ds_read_b128 v[4:7], v233 offset:1024
	ds_read_b128 v[8:11], v233 offset:2048
	ds_read_b128 v[12:15], v233 offset:3072
	s_add_i32 s59, s57, 2
	s_add_u32 s20, s12, 0xfffc0080
	s_addc_u32 s21, s13, -1
	s_cmp_eq_u32 s97, s57
	s_cselect_b32 s67, s3, s21
	s_cselect_b32 s66, s15, s20
	s_cselect_b32 s65, s16, s19
	s_cselect_b32 s64, s17, s18
	v_lshl_add_u64 v[190:191], s[12:13], 0, v[164:165]
	s_add_i32 m0, s74, 0xc000
	ds_read_b128 v[80:83], v234
	ds_read_b128 v[84:87], v234 offset:1024
	ds_read_b128 v[88:91], v234 offset:2048
	ds_read_b128 v[92:95], v234 offset:3072
	ds_read_b128 v[174:177], v234 offset:4096
	ds_read_b128 v[178:181], v234 offset:5120
	ds_read_b128 v[182:185], v234 offset:6144
	ds_read_b128 v[186:189], v234 offset:7168
	global_load_lds_dwordx4 v[190:191], off
	v_lshl_add_u64 v[190:191], s[12:13], 0, v[166:167]
	s_add_i32 m0, s74, 0xe000
	s_nop 0
	global_load_lds_dwordx4 v[190:191], off
	s_waitcnt lgkmcnt(8)
	s_setprio 1
	s_barrier
	s_waitcnt lgkmcnt(0)
	v_mfma_f32_16x16x32_bf16 v[156:159], v[0:3], v[80:83], 0
	v_mfma_f32_16x16x32_bf16 v[152:155], v[8:11], v[80:83], 0
	v_mfma_f32_16x16x32_bf16 v[140:143], v[0:3], v[88:91], 0
	v_mfma_f32_16x16x32_bf16 v[136:139], v[8:11], v[88:91], 0
	v_mfma_f32_16x16x32_bf16 v[124:127], v[0:3], v[174:177], 0
	v_mfma_f32_16x16x32_bf16 v[120:123], v[8:11], v[174:177], 0
	v_mfma_f32_16x16x32_bf16 v[108:111], v[0:3], v[182:185], 0
	v_mfma_f32_16x16x32_bf16 v[104:107], v[8:11], v[182:185], 0
	v_mfma_f32_16x16x32_bf16 v[156:159], v[4:7], v[84:87], v[156:159]
	v_mfma_f32_16x16x32_bf16 v[152:155], v[12:15], v[84:87], v[152:155]
	v_mfma_f32_16x16x32_bf16 v[140:143], v[4:7], v[92:95], v[140:143]
	v_mfma_f32_16x16x32_bf16 v[136:139], v[12:15], v[92:95], v[136:139]
	v_mfma_f32_16x16x32_bf16 v[124:127], v[4:7], v[178:181], v[124:127]
	v_mfma_f32_16x16x32_bf16 v[120:123], v[12:15], v[178:181], v[120:123]
	v_mfma_f32_16x16x32_bf16 v[108:111], v[4:7], v[186:189], v[108:111]
	v_mfma_f32_16x16x32_bf16 v[104:107], v[12:15], v[186:189], v[104:107]
	s_barrier
	s_setprio 0
	s_add_i32 s20, s88, s73
	v_lshl_add_u64 v[214:215], s[64:65], 0, v[160:161]
	s_mov_b32 m0, s20
	ds_read_b128 v[190:193], v235
	ds_read_b128 v[194:197], v235 offset:1024
	ds_read_b128 v[198:201], v235 offset:2048
	ds_read_b128 v[202:205], v235 offset:3072
	global_load_lds_dwordx4 v[214:215], off
	v_lshl_add_u64 v[216:217], s[64:65], 0, v[162:163]
	s_add_i32 m0, s20, 0x2000
	s_nop 0
	global_load_lds_dwordx4 v[216:217], off
	s_setprio 1
	s_barrier
	s_waitcnt lgkmcnt(0)
	v_mfma_f32_16x16x32_bf16 v[148:151], v[190:193], v[80:83], 0
	v_mfma_f32_16x16x32_bf16 v[80:83], v[198:201], v[80:83], 0
	v_mfma_f32_16x16x32_bf16 v[148:151], v[194:197], v[84:87], v[148:151]
	v_mfma_f32_16x16x32_bf16 v[80:83], v[202:205], v[84:87], v[80:83]
	v_mfma_f32_16x16x32_bf16 v[84:87], v[190:193], v[88:91], 0
	v_mfma_f32_16x16x32_bf16 v[88:91], v[198:201], v[88:91], 0
	v_mfma_f32_16x16x32_bf16 v[112:115], v[198:201], v[174:177], 0
	v_mfma_f32_16x16x32_bf16 v[100:103], v[190:193], v[182:185], 0
	v_mfma_f32_16x16x32_bf16 v[96:99], v[198:201], v[182:185], 0
	v_mfma_f32_16x16x32_bf16 v[84:87], v[194:197], v[92:95], v[84:87]
	v_mfma_f32_16x16x32_bf16 v[88:91], v[202:205], v[92:95], v[88:91]
	v_mfma_f32_16x16x32_bf16 v[92:95], v[190:193], v[174:177], 0
	v_mfma_f32_16x16x32_bf16 v[112:115], v[202:205], v[178:181], v[112:115]
	v_mfma_f32_16x16x32_bf16 v[100:103], v[194:197], v[186:189], v[100:103]
	v_mfma_f32_16x16x32_bf16 v[96:99], v[202:205], v[186:189], v[96:99]
	v_mfma_f32_16x16x32_bf16 v[92:95], v[194:197], v[178:181], v[92:95]
	s_mov_b32 m0, s74
	v_lshl_add_u64 v[218:219], s[66:67], 0, v[160:161]
	s_barrier
	s_setprio 0
	ds_read_b128 v[116:119], v234 offset:16384
	ds_read_b128 v[128:131], v234 offset:17408
	ds_read_b128 v[132:135], v234 offset:18432
	ds_read_b128 v[144:147], v234 offset:19456
	ds_read_b128 v[174:177], v234 offset:20480
	ds_read_b128 v[178:181], v234 offset:21504
	ds_read_b128 v[182:185], v234 offset:22528
	ds_read_b128 v[186:189], v234 offset:23552
	global_load_lds_dwordx4 v[218:219], off
	v_lshl_add_u64 v[220:221], s[66:67], 0, v[162:163]
	s_mov_b32 m0, s75
	s_nop 0
	global_load_lds_dwordx4 v[220:221], off
	s_setprio 1
	s_barrier
	s_waitcnt lgkmcnt(0)
	v_mfma_f32_16x16x32_bf16 v[76:79], v[0:3], v[116:119], 0
	v_mfma_f32_16x16x32_bf16 v[72:75], v[8:11], v[116:119], 0
	v_mfma_f32_16x16x32_bf16 v[60:63], v[0:3], v[132:135], 0
	v_mfma_f32_16x16x32_bf16 v[56:59], v[8:11], v[132:135], 0
	v_mfma_f32_16x16x32_bf16 v[44:47], v[0:3], v[174:177], 0
	v_mfma_f32_16x16x32_bf16 v[40:43], v[8:11], v[174:177], 0
	v_mfma_f32_16x16x32_bf16 v[0:3], v[0:3], v[182:185], 0
	v_mfma_f32_16x16x32_bf16 v[76:79], v[4:7], v[128:131], v[76:79]
	v_mfma_f32_16x16x32_bf16 v[72:75], v[12:15], v[128:131], v[72:75]
	v_mfma_f32_16x16x32_bf16 v[60:63], v[4:7], v[144:147], v[60:63]
	v_mfma_f32_16x16x32_bf16 v[56:59], v[12:15], v[144:147], v[56:59]
	v_mfma_f32_16x16x32_bf16 v[44:47], v[4:7], v[178:181], v[44:47]
	v_mfma_f32_16x16x32_bf16 v[40:43], v[12:15], v[178:181], v[40:43]
	v_mfma_f32_16x16x32_bf16 v[0:3], v[4:7], v[186:189], v[0:3]
	v_mfma_f32_16x16x32_bf16 v[4:7], v[8:11], v[182:185], 0
	v_mfma_f32_16x16x32_bf16 v[4:7], v[12:15], v[186:189], v[4:7]
	s_barrier
	s_setprio 0
	s_add_u32 s20, s64, 0x40000
	s_addc_u32 s21, s65, 0
	s_add_i32 s57, s89, s73
	v_lshl_add_u64 v[8:9], s[20:21], 0, v[160:161]
	s_mov_b32 m0, s57
	s_nop 0
	global_load_lds_dwordx4 v[8:9], off
	v_lshl_add_u64 v[8:9], s[20:21], 0, v[162:163]
	s_add_i32 m0, s57, 0x2000
	s_nop 0
	global_load_lds_dwordx4 v[8:9], off
	s_waitcnt vmcnt(6)
	s_setprio 1
	s_barrier
	v_mfma_f32_16x16x32_bf16 v[24:27], v[190:193], v[132:135], 0
	v_mfma_f32_16x16x32_bf16 v[52:55], v[194:197], v[144:147], v[24:27]
	v_mfma_f32_16x16x32_bf16 v[24:27], v[198:201], v[132:135], 0
	v_mfma_f32_16x16x32_bf16 v[48:51], v[202:205], v[144:147], v[24:27]
	v_mfma_f32_16x16x32_bf16 v[24:27], v[190:193], v[174:177], 0
	v_mfma_f32_16x16x32_bf16 v[36:39], v[194:197], v[178:181], v[24:27]
	v_mfma_f32_16x16x32_bf16 v[24:27], v[198:201], v[174:177], 0
	v_mfma_f32_16x16x32_bf16 v[20:23], v[190:193], v[182:185], 0
	v_mfma_f32_16x16x32_bf16 v[16:19], v[198:201], v[182:185], 0
	v_mfma_f32_16x16x32_bf16 v[8:11], v[190:193], v[116:119], 0
	v_mfma_f32_16x16x32_bf16 v[12:15], v[198:201], v[116:119], 0
	v_mfma_f32_16x16x32_bf16 v[32:35], v[202:205], v[178:181], v[24:27]
	v_mfma_f32_16x16x32_bf16 v[20:23], v[194:197], v[186:189], v[20:23]
	v_mfma_f32_16x16x32_bf16 v[16:19], v[202:205], v[186:189], v[16:19]
	v_mfma_f32_16x16x32_bf16 v[8:11], v[194:197], v[128:131], v[8:11]
	v_mfma_f32_16x16x32_bf16 v[12:15], v[202:205], v[128:131], v[12:15]
	s_add_i32 s57, 0, 0x18000
	v_add_u32_e32 v68, s57, v228
	s_barrier
	s_setprio 0
	ds_read_b128 v[24:27], v68
	ds_read_b128 v[28:31], v68 offset:1024
	ds_read_b128 v[64:67], v68 offset:2048
	ds_read_b128 v[68:71], v68 offset:3072
	s_add_u32 s20, s66, 0x40000
	s_addc_u32 s21, s67, 0
	s_mov_b32 m0, s76
	v_lshl_add_u64 v[132:133], s[20:21], 0, v[160:161]
	ds_read_b128 v[116:119], v234 offset:32768
	ds_read_b128 v[128:131], v234 offset:33792
	ds_read_b128 v[174:177], v234 offset:34816
	ds_read_b128 v[178:181], v234 offset:35840
	ds_read_b128 v[182:185], v234 offset:36864
	ds_read_b128 v[186:189], v234 offset:37888
	ds_read_b128 v[190:193], v234 offset:38912
	ds_read_b128 v[194:197], v234 offset:39936
	global_load_lds_dwordx4 v[132:133], off
	v_lshl_add_u64 v[132:133], s[20:21], 0, v[162:163]
	s_mov_b32 m0, s77
	s_nop 0
	global_load_lds_dwordx4 v[132:133], off
	s_waitcnt lgkmcnt(8)
	s_setprio 1
	s_barrier
	s_waitcnt lgkmcnt(0)
	v_mfma_f32_16x16x32_bf16 v[132:135], v[24:27], v[116:119], v[156:159]
	v_mfma_f32_16x16x32_bf16 v[156:159], v[28:31], v[128:131], v[132:135]
	v_mfma_f32_16x16x32_bf16 v[132:135], v[64:67], v[116:119], v[152:155]
	v_mfma_f32_16x16x32_bf16 v[152:155], v[68:71], v[128:131], v[132:135]
	v_mfma_f32_16x16x32_bf16 v[132:135], v[24:27], v[174:177], v[140:143]
	v_mfma_f32_16x16x32_bf16 v[140:143], v[28:31], v[178:181], v[132:135]
	v_mfma_f32_16x16x32_bf16 v[132:135], v[64:67], v[174:177], v[136:139]
	v_mfma_f32_16x16x32_bf16 v[124:127], v[24:27], v[182:185], v[124:127]
	v_mfma_f32_16x16x32_bf16 v[120:123], v[64:67], v[182:185], v[120:123]
	v_mfma_f32_16x16x32_bf16 v[108:111], v[24:27], v[190:193], v[108:111]
	v_mfma_f32_16x16x32_bf16 v[104:107], v[64:67], v[190:193], v[104:107]
	v_mfma_f32_16x16x32_bf16 v[136:139], v[68:71], v[178:181], v[132:135]
	v_mfma_f32_16x16x32_bf16 v[124:127], v[28:31], v[186:189], v[124:127]
	v_mfma_f32_16x16x32_bf16 v[120:123], v[68:71], v[186:189], v[120:123]
	v_mfma_f32_16x16x32_bf16 v[108:111], v[28:31], v[194:197], v[108:111]
	v_mfma_f32_16x16x32_bf16 v[104:107], v[68:71], v[194:197], v[104:107]
	s_barrier
	s_setprio 0
	s_add_i32 s66, 0, 0x1c000
	v_add_u32_e32 v132, s66, v228
	s_add_i32 s20, s57, s73
	ds_read_b128 v[198:201], v132
	ds_read_b128 v[202:205], v132 offset:1024
	ds_read_b128 v[206:209], v132 offset:2048
	ds_read_b128 v[210:213], v132 offset:3072
	v_lshl_add_u64 v[132:133], v[214:215], 0, s[44:45]
	s_mov_b32 m0, s20
	s_nop 0
	global_load_lds_dwordx4 v[132:133], off
	v_lshl_add_u64 v[132:133], v[216:217], 0, s[44:45]
	s_add_i32 m0, s20, 0x2000
	s_nop 0
	global_load_lds_dwordx4 v[132:133], off
	s_setprio 1
	s_barrier
	s_waitcnt lgkmcnt(0)
	v_mfma_f32_16x16x32_bf16 v[80:83], v[206:209], v[116:119], v[80:83]
	v_mfma_f32_16x16x32_bf16 v[132:135], v[198:201], v[116:119], v[148:151]
	v_mfma_f32_16x16x32_bf16 v[144:147], v[210:213], v[128:131], v[80:83]
	v_mfma_f32_16x16x32_bf16 v[80:83], v[198:201], v[174:177], v[84:87]
	v_mfma_f32_16x16x32_bf16 v[148:151], v[202:205], v[128:131], v[132:135]
	v_mfma_f32_16x16x32_bf16 v[132:135], v[202:205], v[178:181], v[80:83]
	v_mfma_f32_16x16x32_bf16 v[80:83], v[206:209], v[174:177], v[88:91]
	v_mfma_f32_16x16x32_bf16 v[128:131], v[210:213], v[178:181], v[80:83]
	v_mfma_f32_16x16x32_bf16 v[80:83], v[198:201], v[182:185], v[92:95]
	v_mfma_f32_16x16x32_bf16 v[116:119], v[202:205], v[186:189], v[80:83]
	v_mfma_f32_16x16x32_bf16 v[80:83], v[206:209], v[182:185], v[112:115]
	v_mfma_f32_16x16x32_bf16 v[112:115], v[210:213], v[186:189], v[80:83]
	v_mfma_f32_16x16x32_bf16 v[80:83], v[198:201], v[190:193], v[100:103]
	v_mfma_f32_16x16x32_bf16 v[100:103], v[202:205], v[194:197], v[80:83]
	v_mfma_f32_16x16x32_bf16 v[80:83], v[206:209], v[190:193], v[96:99]
	v_mfma_f32_16x16x32_bf16 v[96:99], v[210:213], v[194:197], v[80:83]
	s_mov_b32 m0, s95
	v_lshl_add_u64 v[190:191], v[218:219], 0, s[44:45]
	s_barrier
	s_setprio 0
	s_nop 2
	ds_read_b128 v[80:83], v234 offset:49152
	ds_read_b128 v[84:87], v234 offset:50176
	ds_read_b128 v[88:91], v234 offset:51200
	ds_read_b128 v[92:95], v234 offset:52224
	ds_read_b128 v[174:177], v234 offset:53248
	ds_read_b128 v[178:181], v234 offset:54272
	ds_read_b128 v[182:185], v234 offset:55296
	ds_read_b128 v[186:189], v234 offset:56320
	global_load_lds_dwordx4 v[190:191], off
	v_lshl_add_u64 v[190:191], v[220:221], 0, s[44:45]
	s_mov_b32 m0, s96
	s_nop 0
	global_load_lds_dwordx4 v[190:191], off
	s_setprio 1
	s_barrier
	s_waitcnt lgkmcnt(0)
	v_mfma_f32_16x16x32_bf16 v[76:79], v[24:27], v[80:83], v[76:79]
	v_mfma_f32_16x16x32_bf16 v[60:63], v[24:27], v[88:91], v[60:63]
	v_mfma_f32_16x16x32_bf16 v[44:47], v[24:27], v[174:177], v[44:47]
	v_mfma_f32_16x16x32_bf16 v[0:3], v[24:27], v[182:185], v[0:3]
	v_mfma_f32_16x16x32_bf16 v[76:79], v[28:31], v[84:87], v[76:79]
	v_mfma_f32_16x16x32_bf16 v[72:75], v[64:67], v[80:83], v[72:75]
	v_mfma_f32_16x16x32_bf16 v[60:63], v[28:31], v[92:95], v[60:63]
	v_mfma_f32_16x16x32_bf16 v[56:59], v[64:67], v[88:91], v[56:59]
	v_mfma_f32_16x16x32_bf16 v[44:47], v[28:31], v[178:181], v[44:47]
	v_mfma_f32_16x16x32_bf16 v[40:43], v[64:67], v[174:177], v[40:43]
	v_mfma_f32_16x16x32_bf16 v[28:31], v[28:31], v[186:189], v[0:3]
	v_mfma_f32_16x16x32_bf16 v[0:3], v[64:67], v[182:185], v[4:7]
	v_mfma_f32_16x16x32_bf16 v[72:75], v[68:71], v[84:87], v[72:75]
	v_mfma_f32_16x16x32_bf16 v[56:59], v[68:71], v[92:95], v[56:59]
	v_mfma_f32_16x16x32_bf16 v[40:43], v[68:71], v[178:181], v[40:43]
	v_mfma_f32_16x16x32_bf16 v[24:27], v[68:71], v[186:189], v[0:3]
	s_barrier
	s_setprio 0
	s_add_u32 s20, s64, 0x40080
	s_addc_u32 s21, s65, 0
	s_add_i32 s57, s66, s73
	v_lshl_add_u64 v[0:1], s[20:21], 0, v[160:161]
	s_mov_b32 m0, s57
	s_nop 0
	global_load_lds_dwordx4 v[0:1], off
	v_lshl_add_u64 v[0:1], s[20:21], 0, v[162:163]
	s_add_i32 m0, s57, 0x2000
	s_nop 0
	global_load_lds_dwordx4 v[0:1], off
	s_waitcnt vmcnt(6)
	s_setprio 1
	s_barrier
	v_mfma_f32_16x16x32_bf16 v[0:3], v[198:201], v[80:83], v[8:11]
	v_mfma_f32_16x16x32_bf16 v[68:71], v[202:205], v[84:87], v[0:3]
	v_mfma_f32_16x16x32_bf16 v[0:3], v[206:209], v[80:83], v[12:15]
	v_mfma_f32_16x16x32_bf16 v[64:67], v[210:213], v[84:87], v[0:3]
	v_mfma_f32_16x16x32_bf16 v[0:3], v[198:201], v[88:91], v[52:55]
	v_mfma_f32_16x16x32_bf16 v[52:55], v[202:205], v[92:95], v[0:3]
	v_mfma_f32_16x16x32_bf16 v[0:3], v[206:209], v[88:91], v[48:51]
	v_mfma_f32_16x16x32_bf16 v[48:51], v[210:213], v[92:95], v[0:3]
	v_mfma_f32_16x16x32_bf16 v[0:3], v[198:201], v[174:177], v[36:39]
	v_mfma_f32_16x16x32_bf16 v[36:39], v[202:205], v[178:181], v[0:3]
	v_mfma_f32_16x16x32_bf16 v[0:3], v[206:209], v[174:177], v[32:35]
	v_mfma_f32_16x16x32_bf16 v[32:35], v[210:213], v[178:181], v[0:3]
	v_mfma_f32_16x16x32_bf16 v[0:3], v[198:201], v[182:185], v[20:23]
	v_mfma_f32_16x16x32_bf16 v[20:23], v[202:205], v[186:189], v[0:3]
	v_mfma_f32_16x16x32_bf16 v[0:3], v[206:209], v[182:185], v[16:19]
	v_mfma_f32_16x16x32_bf16 v[16:19], v[210:213], v[186:189], v[0:3]
	s_add_u32 s12, s12, 0x100
	s_addc_u32 s13, s13, 0
	s_add_u32 s18, s18, 0x100
	s_addc_u32 s19, s19, 0
	s_cmp_lt_i32 s59, s93
	s_mov_b32 s57, s59
	s_barrier
	s_setprio 0
	s_cbranch_scc0 .Lpeel_done_P8
.LBB0_605:
	ds_read_b128 v[0:3], v233
	ds_read_b128 v[4:7], v233 offset:1024
	ds_read_b128 v[8:11], v233 offset:2048
	ds_read_b128 v[12:15], v233 offset:3072
	s_add_i32 s59, s57, 2
	s_add_u32 s20, s12, 0xfffc0080
	s_addc_u32 s21, s13, -1
	s_cmp_eq_u32 s97, s57
	s_cselect_b32 s67, s3, s21
	s_cselect_b32 s66, s15, s20
	s_cselect_b32 s65, s16, s19
	s_cselect_b32 s64, s17, s18
	v_lshl_add_u64 v[190:191], s[12:13], 0, v[164:165]
	s_add_i32 m0, s74, 0xc000
	ds_read_b128 v[80:83], v234
	ds_read_b128 v[84:87], v234 offset:1024
	ds_read_b128 v[88:91], v234 offset:2048
	ds_read_b128 v[92:95], v234 offset:3072
	ds_read_b128 v[174:177], v234 offset:4096
	ds_read_b128 v[178:181], v234 offset:5120
	ds_read_b128 v[182:185], v234 offset:6144
	ds_read_b128 v[186:189], v234 offset:7168
	global_load_lds_dwordx4 v[190:191], off
	v_lshl_add_u64 v[190:191], s[12:13], 0, v[166:167]
	s_add_i32 m0, s74, 0xe000
	s_nop 0
	global_load_lds_dwordx4 v[190:191], off
	s_waitcnt lgkmcnt(8)
	s_setprio 1
	s_barrier
	s_waitcnt lgkmcnt(0)
	v_mfma_f32_16x16x32_bf16 v[156:159], v[0:3], v[80:83], v[156:159]
	v_mfma_f32_16x16x32_bf16 v[152:155], v[8:11], v[80:83], v[152:155]
	v_mfma_f32_16x16x32_bf16 v[140:143], v[0:3], v[88:91], v[140:143]
	v_mfma_f32_16x16x32_bf16 v[136:139], v[8:11], v[88:91], v[136:139]
	v_mfma_f32_16x16x32_bf16 v[124:127], v[0:3], v[174:177], v[124:127]
	v_mfma_f32_16x16x32_bf16 v[120:123], v[8:11], v[174:177], v[120:123]
	v_mfma_f32_16x16x32_bf16 v[108:111], v[0:3], v[182:185], v[108:111]
	v_mfma_f32_16x16x32_bf16 v[104:107], v[8:11], v[182:185], v[104:107]
	v_mfma_f32_16x16x32_bf16 v[156:159], v[4:7], v[84:87], v[156:159]
	v_mfma_f32_16x16x32_bf16 v[152:155], v[12:15], v[84:87], v[152:155]
	v_mfma_f32_16x16x32_bf16 v[140:143], v[4:7], v[92:95], v[140:143]
	v_mfma_f32_16x16x32_bf16 v[136:139], v[12:15], v[92:95], v[136:139]
	v_mfma_f32_16x16x32_bf16 v[124:127], v[4:7], v[178:181], v[124:127]
	v_mfma_f32_16x16x32_bf16 v[120:123], v[12:15], v[178:181], v[120:123]
	v_mfma_f32_16x16x32_bf16 v[108:111], v[4:7], v[186:189], v[108:111]
	v_mfma_f32_16x16x32_bf16 v[104:107], v[12:15], v[186:189], v[104:107]
	s_barrier
	s_setprio 0
	s_add_i32 s20, s88, s73
	v_lshl_add_u64 v[214:215], s[64:65], 0, v[160:161]
	s_mov_b32 m0, s20
	ds_read_b128 v[190:193], v235
	ds_read_b128 v[194:197], v235 offset:1024
	ds_read_b128 v[198:201], v235 offset:2048
	ds_read_b128 v[202:205], v235 offset:3072
	global_load_lds_dwordx4 v[214:215], off
	v_lshl_add_u64 v[216:217], s[64:65], 0, v[162:163]
	s_add_i32 m0, s20, 0x2000
	s_nop 0
	global_load_lds_dwordx4 v[216:217], off
	s_setprio 1
	s_barrier
	s_waitcnt lgkmcnt(0)
	v_mfma_f32_16x16x32_bf16 v[148:151], v[190:193], v[80:83], v[148:151]
	v_mfma_f32_16x16x32_bf16 v[80:83], v[198:201], v[80:83], v[144:147]
	v_mfma_f32_16x16x32_bf16 v[148:151], v[194:197], v[84:87], v[148:151]
	v_mfma_f32_16x16x32_bf16 v[80:83], v[202:205], v[84:87], v[80:83]
	v_mfma_f32_16x16x32_bf16 v[84:87], v[190:193], v[88:91], v[132:135]
	v_mfma_f32_16x16x32_bf16 v[88:91], v[198:201], v[88:91], v[128:131]
	v_mfma_f32_16x16x32_bf16 v[112:115], v[198:201], v[174:177], v[112:115]
	v_mfma_f32_16x16x32_bf16 v[100:103], v[190:193], v[182:185], v[100:103]
	v_mfma_f32_16x16x32_bf16 v[96:99], v[198:201], v[182:185], v[96:99]
	v_mfma_f32_16x16x32_bf16 v[84:87], v[194:197], v[92:95], v[84:87]
	v_mfma_f32_16x16x32_bf16 v[88:91], v[202:205], v[92:95], v[88:91]
	v_mfma_f32_16x16x32_bf16 v[92:95], v[190:193], v[174:177], v[116:119]
	v_mfma_f32_16x16x32_bf16 v[112:115], v[202:205], v[178:181], v[112:115]
	v_mfma_f32_16x16x32_bf16 v[100:103], v[194:197], v[186:189], v[100:103]
	v_mfma_f32_16x16x32_bf16 v[96:99], v[202:205], v[186:189], v[96:99]
	v_mfma_f32_16x16x32_bf16 v[92:95], v[194:197], v[178:181], v[92:95]
	s_mov_b32 m0, s74
	v_lshl_add_u64 v[218:219], s[66:67], 0, v[160:161]
	s_barrier
	s_setprio 0
	ds_read_b128 v[116:119], v234 offset:16384
	ds_read_b128 v[128:131], v234 offset:17408
	ds_read_b128 v[132:135], v234 offset:18432
	ds_read_b128 v[144:147], v234 offset:19456
	ds_read_b128 v[174:177], v234 offset:20480
	ds_read_b128 v[178:181], v234 offset:21504
	ds_read_b128 v[182:185], v234 offset:22528
	ds_read_b128 v[186:189], v234 offset:23552
	global_load_lds_dwordx4 v[218:219], off
	v_lshl_add_u64 v[220:221], s[66:67], 0, v[162:163]
	s_mov_b32 m0, s75
	s_nop 0
	global_load_lds_dwordx4 v[220:221], off
	s_setprio 1
	s_barrier
	s_waitcnt lgkmcnt(0)
	v_mfma_f32_16x16x32_bf16 v[76:79], v[0:3], v[116:119], v[76:79]
	v_mfma_f32_16x16x32_bf16 v[72:75], v[8:11], v[116:119], v[72:75]
	v_mfma_f32_16x16x32_bf16 v[60:63], v[0:3], v[132:135], v[60:63]
	v_mfma_f32_16x16x32_bf16 v[56:59], v[8:11], v[132:135], v[56:59]
	v_mfma_f32_16x16x32_bf16 v[44:47], v[0:3], v[174:177], v[44:47]
	v_mfma_f32_16x16x32_bf16 v[40:43], v[8:11], v[174:177], v[40:43]
	v_mfma_f32_16x16x32_bf16 v[0:3], v[0:3], v[182:185], v[28:31]
	v_mfma_f32_16x16x32_bf16 v[76:79], v[4:7], v[128:131], v[76:79]
	v_mfma_f32_16x16x32_bf16 v[72:75], v[12:15], v[128:131], v[72:75]
	v_mfma_f32_16x16x32_bf16 v[60:63], v[4:7], v[144:147], v[60:63]
	v_mfma_f32_16x16x32_bf16 v[56:59], v[12:15], v[144:147], v[56:59]
	v_mfma_f32_16x16x32_bf16 v[44:47], v[4:7], v[178:181], v[44:47]
	v_mfma_f32_16x16x32_bf16 v[40:43], v[12:15], v[178:181], v[40:43]
	v_mfma_f32_16x16x32_bf16 v[0:3], v[4:7], v[186:189], v[0:3]
	v_mfma_f32_16x16x32_bf16 v[4:7], v[8:11], v[182:185], v[24:27]
	v_mfma_f32_16x16x32_bf16 v[4:7], v[12:15], v[186:189], v[4:7]
	s_barrier
	s_setprio 0
	s_add_u32 s20, s64, 0x40000
	s_addc_u32 s21, s65, 0
	s_add_i32 s57, s89, s73
	v_lshl_add_u64 v[8:9], s[20:21], 0, v[160:161]
	s_mov_b32 m0, s57
	s_nop 0
	global_load_lds_dwordx4 v[8:9], off
	v_lshl_add_u64 v[8:9], s[20:21], 0, v[162:163]
	s_add_i32 m0, s57, 0x2000
	s_nop 0
	global_load_lds_dwordx4 v[8:9], off
	s_waitcnt vmcnt(6)
	s_setprio 1
	s_barrier
	v_mfma_f32_16x16x32_bf16 v[24:27], v[190:193], v[132:135], v[52:55]
	v_mfma_f32_16x16x32_bf16 v[52:55], v[194:197], v[144:147], v[24:27]
	v_mfma_f32_16x16x32_bf16 v[24:27], v[198:201], v[132:135], v[48:51]
	v_mfma_f32_16x16x32_bf16 v[48:51], v[202:205], v[144:147], v[24:27]
	v_mfma_f32_16x16x32_bf16 v[24:27], v[190:193], v[174:177], v[36:39]
	v_mfma_f32_16x16x32_bf16 v[36:39], v[194:197], v[178:181], v[24:27]
	v_mfma_f32_16x16x32_bf16 v[24:27], v[198:201], v[174:177], v[32:35]
	v_mfma_f32_16x16x32_bf16 v[20:23], v[190:193], v[182:185], v[20:23]
	v_mfma_f32_16x16x32_bf16 v[16:19], v[198:201], v[182:185], v[16:19]
	v_mfma_f32_16x16x32_bf16 v[8:11], v[190:193], v[116:119], v[68:71]
	v_mfma_f32_16x16x32_bf16 v[12:15], v[198:201], v[116:119], v[64:67]
	v_mfma_f32_16x16x32_bf16 v[32:35], v[202:205], v[178:181], v[24:27]
	v_mfma_f32_16x16x32_bf16 v[20:23], v[194:197], v[186:189], v[20:23]
	v_mfma_f32_16x16x32_bf16 v[16:19], v[202:205], v[186:189], v[16:19]
	v_mfma_f32_16x16x32_bf16 v[8:11], v[194:197], v[128:131], v[8:11]
	v_mfma_f32_16x16x32_bf16 v[12:15], v[202:205], v[128:131], v[12:15]
	s_add_i32 s57, 0, 0x18000
	v_add_u32_e32 v68, s57, v228
	s_barrier
	s_setprio 0
	ds_read_b128 v[24:27], v68
	ds_read_b128 v[28:31], v68 offset:1024
	ds_read_b128 v[64:67], v68 offset:2048
	ds_read_b128 v[68:71], v68 offset:3072
	s_add_u32 s20, s66, 0x40000
	s_addc_u32 s21, s67, 0
	s_mov_b32 m0, s76
	v_lshl_add_u64 v[132:133], s[20:21], 0, v[160:161]
	ds_read_b128 v[116:119], v234 offset:32768
	ds_read_b128 v[128:131], v234 offset:33792
	ds_read_b128 v[174:177], v234 offset:34816
	ds_read_b128 v[178:181], v234 offset:35840
	ds_read_b128 v[182:185], v234 offset:36864
	ds_read_b128 v[186:189], v234 offset:37888
	ds_read_b128 v[190:193], v234 offset:38912
	ds_read_b128 v[194:197], v234 offset:39936
	global_load_lds_dwordx4 v[132:133], off
	v_lshl_add_u64 v[132:133], s[20:21], 0, v[162:163]
	s_mov_b32 m0, s77
	s_nop 0
	global_load_lds_dwordx4 v[132:133], off
	s_waitcnt lgkmcnt(8)
	s_setprio 1
	s_barrier
	s_waitcnt lgkmcnt(0)
	v_mfma_f32_16x16x32_bf16 v[132:135], v[24:27], v[116:119], v[156:159]
	v_mfma_f32_16x16x32_bf16 v[156:159], v[28:31], v[128:131], v[132:135]
	v_mfma_f32_16x16x32_bf16 v[132:135], v[64:67], v[116:119], v[152:155]
	v_mfma_f32_16x16x32_bf16 v[152:155], v[68:71], v[128:131], v[132:135]
	v_mfma_f32_16x16x32_bf16 v[132:135], v[24:27], v[174:177], v[140:143]
	v_mfma_f32_16x16x32_bf16 v[140:143], v[28:31], v[178:181], v[132:135]
	v_mfma_f32_16x16x32_bf16 v[132:135], v[64:67], v[174:177], v[136:139]
	v_mfma_f32_16x16x32_bf16 v[124:127], v[24:27], v[182:185], v[124:127]
	v_mfma_f32_16x16x32_bf16 v[120:123], v[64:67], v[182:185], v[120:123]
	v_mfma_f32_16x16x32_bf16 v[108:111], v[24:27], v[190:193], v[108:111]
	v_mfma_f32_16x16x32_bf16 v[104:107], v[64:67], v[190:193], v[104:107]
	v_mfma_f32_16x16x32_bf16 v[136:139], v[68:71], v[178:181], v[132:135]
	v_mfma_f32_16x16x32_bf16 v[124:127], v[28:31], v[186:189], v[124:127]
	v_mfma_f32_16x16x32_bf16 v[120:123], v[68:71], v[186:189], v[120:123]
	v_mfma_f32_16x16x32_bf16 v[108:111], v[28:31], v[194:197], v[108:111]
	v_mfma_f32_16x16x32_bf16 v[104:107], v[68:71], v[194:197], v[104:107]
	s_barrier
	s_setprio 0
	s_add_i32 s66, 0, 0x1c000
	v_add_u32_e32 v132, s66, v228
	s_add_i32 s20, s57, s73
	ds_read_b128 v[198:201], v132
	ds_read_b128 v[202:205], v132 offset:1024
	ds_read_b128 v[206:209], v132 offset:2048
	ds_read_b128 v[210:213], v132 offset:3072
	v_lshl_add_u64 v[132:133], v[214:215], 0, s[44:45]
	s_mov_b32 m0, s20
	s_nop 0
	global_load_lds_dwordx4 v[132:133], off
	v_lshl_add_u64 v[132:133], v[216:217], 0, s[44:45]
	s_add_i32 m0, s20, 0x2000
	s_nop 0
	global_load_lds_dwordx4 v[132:133], off
	s_setprio 1
	s_barrier
	s_waitcnt lgkmcnt(0)
	v_mfma_f32_16x16x32_bf16 v[80:83], v[206:209], v[116:119], v[80:83]
	v_mfma_f32_16x16x32_bf16 v[132:135], v[198:201], v[116:119], v[148:151]
	v_mfma_f32_16x16x32_bf16 v[144:147], v[210:213], v[128:131], v[80:83]
	v_mfma_f32_16x16x32_bf16 v[80:83], v[198:201], v[174:177], v[84:87]
	v_mfma_f32_16x16x32_bf16 v[148:151], v[202:205], v[128:131], v[132:135]
	v_mfma_f32_16x16x32_bf16 v[132:135], v[202:205], v[178:181], v[80:83]
	v_mfma_f32_16x16x32_bf16 v[80:83], v[206:209], v[174:177], v[88:91]
	v_mfma_f32_16x16x32_bf16 v[128:131], v[210:213], v[178:181], v[80:83]
	v_mfma_f32_16x16x32_bf16 v[80:83], v[198:201], v[182:185], v[92:95]
	v_mfma_f32_16x16x32_bf16 v[116:119], v[202:205], v[186:189], v[80:83]
	v_mfma_f32_16x16x32_bf16 v[80:83], v[206:209], v[182:185], v[112:115]
	v_mfma_f32_16x16x32_bf16 v[112:115], v[210:213], v[186:189], v[80:83]
	v_mfma_f32_16x16x32_bf16 v[80:83], v[198:201], v[190:193], v[100:103]
	v_mfma_f32_16x16x32_bf16 v[100:103], v[202:205], v[194:197], v[80:83]
	v_mfma_f32_16x16x32_bf16 v[80:83], v[206:209], v[190:193], v[96:99]
	v_mfma_f32_16x16x32_bf16 v[96:99], v[210:213], v[194:197], v[80:83]
	s_mov_b32 m0, s95
	v_lshl_add_u64 v[190:191], v[218:219], 0, s[44:45]
	s_barrier
	s_setprio 0
	s_nop 2
	ds_read_b128 v[80:83], v234 offset:49152
	ds_read_b128 v[84:87], v234 offset:50176
	ds_read_b128 v[88:91], v234 offset:51200
	ds_read_b128 v[92:95], v234 offset:52224
	ds_read_b128 v[174:177], v234 offset:53248
	ds_read_b128 v[178:181], v234 offset:54272
	ds_read_b128 v[182:185], v234 offset:55296
	ds_read_b128 v[186:189], v234 offset:56320
	global_load_lds_dwordx4 v[190:191], off
	v_lshl_add_u64 v[190:191], v[220:221], 0, s[44:45]
	s_mov_b32 m0, s96
	s_nop 0
	global_load_lds_dwordx4 v[190:191], off
	s_setprio 1
	s_barrier
	s_waitcnt lgkmcnt(0)
	v_mfma_f32_16x16x32_bf16 v[76:79], v[24:27], v[80:83], v[76:79]
	v_mfma_f32_16x16x32_bf16 v[60:63], v[24:27], v[88:91], v[60:63]
	v_mfma_f32_16x16x32_bf16 v[44:47], v[24:27], v[174:177], v[44:47]
	v_mfma_f32_16x16x32_bf16 v[0:3], v[24:27], v[182:185], v[0:3]
	v_mfma_f32_16x16x32_bf16 v[76:79], v[28:31], v[84:87], v[76:79]
	v_mfma_f32_16x16x32_bf16 v[72:75], v[64:67], v[80:83], v[72:75]
	v_mfma_f32_16x16x32_bf16 v[60:63], v[28:31], v[92:95], v[60:63]
	v_mfma_f32_16x16x32_bf16 v[56:59], v[64:67], v[88:91], v[56:59]
	v_mfma_f32_16x16x32_bf16 v[44:47], v[28:31], v[178:181], v[44:47]
	v_mfma_f32_16x16x32_bf16 v[40:43], v[64:67], v[174:177], v[40:43]
	v_mfma_f32_16x16x32_bf16 v[28:31], v[28:31], v[186:189], v[0:3]
	v_mfma_f32_16x16x32_bf16 v[0:3], v[64:67], v[182:185], v[4:7]
	v_mfma_f32_16x16x32_bf16 v[72:75], v[68:71], v[84:87], v[72:75]
	v_mfma_f32_16x16x32_bf16 v[56:59], v[68:71], v[92:95], v[56:59]
	v_mfma_f32_16x16x32_bf16 v[40:43], v[68:71], v[178:181], v[40:43]
	v_mfma_f32_16x16x32_bf16 v[24:27], v[68:71], v[186:189], v[0:3]
	s_barrier
	s_setprio 0
	s_add_u32 s20, s64, 0x40080
	s_addc_u32 s21, s65, 0
	s_add_i32 s57, s66, s73
	v_lshl_add_u64 v[0:1], s[20:21], 0, v[160:161]
	s_mov_b32 m0, s57
	s_nop 0
	global_load_lds_dwordx4 v[0:1], off
	v_lshl_add_u64 v[0:1], s[20:21], 0, v[162:163]
	s_add_i32 m0, s57, 0x2000
	s_nop 0
	global_load_lds_dwordx4 v[0:1], off
	s_waitcnt vmcnt(6)
	s_setprio 1
	s_barrier
	v_mfma_f32_16x16x32_bf16 v[0:3], v[198:201], v[80:83], v[8:11]
	v_mfma_f32_16x16x32_bf16 v[68:71], v[202:205], v[84:87], v[0:3]
	v_mfma_f32_16x16x32_bf16 v[0:3], v[206:209], v[80:83], v[12:15]
	v_mfma_f32_16x16x32_bf16 v[64:67], v[210:213], v[84:87], v[0:3]
	v_mfma_f32_16x16x32_bf16 v[0:3], v[198:201], v[88:91], v[52:55]
	v_mfma_f32_16x16x32_bf16 v[52:55], v[202:205], v[92:95], v[0:3]
	v_mfma_f32_16x16x32_bf16 v[0:3], v[206:209], v[88:91], v[48:51]
	v_mfma_f32_16x16x32_bf16 v[48:51], v[210:213], v[92:95], v[0:3]
	v_mfma_f32_16x16x32_bf16 v[0:3], v[198:201], v[174:177], v[36:39]
	v_mfma_f32_16x16x32_bf16 v[36:39], v[202:205], v[178:181], v[0:3]
	v_mfma_f32_16x16x32_bf16 v[0:3], v[206:209], v[174:177], v[32:35]
	v_mfma_f32_16x16x32_bf16 v[32:35], v[210:213], v[178:181], v[0:3]
	v_mfma_f32_16x16x32_bf16 v[0:3], v[198:201], v[182:185], v[20:23]
	v_mfma_f32_16x16x32_bf16 v[20:23], v[202:205], v[186:189], v[0:3]
	v_mfma_f32_16x16x32_bf16 v[0:3], v[206:209], v[182:185], v[16:19]
	v_mfma_f32_16x16x32_bf16 v[16:19], v[210:213], v[186:189], v[0:3]
	s_add_u32 s12, s12, 0x100
	s_addc_u32 s13, s13, 0
	s_add_u32 s18, s18, 0x100
	s_addc_u32 s19, s19, 0
	s_cmp_lt_i32 s59, s93
	s_mov_b32 s57, s59
	s_barrier
	s_setprio 0
	s_cbranch_scc1 .LBB0_605

.Lzskip_P10:
	v_cmp_lt_i64_e32 vcc, s[46:47], v[136:137]
	s_and_b64 s[20:21], vcc, exec
	s_cselect_b32 s31, s37, s43
	s_cselect_b32 s35, s36, s42
	s_cselect_b32 s58, s39, s45
	s_cselect_b32 s59, s38, s44
	s_add_u32 s42, s42, 0x20080
	s_addc_u32 s43, s43, 0
	s_add_u32 s60, s44, 0x100
	s_addc_u32 s61, s45, 0
	s_mov_b32 s44, 0
	v_add_u32_e32 v152, s88, v167
	ds_read_b128 v[140:143], v152
	ds_read_b128 v[144:147], v152 offset:1024
	ds_read_b128 v[148:151], v152 offset:2048
	ds_read_b128 v[152:155], v152 offset:3072
	s_add_i32 s62, s44, 2
	s_add_u32 s20, s42, 0xfffe0080
	s_addc_u32 s21, s43, -1
	s_cmp_eq_u32 s55, s44
	s_cselect_b32 s44, s59, s60
	s_cselect_b32 s47, s31, s21
	s_cselect_b32 s46, s35, s20
	s_cselect_b32 s45, s58, s61
	v_lshl_add_u64 v[198:199], s[42:43], 0, v[132:133]
	s_add_i32 m0, s41, 0xc000
	ds_read_b128 v[156:159], v172
	ds_read_b128 v[160:163], v172 offset:1024
	ds_read_b128 v[174:177], v172 offset:2048
	ds_read_b128 v[178:181], v172 offset:3072
	ds_read_b128 v[182:185], v172 offset:4096
	ds_read_b128 v[186:189], v172 offset:5120
	ds_read_b128 v[190:193], v172 offset:6144
	ds_read_b128 v[194:197], v172 offset:7168
	global_load_lds_dwordx4 v[198:199], off
	v_lshl_add_u64 v[198:199], s[42:43], 0, v[134:135]
	s_add_i32 m0, s41, 0xe000
	s_nop 0
	global_load_lds_dwordx4 v[198:199], off
	s_waitcnt lgkmcnt(8)
	s_setprio 1
	s_barrier
	s_waitcnt lgkmcnt(0)
	v_mfma_i32_16x16x64_i8 v[124:127], v[140:143], v[156:159], 0
	v_mfma_i32_16x16x64_i8 v[120:123], v[148:151], v[156:159], 0
	v_mfma_i32_16x16x64_i8 v[116:119], v[140:143], v[174:177], 0
	v_mfma_i32_16x16x64_i8 v[112:115], v[148:151], v[174:177], 0
	v_mfma_i32_16x16x64_i8 v[108:111], v[140:143], v[182:185], 0
	v_mfma_i32_16x16x64_i8 v[104:107], v[148:151], v[182:185], 0
	v_mfma_i32_16x16x64_i8 v[100:103], v[140:143], v[190:193], 0
	v_mfma_i32_16x16x64_i8 v[96:99], v[148:151], v[190:193], 0
	v_mfma_i32_16x16x64_i8 v[124:127], v[144:147], v[160:163], v[124:127]
	v_mfma_i32_16x16x64_i8 v[120:123], v[152:155], v[160:163], v[120:123]
	v_mfma_i32_16x16x64_i8 v[116:119], v[144:147], v[178:181], v[116:119]
	v_mfma_i32_16x16x64_i8 v[112:115], v[152:155], v[178:181], v[112:115]
	v_mfma_i32_16x16x64_i8 v[108:111], v[144:147], v[186:189], v[108:111]
	v_mfma_i32_16x16x64_i8 v[104:107], v[152:155], v[186:189], v[104:107]
	v_mfma_i32_16x16x64_i8 v[100:103], v[144:147], v[194:197], v[100:103]
	v_mfma_i32_16x16x64_i8 v[96:99], v[152:155], v[194:197], v[96:99]
	s_barrier
	s_setprio 0
	s_add_i32 s20, s88, s18
	v_add_u32_e32 v164, s89, v167
	v_lshl_add_u64 v[214:215], s[44:45], 0, v[130:131]
	s_mov_b32 m0, s20
	ds_read_b128 v[198:201], v164
	ds_read_b128 v[202:205], v164 offset:1024
	ds_read_b128 v[206:209], v164 offset:2048
	ds_read_b128 v[210:213], v164 offset:3072
	global_load_lds_dwordx4 v[214:215], off
	v_lshl_add_u64 v[216:217], s[44:45], 0, v[128:129]
	s_add_i32 m0, s20, 0x2000
	s_nop 0
	global_load_lds_dwordx4 v[216:217], off
	s_setprio 1
	s_barrier
	s_waitcnt lgkmcnt(0)
	v_mfma_i32_16x16x64_i8 v[92:95], v[198:201], v[156:159], 0
	v_mfma_i32_16x16x64_i8 v[88:91], v[206:209], v[156:159], 0
	v_mfma_i32_16x16x64_i8 v[84:87], v[198:201], v[174:177], 0
	v_mfma_i32_16x16x64_i8 v[80:83], v[206:209], v[174:177], 0
	v_mfma_i32_16x16x64_i8 v[76:79], v[198:201], v[182:185], 0
	v_mfma_i32_16x16x64_i8 v[72:75], v[206:209], v[182:185], 0
	v_mfma_i32_16x16x64_i8 v[68:71], v[198:201], v[190:193], 0
	v_mfma_i32_16x16x64_i8 v[64:67], v[206:209], v[190:193], 0
	v_mfma_i32_16x16x64_i8 v[92:95], v[202:205], v[160:163], v[92:95]
	v_mfma_i32_16x16x64_i8 v[88:91], v[210:213], v[160:163], v[88:91]
	v_mfma_i32_16x16x64_i8 v[84:87], v[202:205], v[178:181], v[84:87]
	v_mfma_i32_16x16x64_i8 v[80:83], v[210:213], v[178:181], v[80:83]
	v_mfma_i32_16x16x64_i8 v[76:79], v[202:205], v[186:189], v[76:79]
	v_mfma_i32_16x16x64_i8 v[72:75], v[210:213], v[186:189], v[72:75]
	v_mfma_i32_16x16x64_i8 v[68:71], v[202:205], v[194:197], v[68:71]
	v_mfma_i32_16x16x64_i8 v[64:67], v[210:213], v[194:197], v[64:67]
	s_mov_b32 m0, s41
	v_lshl_add_u64 v[218:219], s[46:47], 0, v[130:131]
	s_barrier
	s_setprio 0
	ds_read_b128 v[156:159], v172 offset:16384
	ds_read_b128 v[160:163], v172 offset:17408
	ds_read_b128 v[174:177], v172 offset:18432
	ds_read_b128 v[178:181], v172 offset:19456
	ds_read_b128 v[182:185], v172 offset:20480
	ds_read_b128 v[186:189], v172 offset:21504
	ds_read_b128 v[190:193], v172 offset:22528
	ds_read_b128 v[194:197], v172 offset:23552
	global_load_lds_dwordx4 v[218:219], off
	v_lshl_add_u64 v[220:221], s[46:47], 0, v[128:129]
	s_mov_b32 m0, s48
	s_nop 0
	global_load_lds_dwordx4 v[220:221], off
	s_setprio 1
	s_barrier
	s_waitcnt lgkmcnt(0)
	v_mfma_i32_16x16x64_i8 v[60:63], v[140:143], v[156:159], 0
	v_mfma_i32_16x16x64_i8 v[56:59], v[148:151], v[156:159], 0
	v_mfma_i32_16x16x64_i8 v[52:55], v[140:143], v[174:177], 0
	v_mfma_i32_16x16x64_i8 v[48:51], v[148:151], v[174:177], 0
	v_mfma_i32_16x16x64_i8 v[44:47], v[140:143], v[182:185], 0
	v_mfma_i32_16x16x64_i8 v[40:43], v[148:151], v[182:185], 0
	v_mfma_i32_16x16x64_i8 v[36:39], v[140:143], v[190:193], 0
	v_mfma_i32_16x16x64_i8 v[32:35], v[148:151], v[190:193], 0
	v_mfma_i32_16x16x64_i8 v[60:63], v[144:147], v[160:163], v[60:63]
	v_mfma_i32_16x16x64_i8 v[56:59], v[152:155], v[160:163], v[56:59]
	v_mfma_i32_16x16x64_i8 v[52:55], v[144:147], v[178:181], v[52:55]
	v_mfma_i32_16x16x64_i8 v[48:51], v[152:155], v[178:181], v[48:51]
	v_mfma_i32_16x16x64_i8 v[44:47], v[144:147], v[186:189], v[44:47]
	v_mfma_i32_16x16x64_i8 v[40:43], v[152:155], v[186:189], v[40:43]
	v_mfma_i32_16x16x64_i8 v[36:39], v[144:147], v[194:197], v[36:39]
	v_mfma_i32_16x16x64_i8 v[32:35], v[152:155], v[194:197], v[32:35]
	s_barrier
	s_setprio 0
	s_add_u32 s20, s44, 0x20000
	s_addc_u32 s21, s45, 0
	s_add_i32 s63, s89, s18
	v_lshl_add_u64 v[140:141], s[20:21], 0, v[130:131]
	s_mov_b32 m0, s63
	s_nop 0
	global_load_lds_dwordx4 v[140:141], off
	v_lshl_add_u64 v[140:141], s[20:21], 0, v[128:129]
	s_add_i32 m0, s63, 0x2000
	s_nop 0
	global_load_lds_dwordx4 v[140:141], off
	s_waitcnt vmcnt(6)
	s_setprio 1
	s_barrier
	v_mfma_i32_16x16x64_i8 v[28:31], v[198:201], v[156:159], 0
	v_mfma_i32_16x16x64_i8 v[24:27], v[206:209], v[156:159], 0
	v_mfma_i32_16x16x64_i8 v[20:23], v[198:201], v[174:177], 0
	v_mfma_i32_16x16x64_i8 v[16:19], v[206:209], v[174:177], 0
	v_mfma_i32_16x16x64_i8 v[12:15], v[198:201], v[182:185], 0
	v_mfma_i32_16x16x64_i8 v[8:11], v[206:209], v[182:185], 0
	v_mfma_i32_16x16x64_i8 v[4:7], v[198:201], v[190:193], 0
	v_mfma_i32_16x16x64_i8 v[0:3], v[206:209], v[190:193], 0
	v_mfma_i32_16x16x64_i8 v[28:31], v[202:205], v[160:163], v[28:31]
	v_mfma_i32_16x16x64_i8 v[24:27], v[210:213], v[160:163], v[24:27]
	v_mfma_i32_16x16x64_i8 v[20:23], v[202:205], v[178:181], v[20:23]
	v_mfma_i32_16x16x64_i8 v[16:19], v[210:213], v[178:181], v[16:19]
	v_mfma_i32_16x16x64_i8 v[12:15], v[202:205], v[186:189], v[12:15]
	v_mfma_i32_16x16x64_i8 v[8:11], v[210:213], v[186:189], v[8:11]
	v_mfma_i32_16x16x64_i8 v[4:7], v[202:205], v[194:197], v[4:7]
	v_mfma_i32_16x16x64_i8 v[0:3], v[210:213], v[194:197], v[0:3]
	s_add_i32 s63, 0, 0x18000
	v_add_u32_e32 v152, s63, v167
	s_barrier
	s_setprio 0
	ds_read_b128 v[140:143], v152
	ds_read_b128 v[144:147], v152 offset:1024
	ds_read_b128 v[148:151], v152 offset:2048
	ds_read_b128 v[152:155], v152 offset:3072
	s_add_u32 s20, s46, 0x20000
	s_addc_u32 s21, s47, 0
	s_mov_b32 m0, s49
	v_lshl_add_u64 v[198:199], s[20:21], 0, v[130:131]
	ds_read_b128 v[156:159], v172 offset:32768
	ds_read_b128 v[160:163], v172 offset:33792
	ds_read_b128 v[174:177], v172 offset:34816
	ds_read_b128 v[178:181], v172 offset:35840
	ds_read_b128 v[182:185], v172 offset:36864
	ds_read_b128 v[186:189], v172 offset:37888
	ds_read_b128 v[190:193], v172 offset:38912
	ds_read_b128 v[194:197], v172 offset:39936
	global_load_lds_dwordx4 v[198:199], off
	v_lshl_add_u64 v[198:199], s[20:21], 0, v[128:129]
	s_mov_b32 m0, s50
	s_nop 0
	global_load_lds_dwordx4 v[198:199], off
	s_waitcnt lgkmcnt(8)
	s_setprio 1
	s_barrier
	s_waitcnt lgkmcnt(0)
	v_mfma_i32_16x16x64_i8 v[124:127], v[140:143], v[156:159], v[124:127]
	v_mfma_i32_16x16x64_i8 v[120:123], v[148:151], v[156:159], v[120:123]
	v_mfma_i32_16x16x64_i8 v[116:119], v[140:143], v[174:177], v[116:119]
	v_mfma_i32_16x16x64_i8 v[112:115], v[148:151], v[174:177], v[112:115]
	v_mfma_i32_16x16x64_i8 v[108:111], v[140:143], v[182:185], v[108:111]
	v_mfma_i32_16x16x64_i8 v[104:107], v[148:151], v[182:185], v[104:107]
	v_mfma_i32_16x16x64_i8 v[100:103], v[140:143], v[190:193], v[100:103]
	v_mfma_i32_16x16x64_i8 v[96:99], v[148:151], v[190:193], v[96:99]
	v_mfma_i32_16x16x64_i8 v[124:127], v[144:147], v[160:163], v[124:127]
	v_mfma_i32_16x16x64_i8 v[120:123], v[152:155], v[160:163], v[120:123]
	v_mfma_i32_16x16x64_i8 v[116:119], v[144:147], v[178:181], v[116:119]
	v_mfma_i32_16x16x64_i8 v[112:115], v[152:155], v[178:181], v[112:115]
	v_mfma_i32_16x16x64_i8 v[108:111], v[144:147], v[186:189], v[108:111]
	v_mfma_i32_16x16x64_i8 v[104:107], v[152:155], v[186:189], v[104:107]
	v_mfma_i32_16x16x64_i8 v[100:103], v[144:147], v[194:197], v[100:103]
	v_mfma_i32_16x16x64_i8 v[96:99], v[152:155], v[194:197], v[96:99]
	s_barrier
	s_setprio 0
	s_add_i32 s46, 0, 0x1c000
	s_add_i32 s20, s63, s18
	v_add_u32_e32 v164, s46, v167
	v_lshl_add_u64 v[214:215], v[214:215], 0, s[26:27]
	s_mov_b32 m0, s20
	ds_read_b128 v[198:201], v164
	ds_read_b128 v[202:205], v164 offset:1024
	ds_read_b128 v[206:209], v164 offset:2048
	ds_read_b128 v[210:213], v164 offset:3072
	global_load_lds_dwordx4 v[214:215], off
	v_lshl_add_u64 v[214:215], v[216:217], 0, s[26:27]
	s_add_i32 m0, s20, 0x2000
	s_nop 0
	global_load_lds_dwordx4 v[214:215], off
	s_setprio 1
	s_barrier
	s_waitcnt lgkmcnt(0)
	v_mfma_i32_16x16x64_i8 v[92:95], v[198:201], v[156:159], v[92:95]
	v_mfma_i32_16x16x64_i8 v[88:91], v[206:209], v[156:159], v[88:91]
	v_mfma_i32_16x16x64_i8 v[84:87], v[198:201], v[174:177], v[84:87]
	v_mfma_i32_16x16x64_i8 v[80:83], v[206:209], v[174:177], v[80:83]
	v_mfma_i32_16x16x64_i8 v[76:79], v[198:201], v[182:185], v[76:79]
	v_mfma_i32_16x16x64_i8 v[72:75], v[206:209], v[182:185], v[72:75]
	v_mfma_i32_16x16x64_i8 v[68:71], v[198:201], v[190:193], v[68:71]
	v_mfma_i32_16x16x64_i8 v[64:67], v[206:209], v[190:193], v[64:67]
	v_mfma_i32_16x16x64_i8 v[92:95], v[202:205], v[160:163], v[92:95]
	v_mfma_i32_16x16x64_i8 v[88:91], v[210:213], v[160:163], v[88:91]
	v_mfma_i32_16x16x64_i8 v[84:87], v[202:205], v[178:181], v[84:87]
	v_mfma_i32_16x16x64_i8 v[80:83], v[210:213], v[178:181], v[80:83]
	v_mfma_i32_16x16x64_i8 v[76:79], v[202:205], v[186:189], v[76:79]
	v_mfma_i32_16x16x64_i8 v[72:75], v[210:213], v[186:189], v[72:75]
	v_mfma_i32_16x16x64_i8 v[68:71], v[202:205], v[194:197], v[68:71]
	v_mfma_i32_16x16x64_i8 v[64:67], v[210:213], v[194:197], v[64:67]
	s_mov_b32 m0, s53
	v_lshl_add_u64 v[214:215], v[218:219], 0, s[26:27]
	s_barrier
	s_setprio 0
	ds_read_b128 v[156:159], v172 offset:49152
	ds_read_b128 v[160:163], v172 offset:50176
	ds_read_b128 v[174:177], v172 offset:51200
	ds_read_b128 v[178:181], v172 offset:52224
	ds_read_b128 v[182:185], v172 offset:53248
	ds_read_b128 v[186:189], v172 offset:54272
	ds_read_b128 v[190:193], v172 offset:55296
	ds_read_b128 v[194:197], v172 offset:56320
	global_load_lds_dwordx4 v[214:215], off
	v_lshl_add_u64 v[214:215], v[220:221], 0, s[26:27]
	s_mov_b32 m0, s54
	s_nop 0
	global_load_lds_dwordx4 v[214:215], off
	s_setprio 1
	s_barrier
	s_waitcnt lgkmcnt(0)
	v_mfma_i32_16x16x64_i8 v[60:63], v[140:143], v[156:159], v[60:63]
	v_mfma_i32_16x16x64_i8 v[56:59], v[148:151], v[156:159], v[56:59]
	v_mfma_i32_16x16x64_i8 v[52:55], v[140:143], v[174:177], v[52:55]
	v_mfma_i32_16x16x64_i8 v[48:51], v[148:151], v[174:177], v[48:51]
	v_mfma_i32_16x16x64_i8 v[44:47], v[140:143], v[182:185], v[44:47]
	v_mfma_i32_16x16x64_i8 v[40:43], v[148:151], v[182:185], v[40:43]
	v_mfma_i32_16x16x64_i8 v[36:39], v[140:143], v[190:193], v[36:39]
	v_mfma_i32_16x16x64_i8 v[32:35], v[148:151], v[190:193], v[32:35]
	v_mfma_i32_16x16x64_i8 v[60:63], v[144:147], v[160:163], v[60:63]
	v_mfma_i32_16x16x64_i8 v[56:59], v[152:155], v[160:163], v[56:59]
	v_mfma_i32_16x16x64_i8 v[52:55], v[144:147], v[178:181], v[52:55]
	v_mfma_i32_16x16x64_i8 v[48:51], v[152:155], v[178:181], v[48:51]
	v_mfma_i32_16x16x64_i8 v[44:47], v[144:147], v[186:189], v[44:47]
	v_mfma_i32_16x16x64_i8 v[40:43], v[152:155], v[186:189], v[40:43]
	v_mfma_i32_16x16x64_i8 v[36:39], v[144:147], v[194:197], v[36:39]
	v_mfma_i32_16x16x64_i8 v[32:35], v[152:155], v[194:197], v[32:35]
	s_barrier
	s_setprio 0
	s_add_u32 s20, s44, 0x20080
	s_addc_u32 s21, s45, 0
	s_add_i32 s44, s46, s18
	v_lshl_add_u64 v[140:141], s[20:21], 0, v[130:131]
	s_mov_b32 m0, s44
	s_nop 0
	global_load_lds_dwordx4 v[140:141], off
	v_lshl_add_u64 v[140:141], s[20:21], 0, v[128:129]
	s_add_i32 m0, s44, 0x2000
	s_nop 0
	global_load_lds_dwordx4 v[140:141], off
	s_waitcnt vmcnt(6)
	s_setprio 1
	s_barrier
	v_mfma_i32_16x16x64_i8 v[28:31], v[198:201], v[156:159], v[28:31]
	v_mfma_i32_16x16x64_i8 v[24:27], v[206:209], v[156:159], v[24:27]
	v_mfma_i32_16x16x64_i8 v[20:23], v[198:201], v[174:177], v[20:23]
	v_mfma_i32_16x16x64_i8 v[16:19], v[206:209], v[174:177], v[16:19]
	v_mfma_i32_16x16x64_i8 v[12:15], v[198:201], v[182:185], v[12:15]
	v_mfma_i32_16x16x64_i8 v[8:11], v[206:209], v[182:185], v[8:11]
	v_mfma_i32_16x16x64_i8 v[4:7], v[198:201], v[190:193], v[4:7]
	v_mfma_i32_16x16x64_i8 v[0:3], v[206:209], v[190:193], v[0:3]
	v_mfma_i32_16x16x64_i8 v[28:31], v[202:205], v[160:163], v[28:31]
	v_mfma_i32_16x16x64_i8 v[24:27], v[210:213], v[160:163], v[24:27]
	v_mfma_i32_16x16x64_i8 v[20:23], v[202:205], v[178:181], v[20:23]
	v_mfma_i32_16x16x64_i8 v[16:19], v[210:213], v[178:181], v[16:19]
	v_mfma_i32_16x16x64_i8 v[12:15], v[202:205], v[186:189], v[12:15]
	v_mfma_i32_16x16x64_i8 v[8:11], v[210:213], v[186:189], v[8:11]
	v_mfma_i32_16x16x64_i8 v[4:7], v[202:205], v[194:197], v[4:7]
	v_mfma_i32_16x16x64_i8 v[0:3], v[210:213], v[194:197], v[0:3]
	s_add_u32 s42, s42, 0x100
	s_addc_u32 s43, s43, 0
	s_add_u32 s60, s60, 0x100
	s_addc_u32 s61, s61, 0
	s_cmp_ge_i32 s62, s52
	s_mov_b32 s44, s62
	s_barrier
	s_setprio 0
	s_cbranch_scc1 .Lpeel_done_P10
.LBB0_716:
	v_add_u32_e32 v152, s88, v167
	ds_read_b128 v[140:143], v152
	ds_read_b128 v[144:147], v152 offset:1024
	ds_read_b128 v[148:151], v152 offset:2048
	ds_read_b128 v[152:155], v152 offset:3072
	s_add_i32 s62, s44, 2
	s_add_u32 s20, s42, 0xfffe0080
	s_addc_u32 s21, s43, -1
	s_cmp_eq_u32 s55, s44
	s_cselect_b32 s44, s59, s60
	s_cselect_b32 s47, s31, s21
	s_cselect_b32 s46, s35, s20
	s_cselect_b32 s45, s58, s61
	v_lshl_add_u64 v[198:199], s[42:43], 0, v[132:133]
	s_add_i32 m0, s41, 0xc000
	ds_read_b128 v[156:159], v172
	ds_read_b128 v[160:163], v172 offset:1024
	ds_read_b128 v[174:177], v172 offset:2048
	ds_read_b128 v[178:181], v172 offset:3072
	ds_read_b128 v[182:185], v172 offset:4096
	ds_read_b128 v[186:189], v172 offset:5120
	ds_read_b128 v[190:193], v172 offset:6144
	ds_read_b128 v[194:197], v172 offset:7168
	global_load_lds_dwordx4 v[198:199], off
	v_lshl_add_u64 v[198:199], s[42:43], 0, v[134:135]
	s_add_i32 m0, s41, 0xe000
	s_nop 0
	global_load_lds_dwordx4 v[198:199], off
	s_waitcnt lgkmcnt(8)
	s_setprio 1
	s_barrier
	s_waitcnt lgkmcnt(0)
	v_mfma_i32_16x16x64_i8 v[124:127], v[140:143], v[156:159], v[124:127]
	v_mfma_i32_16x16x64_i8 v[120:123], v[148:151], v[156:159], v[120:123]
	v_mfma_i32_16x16x64_i8 v[116:119], v[140:143], v[174:177], v[116:119]
	v_mfma_i32_16x16x64_i8 v[112:115], v[148:151], v[174:177], v[112:115]
	v_mfma_i32_16x16x64_i8 v[108:111], v[140:143], v[182:185], v[108:111]
	v_mfma_i32_16x16x64_i8 v[104:107], v[148:151], v[182:185], v[104:107]
	v_mfma_i32_16x16x64_i8 v[100:103], v[140:143], v[190:193], v[100:103]
	v_mfma_i32_16x16x64_i8 v[96:99], v[148:151], v[190:193], v[96:99]
	v_mfma_i32_16x16x64_i8 v[124:127], v[144:147], v[160:163], v[124:127]
	v_mfma_i32_16x16x64_i8 v[120:123], v[152:155], v[160:163], v[120:123]
	v_mfma_i32_16x16x64_i8 v[116:119], v[144:147], v[178:181], v[116:119]
	v_mfma_i32_16x16x64_i8 v[112:115], v[152:155], v[178:181], v[112:115]
	v_mfma_i32_16x16x64_i8 v[108:111], v[144:147], v[186:189], v[108:111]
	v_mfma_i32_16x16x64_i8 v[104:107], v[152:155], v[186:189], v[104:107]
	v_mfma_i32_16x16x64_i8 v[100:103], v[144:147], v[194:197], v[100:103]
	v_mfma_i32_16x16x64_i8 v[96:99], v[152:155], v[194:197], v[96:99]
	s_barrier
	s_setprio 0
	s_add_i32 s20, s88, s18
	v_add_u32_e32 v164, s89, v167
	v_lshl_add_u64 v[214:215], s[44:45], 0, v[130:131]
	s_mov_b32 m0, s20
	ds_read_b128 v[198:201], v164
	ds_read_b128 v[202:205], v164 offset:1024
	ds_read_b128 v[206:209], v164 offset:2048
	ds_read_b128 v[210:213], v164 offset:3072
	global_load_lds_dwordx4 v[214:215], off
	v_lshl_add_u64 v[216:217], s[44:45], 0, v[128:129]
	s_add_i32 m0, s20, 0x2000
	s_nop 0
	global_load_lds_dwordx4 v[216:217], off
	s_setprio 1
	s_barrier
	s_waitcnt lgkmcnt(0)
	v_mfma_i32_16x16x64_i8 v[92:95], v[198:201], v[156:159], v[92:95]
	v_mfma_i32_16x16x64_i8 v[88:91], v[206:209], v[156:159], v[88:91]
	v_mfma_i32_16x16x64_i8 v[84:87], v[198:201], v[174:177], v[84:87]
	v_mfma_i32_16x16x64_i8 v[80:83], v[206:209], v[174:177], v[80:83]
	v_mfma_i32_16x16x64_i8 v[76:79], v[198:201], v[182:185], v[76:79]
	v_mfma_i32_16x16x64_i8 v[72:75], v[206:209], v[182:185], v[72:75]
	v_mfma_i32_16x16x64_i8 v[68:71], v[198:201], v[190:193], v[68:71]
	v_mfma_i32_16x16x64_i8 v[64:67], v[206:209], v[190:193], v[64:67]
	v_mfma_i32_16x16x64_i8 v[92:95], v[202:205], v[160:163], v[92:95]
	v_mfma_i32_16x16x64_i8 v[88:91], v[210:213], v[160:163], v[88:91]
	v_mfma_i32_16x16x64_i8 v[84:87], v[202:205], v[178:181], v[84:87]
	v_mfma_i32_16x16x64_i8 v[80:83], v[210:213], v[178:181], v[80:83]
	v_mfma_i32_16x16x64_i8 v[76:79], v[202:205], v[186:189], v[76:79]
	v_mfma_i32_16x16x64_i8 v[72:75], v[210:213], v[186:189], v[72:75]
	v_mfma_i32_16x16x64_i8 v[68:71], v[202:205], v[194:197], v[68:71]
	v_mfma_i32_16x16x64_i8 v[64:67], v[210:213], v[194:197], v[64:67]
	s_mov_b32 m0, s41
	v_lshl_add_u64 v[218:219], s[46:47], 0, v[130:131]
	s_barrier
	s_setprio 0
	ds_read_b128 v[156:159], v172 offset:16384
	ds_read_b128 v[160:163], v172 offset:17408
	ds_read_b128 v[174:177], v172 offset:18432
	ds_read_b128 v[178:181], v172 offset:19456
	ds_read_b128 v[182:185], v172 offset:20480
	ds_read_b128 v[186:189], v172 offset:21504
	ds_read_b128 v[190:193], v172 offset:22528
	ds_read_b128 v[194:197], v172 offset:23552
	global_load_lds_dwordx4 v[218:219], off
	v_lshl_add_u64 v[220:221], s[46:47], 0, v[128:129]
	s_mov_b32 m0, s48
	s_nop 0
	global_load_lds_dwordx4 v[220:221], off
	s_setprio 1
	s_barrier
	s_waitcnt lgkmcnt(0)
	v_mfma_i32_16x16x64_i8 v[60:63], v[140:143], v[156:159], v[60:63]
	v_mfma_i32_16x16x64_i8 v[56:59], v[148:151], v[156:159], v[56:59]
	v_mfma_i32_16x16x64_i8 v[52:55], v[140:143], v[174:177], v[52:55]
	v_mfma_i32_16x16x64_i8 v[48:51], v[148:151], v[174:177], v[48:51]
	v_mfma_i32_16x16x64_i8 v[44:47], v[140:143], v[182:185], v[44:47]
	v_mfma_i32_16x16x64_i8 v[40:43], v[148:151], v[182:185], v[40:43]
	v_mfma_i32_16x16x64_i8 v[36:39], v[140:143], v[190:193], v[36:39]
	v_mfma_i32_16x16x64_i8 v[32:35], v[148:151], v[190:193], v[32:35]
	v_mfma_i32_16x16x64_i8 v[60:63], v[144:147], v[160:163], v[60:63]
	v_mfma_i32_16x16x64_i8 v[56:59], v[152:155], v[160:163], v[56:59]
	v_mfma_i32_16x16x64_i8 v[52:55], v[144:147], v[178:181], v[52:55]
	v_mfma_i32_16x16x64_i8 v[48:51], v[152:155], v[178:181], v[48:51]
	v_mfma_i32_16x16x64_i8 v[44:47], v[144:147], v[186:189], v[44:47]
	v_mfma_i32_16x16x64_i8 v[40:43], v[152:155], v[186:189], v[40:43]
	v_mfma_i32_16x16x64_i8 v[36:39], v[144:147], v[194:197], v[36:39]
	v_mfma_i32_16x16x64_i8 v[32:35], v[152:155], v[194:197], v[32:35]
	s_barrier
	s_setprio 0
	s_add_u32 s20, s44, 0x20000
	s_addc_u32 s21, s45, 0
	s_add_i32 s63, s89, s18
	v_lshl_add_u64 v[140:141], s[20:21], 0, v[130:131]
	s_mov_b32 m0, s63
	s_nop 0
	global_load_lds_dwordx4 v[140:141], off
	v_lshl_add_u64 v[140:141], s[20:21], 0, v[128:129]
	s_add_i32 m0, s63, 0x2000
	s_nop 0
	global_load_lds_dwordx4 v[140:141], off
	s_waitcnt vmcnt(6)
	s_setprio 1
	s_barrier
	v_mfma_i32_16x16x64_i8 v[28:31], v[198:201], v[156:159], v[28:31]
	v_mfma_i32_16x16x64_i8 v[24:27], v[206:209], v[156:159], v[24:27]
	v_mfma_i32_16x16x64_i8 v[20:23], v[198:201], v[174:177], v[20:23]
	v_mfma_i32_16x16x64_i8 v[16:19], v[206:209], v[174:177], v[16:19]
	v_mfma_i32_16x16x64_i8 v[12:15], v[198:201], v[182:185], v[12:15]
	v_mfma_i32_16x16x64_i8 v[8:11], v[206:209], v[182:185], v[8:11]
	v_mfma_i32_16x16x64_i8 v[4:7], v[198:201], v[190:193], v[4:7]
	v_mfma_i32_16x16x64_i8 v[0:3], v[206:209], v[190:193], v[0:3]
	v_mfma_i32_16x16x64_i8 v[28:31], v[202:205], v[160:163], v[28:31]
	v_mfma_i32_16x16x64_i8 v[24:27], v[210:213], v[160:163], v[24:27]
	v_mfma_i32_16x16x64_i8 v[20:23], v[202:205], v[178:181], v[20:23]
	v_mfma_i32_16x16x64_i8 v[16:19], v[210:213], v[178:181], v[16:19]
	v_mfma_i32_16x16x64_i8 v[12:15], v[202:205], v[186:189], v[12:15]
	v_mfma_i32_16x16x64_i8 v[8:11], v[210:213], v[186:189], v[8:11]
	v_mfma_i32_16x16x64_i8 v[4:7], v[202:205], v[194:197], v[4:7]
	v_mfma_i32_16x16x64_i8 v[0:3], v[210:213], v[194:197], v[0:3]
	s_add_i32 s63, 0, 0x18000
	v_add_u32_e32 v152, s63, v167
	s_barrier
	s_setprio 0
	ds_read_b128 v[140:143], v152
	ds_read_b128 v[144:147], v152 offset:1024
	ds_read_b128 v[148:151], v152 offset:2048
	ds_read_b128 v[152:155], v152 offset:3072
	s_add_u32 s20, s46, 0x20000
	s_addc_u32 s21, s47, 0
	s_mov_b32 m0, s49
	v_lshl_add_u64 v[198:199], s[20:21], 0, v[130:131]
	ds_read_b128 v[156:159], v172 offset:32768
	ds_read_b128 v[160:163], v172 offset:33792
	ds_read_b128 v[174:177], v172 offset:34816
	ds_read_b128 v[178:181], v172 offset:35840
	ds_read_b128 v[182:185], v172 offset:36864
	ds_read_b128 v[186:189], v172 offset:37888
	ds_read_b128 v[190:193], v172 offset:38912
	ds_read_b128 v[194:197], v172 offset:39936
	global_load_lds_dwordx4 v[198:199], off
	v_lshl_add_u64 v[198:199], s[20:21], 0, v[128:129]
	s_mov_b32 m0, s50
	s_nop 0
	global_load_lds_dwordx4 v[198:199], off
	s_waitcnt lgkmcnt(8)
	s_setprio 1
	s_barrier
	s_waitcnt lgkmcnt(0)
	v_mfma_i32_16x16x64_i8 v[124:127], v[140:143], v[156:159], v[124:127]
	v_mfma_i32_16x16x64_i8 v[120:123], v[148:151], v[156:159], v[120:123]
	v_mfma_i32_16x16x64_i8 v[116:119], v[140:143], v[174:177], v[116:119]
	v_mfma_i32_16x16x64_i8 v[112:115], v[148:151], v[174:177], v[112:115]
	v_mfma_i32_16x16x64_i8 v[108:111], v[140:143], v[182:185], v[108:111]
	v_mfma_i32_16x16x64_i8 v[104:107], v[148:151], v[182:185], v[104:107]
	v_mfma_i32_16x16x64_i8 v[100:103], v[140:143], v[190:193], v[100:103]
	v_mfma_i32_16x16x64_i8 v[96:99], v[148:151], v[190:193], v[96:99]
	v_mfma_i32_16x16x64_i8 v[124:127], v[144:147], v[160:163], v[124:127]
	v_mfma_i32_16x16x64_i8 v[120:123], v[152:155], v[160:163], v[120:123]
	v_mfma_i32_16x16x64_i8 v[116:119], v[144:147], v[178:181], v[116:119]
	v_mfma_i32_16x16x64_i8 v[112:115], v[152:155], v[178:181], v[112:115]
	v_mfma_i32_16x16x64_i8 v[108:111], v[144:147], v[186:189], v[108:111]
	v_mfma_i32_16x16x64_i8 v[104:107], v[152:155], v[186:189], v[104:107]
	v_mfma_i32_16x16x64_i8 v[100:103], v[144:147], v[194:197], v[100:103]
	v_mfma_i32_16x16x64_i8 v[96:99], v[152:155], v[194:197], v[96:99]
	s_barrier
	s_setprio 0
	s_add_i32 s46, 0, 0x1c000
	s_add_i32 s20, s63, s18
	v_add_u32_e32 v164, s46, v167
	v_lshl_add_u64 v[214:215], v[214:215], 0, s[26:27]
	s_mov_b32 m0, s20
	ds_read_b128 v[198:201], v164
	ds_read_b128 v[202:205], v164 offset:1024
	ds_read_b128 v[206:209], v164 offset:2048
	ds_read_b128 v[210:213], v164 offset:3072
	global_load_lds_dwordx4 v[214:215], off
	v_lshl_add_u64 v[214:215], v[216:217], 0, s[26:27]
	s_add_i32 m0, s20, 0x2000
	s_nop 0
	global_load_lds_dwordx4 v[214:215], off
	s_setprio 1
	s_barrier
	s_waitcnt lgkmcnt(0)
	v_mfma_i32_16x16x64_i8 v[92:95], v[198:201], v[156:159], v[92:95]
	v_mfma_i32_16x16x64_i8 v[88:91], v[206:209], v[156:159], v[88:91]
	v_mfma_i32_16x16x64_i8 v[84:87], v[198:201], v[174:177], v[84:87]
	v_mfma_i32_16x16x64_i8 v[80:83], v[206:209], v[174:177], v[80:83]
	v_mfma_i32_16x16x64_i8 v[76:79], v[198:201], v[182:185], v[76:79]
	v_mfma_i32_16x16x64_i8 v[72:75], v[206:209], v[182:185], v[72:75]
	v_mfma_i32_16x16x64_i8 v[68:71], v[198:201], v[190:193], v[68:71]
	v_mfma_i32_16x16x64_i8 v[64:67], v[206:209], v[190:193], v[64:67]
	v_mfma_i32_16x16x64_i8 v[92:95], v[202:205], v[160:163], v[92:95]
	v_mfma_i32_16x16x64_i8 v[88:91], v[210:213], v[160:163], v[88:91]
	v_mfma_i32_16x16x64_i8 v[84:87], v[202:205], v[178:181], v[84:87]
	v_mfma_i32_16x16x64_i8 v[80:83], v[210:213], v[178:181], v[80:83]
	v_mfma_i32_16x16x64_i8 v[76:79], v[202:205], v[186:189], v[76:79]
	v_mfma_i32_16x16x64_i8 v[72:75], v[210:213], v[186:189], v[72:75]
	v_mfma_i32_16x16x64_i8 v[68:71], v[202:205], v[194:197], v[68:71]
	v_mfma_i32_16x16x64_i8 v[64:67], v[210:213], v[194:197], v[64:67]
	s_mov_b32 m0, s53
	v_lshl_add_u64 v[214:215], v[218:219], 0, s[26:27]
	s_barrier
	s_setprio 0
	ds_read_b128 v[156:159], v172 offset:49152
	ds_read_b128 v[160:163], v172 offset:50176
	ds_read_b128 v[174:177], v172 offset:51200
	ds_read_b128 v[178:181], v172 offset:52224
	ds_read_b128 v[182:185], v172 offset:53248
	ds_read_b128 v[186:189], v172 offset:54272
	ds_read_b128 v[190:193], v172 offset:55296
	ds_read_b128 v[194:197], v172 offset:56320
	global_load_lds_dwordx4 v[214:215], off
	v_lshl_add_u64 v[214:215], v[220:221], 0, s[26:27]
	s_mov_b32 m0, s54
	s_nop 0
	global_load_lds_dwordx4 v[214:215], off
	s_setprio 1
	s_barrier
	s_waitcnt lgkmcnt(0)
	v_mfma_i32_16x16x64_i8 v[60:63], v[140:143], v[156:159], v[60:63]
	v_mfma_i32_16x16x64_i8 v[56:59], v[148:151], v[156:159], v[56:59]
	v_mfma_i32_16x16x64_i8 v[52:55], v[140:143], v[174:177], v[52:55]
	v_mfma_i32_16x16x64_i8 v[48:51], v[148:151], v[174:177], v[48:51]
	v_mfma_i32_16x16x64_i8 v[44:47], v[140:143], v[182:185], v[44:47]
	v_mfma_i32_16x16x64_i8 v[40:43], v[148:151], v[182:185], v[40:43]
	v_mfma_i32_16x16x64_i8 v[36:39], v[140:143], v[190:193], v[36:39]
	v_mfma_i32_16x16x64_i8 v[32:35], v[148:151], v[190:193], v[32:35]
	v_mfma_i32_16x16x64_i8 v[60:63], v[144:147], v[160:163], v[60:63]
	v_mfma_i32_16x16x64_i8 v[56:59], v[152:155], v[160:163], v[56:59]
	v_mfma_i32_16x16x64_i8 v[52:55], v[144:147], v[178:181], v[52:55]
	v_mfma_i32_16x16x64_i8 v[48:51], v[152:155], v[178:181], v[48:51]
	v_mfma_i32_16x16x64_i8 v[44:47], v[144:147], v[186:189], v[44:47]
	v_mfma_i32_16x16x64_i8 v[40:43], v[152:155], v[186:189], v[40:43]
	v_mfma_i32_16x16x64_i8 v[36:39], v[144:147], v[194:197], v[36:39]
	v_mfma_i32_16x16x64_i8 v[32:35], v[152:155], v[194:197], v[32:35]
	s_barrier
	s_setprio 0
	s_add_u32 s20, s44, 0x20080
	s_addc_u32 s21, s45, 0
	s_add_i32 s44, s46, s18
	v_lshl_add_u64 v[140:141], s[20:21], 0, v[130:131]
	s_mov_b32 m0, s44
	s_nop 0
	global_load_lds_dwordx4 v[140:141], off
	v_lshl_add_u64 v[140:141], s[20:21], 0, v[128:129]
	s_add_i32 m0, s44, 0x2000
	s_nop 0
	global_load_lds_dwordx4 v[140:141], off
	s_waitcnt vmcnt(6)
	s_setprio 1
	s_barrier
	v_mfma_i32_16x16x64_i8 v[28:31], v[198:201], v[156:159], v[28:31]
	v_mfma_i32_16x16x64_i8 v[24:27], v[206:209], v[156:159], v[24:27]
	v_mfma_i32_16x16x64_i8 v[20:23], v[198:201], v[174:177], v[20:23]
	v_mfma_i32_16x16x64_i8 v[16:19], v[206:209], v[174:177], v[16:19]
	v_mfma_i32_16x16x64_i8 v[12:15], v[198:201], v[182:185], v[12:15]
	v_mfma_i32_16x16x64_i8 v[8:11], v[206:209], v[182:185], v[8:11]
	v_mfma_i32_16x16x64_i8 v[4:7], v[198:201], v[190:193], v[4:7]
	v_mfma_i32_16x16x64_i8 v[0:3], v[206:209], v[190:193], v[0:3]
	v_mfma_i32_16x16x64_i8 v[28:31], v[202:205], v[160:163], v[28:31]
	v_mfma_i32_16x16x64_i8 v[24:27], v[210:213], v[160:163], v[24:27]
	v_mfma_i32_16x16x64_i8 v[20:23], v[202:205], v[178:181], v[20:23]
	v_mfma_i32_16x16x64_i8 v[16:19], v[210:213], v[178:181], v[16:19]
	v_mfma_i32_16x16x64_i8 v[12:15], v[202:205], v[186:189], v[12:15]
	v_mfma_i32_16x16x64_i8 v[8:11], v[210:213], v[186:189], v[8:11]
	v_mfma_i32_16x16x64_i8 v[4:7], v[202:205], v[194:197], v[4:7]
	v_mfma_i32_16x16x64_i8 v[0:3], v[210:213], v[194:197], v[0:3]
	s_add_u32 s42, s42, 0x100
	s_addc_u32 s43, s43, 0
	s_add_u32 s60, s60, 0x100
	s_addc_u32 s61, s61, 0
	s_cmp_ge_i32 s62, s52
	s_mov_b32 s44, s62
	s_barrier
	s_setprio 0
	s_cbranch_scc0 .LBB0_716

.Lpz_P11:
	s_add_u32 s14, s12, 0x100
	s_addc_u32 s15, s13, 0
	s_mov_b32 s8, 0
	ds_read_b128 v[56:59], v181
	ds_read_b128 v[68:71], v181 offset:1024
	ds_read_b128 v[72:75], v181 offset:2048
	ds_read_b128 v[76:79], v181 offset:3072
	s_add_i32 s16, s8, 2
	s_add_u32 s6, s10, 0x100
	s_addc_u32 s7, s11, 0
	s_cmp_eq_u32 s66, s8
	s_cselect_b32 s8, s48, s14
	s_cselect_b32 s13, s47, s7
	s_cselect_b32 s12, s46, s6
	s_cselect_b32 s9, s49, s15
	v_lshl_add_u64 v[196:197], s[10:11], 0, v[164:165]
	s_add_i32 m0, s53, 0xc000
	ds_read_b128 v[144:147], v182
	ds_read_b128 v[148:151], v182 offset:1024
	ds_read_b128 v[152:155], v182 offset:2048
	ds_read_b128 v[156:159], v182 offset:3072
	ds_read_b128 v[172:175], v182 offset:4096
	ds_read_b128 v[184:187], v182 offset:5120
	ds_read_b128 v[188:191], v182 offset:6144
	ds_read_b128 v[192:195], v182 offset:7168
	global_load_lds_dwordx4 v[196:197], off
	v_lshl_add_u64 v[196:197], s[10:11], 0, v[166:167]
	s_add_i32 m0, s53, 0xe000
	s_nop 0
	global_load_lds_dwordx4 v[196:197], off
	s_waitcnt lgkmcnt(8)
	s_setprio 1
	s_barrier
	s_waitcnt lgkmcnt(0)
	v_mfma_f32_16x16x32_bf16 v[136:139], v[56:59], v[144:147], 0
	v_mfma_f32_16x16x32_bf16 v[140:143], v[72:75], v[144:147], 0
	v_mfma_f32_16x16x32_bf16 v[124:127], v[56:59], v[152:155], 0
	v_mfma_f32_16x16x32_bf16 v[120:123], v[72:75], v[152:155], 0
	v_mfma_f32_16x16x32_bf16 v[108:111], v[56:59], v[172:175], 0
	v_mfma_f32_16x16x32_bf16 v[104:107], v[72:75], v[172:175], 0
	v_mfma_f32_16x16x32_bf16 v[92:95], v[56:59], v[188:191], 0
	v_mfma_f32_16x16x32_bf16 v[88:91], v[72:75], v[188:191], 0
	v_mfma_f32_16x16x32_bf16 v[136:139], v[68:71], v[148:151], v[136:139]
	v_mfma_f32_16x16x32_bf16 v[140:143], v[76:79], v[148:151], v[140:143]
	v_mfma_f32_16x16x32_bf16 v[124:127], v[68:71], v[156:159], v[124:127]
	v_mfma_f32_16x16x32_bf16 v[120:123], v[76:79], v[156:159], v[120:123]
	v_mfma_f32_16x16x32_bf16 v[108:111], v[68:71], v[184:187], v[108:111]
	v_mfma_f32_16x16x32_bf16 v[104:107], v[76:79], v[184:187], v[104:107]
	v_mfma_f32_16x16x32_bf16 v[92:95], v[68:71], v[192:195], v[92:95]
	v_mfma_f32_16x16x32_bf16 v[88:91], v[76:79], v[192:195], v[88:91]
	s_barrier
	s_setprio 0
	s_add_i32 s10, s88, s52
	v_lshl_add_u64 v[212:213], s[8:9], 0, v[160:161]
	s_mov_b32 m0, s10
	ds_read_b128 v[196:199], v183
	ds_read_b128 v[200:203], v183 offset:1024
	ds_read_b128 v[204:207], v183 offset:2048
	ds_read_b128 v[208:211], v183 offset:3072
	global_load_lds_dwordx4 v[212:213], off
	v_lshl_add_u64 v[214:215], s[8:9], 0, v[162:163]
	s_add_i32 m0, s10, 0x2000
	s_nop 0
	global_load_lds_dwordx4 v[214:215], off
	s_setprio 1
	s_barrier
	s_waitcnt lgkmcnt(0)
	v_mfma_f32_16x16x32_bf16 v[132:135], v[196:199], v[144:147], 0
	v_mfma_f32_16x16x32_bf16 v[128:131], v[204:207], v[144:147], 0
	v_mfma_f32_16x16x32_bf16 v[116:119], v[196:199], v[152:155], 0
	v_mfma_f32_16x16x32_bf16 v[112:115], v[204:207], v[152:155], 0
	v_mfma_f32_16x16x32_bf16 v[100:103], v[196:199], v[172:175], 0
	v_mfma_f32_16x16x32_bf16 v[96:99], v[204:207], v[172:175], 0
	v_mfma_f32_16x16x32_bf16 v[84:87], v[196:199], v[188:191], 0
	v_mfma_f32_16x16x32_bf16 v[80:83], v[204:207], v[188:191], 0
	v_mfma_f32_16x16x32_bf16 v[132:135], v[200:203], v[148:151], v[132:135]
	v_mfma_f32_16x16x32_bf16 v[128:131], v[208:211], v[148:151], v[128:131]
	v_mfma_f32_16x16x32_bf16 v[116:119], v[200:203], v[156:159], v[116:119]
	v_mfma_f32_16x16x32_bf16 v[112:115], v[208:211], v[156:159], v[112:115]
	v_mfma_f32_16x16x32_bf16 v[100:103], v[200:203], v[184:187], v[100:103]
	v_mfma_f32_16x16x32_bf16 v[96:99], v[208:211], v[184:187], v[96:99]
	v_mfma_f32_16x16x32_bf16 v[84:87], v[200:203], v[192:195], v[84:87]
	v_mfma_f32_16x16x32_bf16 v[80:83], v[208:211], v[192:195], v[80:83]
	s_mov_b32 m0, s53
	v_lshl_add_u64 v[216:217], s[12:13], 0, v[160:161]
	s_barrier
	s_setprio 0
	ds_read_b128 v[144:147], v182 offset:16384
	ds_read_b128 v[148:151], v182 offset:17408
	ds_read_b128 v[152:155], v182 offset:18432
	ds_read_b128 v[156:159], v182 offset:19456
	ds_read_b128 v[172:175], v182 offset:20480
	ds_read_b128 v[184:187], v182 offset:21504
	ds_read_b128 v[188:191], v182 offset:22528
	ds_read_b128 v[192:195], v182 offset:23552
	global_load_lds_dwordx4 v[216:217], off
	v_lshl_add_u64 v[218:219], s[12:13], 0, v[162:163]
	s_mov_b32 m0, s54
	s_nop 0
	global_load_lds_dwordx4 v[218:219], off
	s_setprio 1
	s_barrier
	s_waitcnt lgkmcnt(0)
	v_mfma_f32_16x16x32_bf16 v[64:67], v[56:59], v[144:147], 0
	v_mfma_f32_16x16x32_bf16 v[60:63], v[72:75], v[144:147], 0
	v_mfma_f32_16x16x32_bf16 v[44:47], v[56:59], v[152:155], 0
	v_mfma_f32_16x16x32_bf16 v[40:43], v[72:75], v[152:155], 0
	v_mfma_f32_16x16x32_bf16 v[28:31], v[56:59], v[172:175], 0
	v_mfma_f32_16x16x32_bf16 v[24:27], v[72:75], v[172:175], 0
	v_mfma_f32_16x16x32_bf16 v[12:15], v[56:59], v[188:191], 0
	v_mfma_f32_16x16x32_bf16 v[8:11], v[72:75], v[188:191], 0
	v_mfma_f32_16x16x32_bf16 v[64:67], v[68:71], v[148:151], v[64:67]
	v_mfma_f32_16x16x32_bf16 v[60:63], v[76:79], v[148:151], v[60:63]
	v_mfma_f32_16x16x32_bf16 v[44:47], v[68:71], v[156:159], v[44:47]
	v_mfma_f32_16x16x32_bf16 v[40:43], v[76:79], v[156:159], v[40:43]
	v_mfma_f32_16x16x32_bf16 v[28:31], v[68:71], v[184:187], v[28:31]
	v_mfma_f32_16x16x32_bf16 v[24:27], v[76:79], v[184:187], v[24:27]
	v_mfma_f32_16x16x32_bf16 v[12:15], v[68:71], v[192:195], v[12:15]
	v_mfma_f32_16x16x32_bf16 v[8:11], v[76:79], v[192:195], v[8:11]
	s_barrier
	s_setprio 0
	s_add_u32 s10, s8, 0xb0000
	s_addc_u32 s11, s9, 0
	s_add_i32 s17, s89, s52
	v_lshl_add_u64 v[56:57], s[10:11], 0, v[160:161]
	s_mov_b32 m0, s17
	s_nop 0
	global_load_lds_dwordx4 v[56:57], off
	v_lshl_add_u64 v[56:57], s[10:11], 0, v[162:163]
	s_add_i32 m0, s17, 0x2000
	s_nop 0
	global_load_lds_dwordx4 v[56:57], off
	s_waitcnt vmcnt(6)
	s_setprio 1
	s_barrier
	v_mfma_f32_16x16x32_bf16 v[52:55], v[196:199], v[144:147], 0
	v_mfma_f32_16x16x32_bf16 v[48:51], v[204:207], v[144:147], 0
	v_mfma_f32_16x16x32_bf16 v[36:39], v[196:199], v[152:155], 0
	v_mfma_f32_16x16x32_bf16 v[32:35], v[204:207], v[152:155], 0
	v_mfma_f32_16x16x32_bf16 v[20:23], v[196:199], v[172:175], 0
	v_mfma_f32_16x16x32_bf16 v[16:19], v[204:207], v[172:175], 0
	v_mfma_f32_16x16x32_bf16 v[4:7], v[196:199], v[188:191], 0
	v_mfma_f32_16x16x32_bf16 v[0:3], v[204:207], v[188:191], 0
	v_mfma_f32_16x16x32_bf16 v[52:55], v[200:203], v[148:151], v[52:55]
	v_mfma_f32_16x16x32_bf16 v[48:51], v[208:211], v[148:151], v[48:51]
	v_mfma_f32_16x16x32_bf16 v[36:39], v[200:203], v[156:159], v[36:39]
	v_mfma_f32_16x16x32_bf16 v[32:35], v[208:211], v[156:159], v[32:35]
	v_mfma_f32_16x16x32_bf16 v[20:23], v[200:203], v[184:187], v[20:23]
	v_mfma_f32_16x16x32_bf16 v[16:19], v[208:211], v[184:187], v[16:19]
	v_mfma_f32_16x16x32_bf16 v[4:7], v[200:203], v[192:195], v[4:7]
	v_mfma_f32_16x16x32_bf16 v[0:3], v[208:211], v[192:195], v[0:3]
	s_add_i32 s17, 0, 0x18000
	v_add_u32_e32 v76, s17, v177
	s_barrier
	s_setprio 0
	ds_read_b128 v[56:59], v76
	ds_read_b128 v[68:71], v76 offset:1024
	ds_read_b128 v[72:75], v76 offset:2048
	ds_read_b128 v[76:79], v76 offset:3072
	s_add_u32 s10, s12, 0xb0000
	s_addc_u32 s11, s13, 0
	s_mov_b32 m0, s55
	v_lshl_add_u64 v[196:197], s[10:11], 0, v[160:161]
	ds_read_b128 v[144:147], v182 offset:32768
	ds_read_b128 v[148:151], v182 offset:33792
	ds_read_b128 v[152:155], v182 offset:34816
	ds_read_b128 v[156:159], v182 offset:35840
	ds_read_b128 v[172:175], v182 offset:36864
	ds_read_b128 v[184:187], v182 offset:37888
	ds_read_b128 v[188:191], v182 offset:38912
	ds_read_b128 v[192:195], v182 offset:39936
	global_load_lds_dwordx4 v[196:197], off
	v_lshl_add_u64 v[196:197], s[10:11], 0, v[162:163]
	s_mov_b32 m0, s56
	s_nop 0
	global_load_lds_dwordx4 v[196:197], off
	s_waitcnt lgkmcnt(8)
	s_setprio 1
	s_barrier
	s_waitcnt lgkmcnt(0)
	v_mfma_f32_16x16x32_bf16 v[136:139], v[56:59], v[144:147], v[136:139]
	v_mfma_f32_16x16x32_bf16 v[140:143], v[72:75], v[144:147], v[140:143]
	v_mfma_f32_16x16x32_bf16 v[124:127], v[56:59], v[152:155], v[124:127]
	v_mfma_f32_16x16x32_bf16 v[120:123], v[72:75], v[152:155], v[120:123]
	v_mfma_f32_16x16x32_bf16 v[108:111], v[56:59], v[172:175], v[108:111]
	v_mfma_f32_16x16x32_bf16 v[104:107], v[72:75], v[172:175], v[104:107]
	v_mfma_f32_16x16x32_bf16 v[92:95], v[56:59], v[188:191], v[92:95]
	v_mfma_f32_16x16x32_bf16 v[88:91], v[72:75], v[188:191], v[88:91]
	v_mfma_f32_16x16x32_bf16 v[136:139], v[68:71], v[148:151], v[136:139]
	v_mfma_f32_16x16x32_bf16 v[140:143], v[76:79], v[148:151], v[140:143]
	v_mfma_f32_16x16x32_bf16 v[124:127], v[68:71], v[156:159], v[124:127]
	v_mfma_f32_16x16x32_bf16 v[120:123], v[76:79], v[156:159], v[120:123]
	v_mfma_f32_16x16x32_bf16 v[108:111], v[68:71], v[184:187], v[108:111]
	v_mfma_f32_16x16x32_bf16 v[104:107], v[76:79], v[184:187], v[104:107]
	v_mfma_f32_16x16x32_bf16 v[92:95], v[68:71], v[192:195], v[92:95]
	v_mfma_f32_16x16x32_bf16 v[88:91], v[76:79], v[192:195], v[88:91]
	s_barrier
	s_setprio 0
	s_add_i32 s10, 0, 0x1c000
	s_add_i32 s11, s17, s52
	v_add_u32_e32 v208, s10, v177
	v_lshl_add_u64 v[212:213], v[212:213], 0, s[36:37]
	s_mov_b32 m0, s11
	ds_read_b128 v[196:199], v208
	ds_read_b128 v[200:203], v208 offset:1024
	ds_read_b128 v[204:207], v208 offset:2048
	ds_read_b128 v[208:211], v208 offset:3072
	global_load_lds_dwordx4 v[212:213], off
	v_lshl_add_u64 v[212:213], v[214:215], 0, s[36:37]
	s_add_i32 m0, s11, 0x2000
	s_nop 0
	global_load_lds_dwordx4 v[212:213], off
	s_setprio 1
	s_barrier
	s_waitcnt lgkmcnt(0)
	v_mfma_f32_16x16x32_bf16 v[132:135], v[196:199], v[144:147], v[132:135]
	v_mfma_f32_16x16x32_bf16 v[128:131], v[204:207], v[144:147], v[128:131]
	v_mfma_f32_16x16x32_bf16 v[116:119], v[196:199], v[152:155], v[116:119]
	v_mfma_f32_16x16x32_bf16 v[112:115], v[204:207], v[152:155], v[112:115]
	v_mfma_f32_16x16x32_bf16 v[100:103], v[196:199], v[172:175], v[100:103]
	v_mfma_f32_16x16x32_bf16 v[96:99], v[204:207], v[172:175], v[96:99]
	v_mfma_f32_16x16x32_bf16 v[84:87], v[196:199], v[188:191], v[84:87]
	v_mfma_f32_16x16x32_bf16 v[80:83], v[204:207], v[188:191], v[80:83]
	v_mfma_f32_16x16x32_bf16 v[132:135], v[200:203], v[148:151], v[132:135]
	v_mfma_f32_16x16x32_bf16 v[128:131], v[208:211], v[148:151], v[128:131]
	v_mfma_f32_16x16x32_bf16 v[116:119], v[200:203], v[156:159], v[116:119]
	v_mfma_f32_16x16x32_bf16 v[112:115], v[208:211], v[156:159], v[112:115]
	v_mfma_f32_16x16x32_bf16 v[100:103], v[200:203], v[184:187], v[100:103]
	v_mfma_f32_16x16x32_bf16 v[96:99], v[208:211], v[184:187], v[96:99]
	v_mfma_f32_16x16x32_bf16 v[84:87], v[200:203], v[192:195], v[84:87]
	v_mfma_f32_16x16x32_bf16 v[80:83], v[208:211], v[192:195], v[80:83]
	s_mov_b32 m0, s64
	v_lshl_add_u64 v[212:213], v[216:217], 0, s[36:37]
	s_barrier
	s_setprio 0
	ds_read_b128 v[144:147], v182 offset:49152
	ds_read_b128 v[148:151], v182 offset:50176
	ds_read_b128 v[152:155], v182 offset:51200
	ds_read_b128 v[156:159], v182 offset:52224
	ds_read_b128 v[172:175], v182 offset:53248
	ds_read_b128 v[184:187], v182 offset:54272
	ds_read_b128 v[188:191], v182 offset:55296
	ds_read_b128 v[192:195], v182 offset:56320
	global_load_lds_dwordx4 v[212:213], off
	v_lshl_add_u64 v[212:213], v[218:219], 0, s[36:37]
	s_mov_b32 m0, s65
	s_nop 0
	global_load_lds_dwordx4 v[212:213], off
	s_setprio 1
	s_barrier
	s_waitcnt lgkmcnt(0)
	v_mfma_f32_16x16x32_bf16 v[64:67], v[56:59], v[144:147], v[64:67]
	v_mfma_f32_16x16x32_bf16 v[60:63], v[72:75], v[144:147], v[60:63]
	v_mfma_f32_16x16x32_bf16 v[44:47], v[56:59], v[152:155], v[44:47]
	v_mfma_f32_16x16x32_bf16 v[40:43], v[72:75], v[152:155], v[40:43]
	v_mfma_f32_16x16x32_bf16 v[28:31], v[56:59], v[172:175], v[28:31]
	v_mfma_f32_16x16x32_bf16 v[24:27], v[72:75], v[172:175], v[24:27]
	v_mfma_f32_16x16x32_bf16 v[12:15], v[56:59], v[188:191], v[12:15]
	v_mfma_f32_16x16x32_bf16 v[8:11], v[72:75], v[188:191], v[8:11]
	v_mfma_f32_16x16x32_bf16 v[64:67], v[68:71], v[148:151], v[64:67]
	v_mfma_f32_16x16x32_bf16 v[60:63], v[76:79], v[148:151], v[60:63]
	v_mfma_f32_16x16x32_bf16 v[44:47], v[68:71], v[156:159], v[44:47]
	v_mfma_f32_16x16x32_bf16 v[40:43], v[76:79], v[156:159], v[40:43]
	v_mfma_f32_16x16x32_bf16 v[28:31], v[68:71], v[184:187], v[28:31]
	v_mfma_f32_16x16x32_bf16 v[24:27], v[76:79], v[184:187], v[24:27]
	v_mfma_f32_16x16x32_bf16 v[12:15], v[68:71], v[192:195], v[12:15]
	v_mfma_f32_16x16x32_bf16 v[8:11], v[76:79], v[192:195], v[8:11]
	s_barrier
	s_setprio 0
	s_add_u32 s8, s8, 0xb0080
	s_addc_u32 s9, s9, 0
	s_add_i32 s10, s10, s52
	v_lshl_add_u64 v[56:57], s[8:9], 0, v[160:161]
	s_mov_b32 m0, s10
	s_nop 0
	global_load_lds_dwordx4 v[56:57], off
	v_lshl_add_u64 v[56:57], s[8:9], 0, v[162:163]
	s_add_i32 m0, s10, 0x2000
	s_nop 0
	global_load_lds_dwordx4 v[56:57], off
	s_waitcnt vmcnt(6)
	s_setprio 1
	s_barrier
	v_mfma_f32_16x16x32_bf16 v[52:55], v[196:199], v[144:147], v[52:55]
	v_mfma_f32_16x16x32_bf16 v[48:51], v[204:207], v[144:147], v[48:51]
	v_mfma_f32_16x16x32_bf16 v[36:39], v[196:199], v[152:155], v[36:39]
	v_mfma_f32_16x16x32_bf16 v[32:35], v[204:207], v[152:155], v[32:35]
	v_mfma_f32_16x16x32_bf16 v[20:23], v[196:199], v[172:175], v[20:23]
	v_mfma_f32_16x16x32_bf16 v[16:19], v[204:207], v[172:175], v[16:19]
	v_mfma_f32_16x16x32_bf16 v[4:7], v[196:199], v[188:191], v[4:7]
	v_mfma_f32_16x16x32_bf16 v[0:3], v[204:207], v[188:191], v[0:3]
	v_mfma_f32_16x16x32_bf16 v[52:55], v[200:203], v[148:151], v[52:55]
	v_mfma_f32_16x16x32_bf16 v[48:51], v[208:211], v[148:151], v[48:51]
	v_mfma_f32_16x16x32_bf16 v[36:39], v[200:203], v[156:159], v[36:39]
	v_mfma_f32_16x16x32_bf16 v[32:35], v[208:211], v[156:159], v[32:35]
	v_mfma_f32_16x16x32_bf16 v[20:23], v[200:203], v[184:187], v[20:23]
	v_mfma_f32_16x16x32_bf16 v[16:19], v[208:211], v[184:187], v[16:19]
	v_mfma_f32_16x16x32_bf16 v[4:7], v[200:203], v[192:195], v[4:7]
	v_mfma_f32_16x16x32_bf16 v[0:3], v[208:211], v[192:195], v[0:3]
	s_add_u32 s14, s14, 0x100
	s_addc_u32 s15, s15, 0
	s_cmp_lt_i32 s16, s62
	s_mov_b64 s[10:11], s[6:7]
	s_mov_b32 s8, s16
	s_barrier
	s_setprio 0
	s_cbranch_scc0 .Lpeel_done_P11
.LBB0_798:
	ds_read_b128 v[56:59], v181
	ds_read_b128 v[68:71], v181 offset:1024
	ds_read_b128 v[72:75], v181 offset:2048
	ds_read_b128 v[76:79], v181 offset:3072
	s_add_i32 s16, s8, 2
	s_add_u32 s6, s10, 0x100
	s_addc_u32 s7, s11, 0
	s_cmp_eq_u32 s66, s8
	s_cselect_b32 s8, s48, s14
	s_cselect_b32 s13, s47, s7
	s_cselect_b32 s12, s46, s6
	s_cselect_b32 s9, s49, s15
	v_lshl_add_u64 v[196:197], s[10:11], 0, v[164:165]
	s_add_i32 m0, s53, 0xc000
	ds_read_b128 v[144:147], v182
	ds_read_b128 v[148:151], v182 offset:1024
	ds_read_b128 v[152:155], v182 offset:2048
	ds_read_b128 v[156:159], v182 offset:3072
	ds_read_b128 v[172:175], v182 offset:4096
	ds_read_b128 v[184:187], v182 offset:5120
	ds_read_b128 v[188:191], v182 offset:6144
	ds_read_b128 v[192:195], v182 offset:7168
	global_load_lds_dwordx4 v[196:197], off
	v_lshl_add_u64 v[196:197], s[10:11], 0, v[166:167]
	s_add_i32 m0, s53, 0xe000
	s_nop 0
	global_load_lds_dwordx4 v[196:197], off
	s_waitcnt lgkmcnt(8)
	s_setprio 1
	s_barrier
	s_waitcnt lgkmcnt(0)
	v_mfma_f32_16x16x32_bf16 v[136:139], v[56:59], v[144:147], v[136:139]
	v_mfma_f32_16x16x32_bf16 v[140:143], v[72:75], v[144:147], v[140:143]
	v_mfma_f32_16x16x32_bf16 v[124:127], v[56:59], v[152:155], v[124:127]
	v_mfma_f32_16x16x32_bf16 v[120:123], v[72:75], v[152:155], v[120:123]
	v_mfma_f32_16x16x32_bf16 v[108:111], v[56:59], v[172:175], v[108:111]
	v_mfma_f32_16x16x32_bf16 v[104:107], v[72:75], v[172:175], v[104:107]
	v_mfma_f32_16x16x32_bf16 v[92:95], v[56:59], v[188:191], v[92:95]
	v_mfma_f32_16x16x32_bf16 v[88:91], v[72:75], v[188:191], v[88:91]
	v_mfma_f32_16x16x32_bf16 v[136:139], v[68:71], v[148:151], v[136:139]
	v_mfma_f32_16x16x32_bf16 v[140:143], v[76:79], v[148:151], v[140:143]
	v_mfma_f32_16x16x32_bf16 v[124:127], v[68:71], v[156:159], v[124:127]
	v_mfma_f32_16x16x32_bf16 v[120:123], v[76:79], v[156:159], v[120:123]
	v_mfma_f32_16x16x32_bf16 v[108:111], v[68:71], v[184:187], v[108:111]
	v_mfma_f32_16x16x32_bf16 v[104:107], v[76:79], v[184:187], v[104:107]
	v_mfma_f32_16x16x32_bf16 v[92:95], v[68:71], v[192:195], v[92:95]
	v_mfma_f32_16x16x32_bf16 v[88:91], v[76:79], v[192:195], v[88:91]
	s_barrier
	s_setprio 0
	s_add_i32 s10, s88, s52
	v_lshl_add_u64 v[212:213], s[8:9], 0, v[160:161]
	s_mov_b32 m0, s10
	ds_read_b128 v[196:199], v183
	ds_read_b128 v[200:203], v183 offset:1024
	ds_read_b128 v[204:207], v183 offset:2048
	ds_read_b128 v[208:211], v183 offset:3072
	global_load_lds_dwordx4 v[212:213], off
	v_lshl_add_u64 v[214:215], s[8:9], 0, v[162:163]
	s_add_i32 m0, s10, 0x2000
	s_nop 0
	global_load_lds_dwordx4 v[214:215], off
	s_setprio 1
	s_barrier
	s_waitcnt lgkmcnt(0)
	v_mfma_f32_16x16x32_bf16 v[132:135], v[196:199], v[144:147], v[132:135]
	v_mfma_f32_16x16x32_bf16 v[128:131], v[204:207], v[144:147], v[128:131]
	v_mfma_f32_16x16x32_bf16 v[116:119], v[196:199], v[152:155], v[116:119]
	v_mfma_f32_16x16x32_bf16 v[112:115], v[204:207], v[152:155], v[112:115]
	v_mfma_f32_16x16x32_bf16 v[100:103], v[196:199], v[172:175], v[100:103]
	v_mfma_f32_16x16x32_bf16 v[96:99], v[204:207], v[172:175], v[96:99]
	v_mfma_f32_16x16x32_bf16 v[84:87], v[196:199], v[188:191], v[84:87]
	v_mfma_f32_16x16x32_bf16 v[80:83], v[204:207], v[188:191], v[80:83]
	v_mfma_f32_16x16x32_bf16 v[132:135], v[200:203], v[148:151], v[132:135]
	v_mfma_f32_16x16x32_bf16 v[128:131], v[208:211], v[148:151], v[128:131]
	v_mfma_f32_16x16x32_bf16 v[116:119], v[200:203], v[156:159], v[116:119]
	v_mfma_f32_16x16x32_bf16 v[112:115], v[208:211], v[156:159], v[112:115]
	v_mfma_f32_16x16x32_bf16 v[100:103], v[200:203], v[184:187], v[100:103]
	v_mfma_f32_16x16x32_bf16 v[96:99], v[208:211], v[184:187], v[96:99]
	v_mfma_f32_16x16x32_bf16 v[84:87], v[200:203], v[192:195], v[84:87]
	v_mfma_f32_16x16x32_bf16 v[80:83], v[208:211], v[192:195], v[80:83]
	s_mov_b32 m0, s53
	v_lshl_add_u64 v[216:217], s[12:13], 0, v[160:161]
	s_barrier
	s_setprio 0
	ds_read_b128 v[144:147], v182 offset:16384
	ds_read_b128 v[148:151], v182 offset:17408
	ds_read_b128 v[152:155], v182 offset:18432
	ds_read_b128 v[156:159], v182 offset:19456
	ds_read_b128 v[172:175], v182 offset:20480
	ds_read_b128 v[184:187], v182 offset:21504
	ds_read_b128 v[188:191], v182 offset:22528
	ds_read_b128 v[192:195], v182 offset:23552
	global_load_lds_dwordx4 v[216:217], off
	v_lshl_add_u64 v[218:219], s[12:13], 0, v[162:163]
	s_mov_b32 m0, s54
	s_nop 0
	global_load_lds_dwordx4 v[218:219], off
	s_setprio 1
	s_barrier
	s_waitcnt lgkmcnt(0)
	v_mfma_f32_16x16x32_bf16 v[64:67], v[56:59], v[144:147], v[64:67]
	v_mfma_f32_16x16x32_bf16 v[60:63], v[72:75], v[144:147], v[60:63]
	v_mfma_f32_16x16x32_bf16 v[44:47], v[56:59], v[152:155], v[44:47]
	v_mfma_f32_16x16x32_bf16 v[40:43], v[72:75], v[152:155], v[40:43]
	v_mfma_f32_16x16x32_bf16 v[28:31], v[56:59], v[172:175], v[28:31]
	v_mfma_f32_16x16x32_bf16 v[24:27], v[72:75], v[172:175], v[24:27]
	v_mfma_f32_16x16x32_bf16 v[12:15], v[56:59], v[188:191], v[12:15]
	v_mfma_f32_16x16x32_bf16 v[8:11], v[72:75], v[188:191], v[8:11]
	v_mfma_f32_16x16x32_bf16 v[64:67], v[68:71], v[148:151], v[64:67]
	v_mfma_f32_16x16x32_bf16 v[60:63], v[76:79], v[148:151], v[60:63]
	v_mfma_f32_16x16x32_bf16 v[44:47], v[68:71], v[156:159], v[44:47]
	v_mfma_f32_16x16x32_bf16 v[40:43], v[76:79], v[156:159], v[40:43]
	v_mfma_f32_16x16x32_bf16 v[28:31], v[68:71], v[184:187], v[28:31]
	v_mfma_f32_16x16x32_bf16 v[24:27], v[76:79], v[184:187], v[24:27]
	v_mfma_f32_16x16x32_bf16 v[12:15], v[68:71], v[192:195], v[12:15]
	v_mfma_f32_16x16x32_bf16 v[8:11], v[76:79], v[192:195], v[8:11]
	s_barrier
	s_setprio 0
	s_add_u32 s10, s8, 0xb0000
	s_addc_u32 s11, s9, 0
	s_add_i32 s17, s89, s52
	v_lshl_add_u64 v[56:57], s[10:11], 0, v[160:161]
	s_mov_b32 m0, s17
	s_nop 0
	global_load_lds_dwordx4 v[56:57], off
	v_lshl_add_u64 v[56:57], s[10:11], 0, v[162:163]
	s_add_i32 m0, s17, 0x2000
	s_nop 0
	global_load_lds_dwordx4 v[56:57], off
	s_waitcnt vmcnt(6)
	s_setprio 1
	s_barrier
	v_mfma_f32_16x16x32_bf16 v[52:55], v[196:199], v[144:147], v[52:55]
	v_mfma_f32_16x16x32_bf16 v[48:51], v[204:207], v[144:147], v[48:51]
	v_mfma_f32_16x16x32_bf16 v[36:39], v[196:199], v[152:155], v[36:39]
	v_mfma_f32_16x16x32_bf16 v[32:35], v[204:207], v[152:155], v[32:35]
	v_mfma_f32_16x16x32_bf16 v[20:23], v[196:199], v[172:175], v[20:23]
	v_mfma_f32_16x16x32_bf16 v[16:19], v[204:207], v[172:175], v[16:19]
	v_mfma_f32_16x16x32_bf16 v[4:7], v[196:199], v[188:191], v[4:7]
	v_mfma_f32_16x16x32_bf16 v[0:3], v[204:207], v[188:191], v[0:3]
	v_mfma_f32_16x16x32_bf16 v[52:55], v[200:203], v[148:151], v[52:55]
	v_mfma_f32_16x16x32_bf16 v[48:51], v[208:211], v[148:151], v[48:51]
	v_mfma_f32_16x16x32_bf16 v[36:39], v[200:203], v[156:159], v[36:39]
	v_mfma_f32_16x16x32_bf16 v[32:35], v[208:211], v[156:159], v[32:35]
	v_mfma_f32_16x16x32_bf16 v[20:23], v[200:203], v[184:187], v[20:23]
	v_mfma_f32_16x16x32_bf16 v[16:19], v[208:211], v[184:187], v[16:19]
	v_mfma_f32_16x16x32_bf16 v[4:7], v[200:203], v[192:195], v[4:7]
	v_mfma_f32_16x16x32_bf16 v[0:3], v[208:211], v[192:195], v[0:3]
	s_add_i32 s17, 0, 0x18000
	v_add_u32_e32 v76, s17, v177
	s_barrier
	s_setprio 0
	ds_read_b128 v[56:59], v76
	ds_read_b128 v[68:71], v76 offset:1024
	ds_read_b128 v[72:75], v76 offset:2048
	ds_read_b128 v[76:79], v76 offset:3072
	s_add_u32 s10, s12, 0xb0000
	s_addc_u32 s11, s13, 0
	s_mov_b32 m0, s55
	v_lshl_add_u64 v[196:197], s[10:11], 0, v[160:161]
	ds_read_b128 v[144:147], v182 offset:32768
	ds_read_b128 v[148:151], v182 offset:33792
	ds_read_b128 v[152:155], v182 offset:34816
	ds_read_b128 v[156:159], v182 offset:35840
	ds_read_b128 v[172:175], v182 offset:36864
	ds_read_b128 v[184:187], v182 offset:37888
	ds_read_b128 v[188:191], v182 offset:38912
	ds_read_b128 v[192:195], v182 offset:39936
	global_load_lds_dwordx4 v[196:197], off
	v_lshl_add_u64 v[196:197], s[10:11], 0, v[162:163]
	s_mov_b32 m0, s56
	s_nop 0
	global_load_lds_dwordx4 v[196:197], off
	s_waitcnt lgkmcnt(8)
	s_setprio 1
	s_barrier
	s_waitcnt lgkmcnt(0)
	v_mfma_f32_16x16x32_bf16 v[136:139], v[56:59], v[144:147], v[136:139]
	v_mfma_f32_16x16x32_bf16 v[140:143], v[72:75], v[144:147], v[140:143]
	v_mfma_f32_16x16x32_bf16 v[124:127], v[56:59], v[152:155], v[124:127]
	v_mfma_f32_16x16x32_bf16 v[120:123], v[72:75], v[152:155], v[120:123]
	v_mfma_f32_16x16x32_bf16 v[108:111], v[56:59], v[172:175], v[108:111]
	v_mfma_f32_16x16x32_bf16 v[104:107], v[72:75], v[172:175], v[104:107]
	v_mfma_f32_16x16x32_bf16 v[92:95], v[56:59], v[188:191], v[92:95]
	v_mfma_f32_16x16x32_bf16 v[88:91], v[72:75], v[188:191], v[88:91]
	v_mfma_f32_16x16x32_bf16 v[136:139], v[68:71], v[148:151], v[136:139]
	v_mfma_f32_16x16x32_bf16 v[140:143], v[76:79], v[148:151], v[140:143]
	v_mfma_f32_16x16x32_bf16 v[124:127], v[68:71], v[156:159], v[124:127]
	v_mfma_f32_16x16x32_bf16 v[120:123], v[76:79], v[156:159], v[120:123]
	v_mfma_f32_16x16x32_bf16 v[108:111], v[68:71], v[184:187], v[108:111]
	v_mfma_f32_16x16x32_bf16 v[104:107], v[76:79], v[184:187], v[104:107]
	v_mfma_f32_16x16x32_bf16 v[92:95], v[68:71], v[192:195], v[92:95]
	v_mfma_f32_16x16x32_bf16 v[88:91], v[76:79], v[192:195], v[88:91]
	s_barrier
	s_setprio 0
	s_add_i32 s10, 0, 0x1c000
	s_add_i32 s11, s17, s52
	v_add_u32_e32 v208, s10, v177
	v_lshl_add_u64 v[212:213], v[212:213], 0, s[36:37]
	s_mov_b32 m0, s11
	ds_read_b128 v[196:199], v208
	ds_read_b128 v[200:203], v208 offset:1024
	ds_read_b128 v[204:207], v208 offset:2048
	ds_read_b128 v[208:211], v208 offset:3072
	global_load_lds_dwordx4 v[212:213], off
	v_lshl_add_u64 v[212:213], v[214:215], 0, s[36:37]
	s_add_i32 m0, s11, 0x2000
	s_nop 0
	global_load_lds_dwordx4 v[212:213], off
	s_setprio 1
	s_barrier
	s_waitcnt lgkmcnt(0)
	v_mfma_f32_16x16x32_bf16 v[132:135], v[196:199], v[144:147], v[132:135]
	v_mfma_f32_16x16x32_bf16 v[128:131], v[204:207], v[144:147], v[128:131]
	v_mfma_f32_16x16x32_bf16 v[116:119], v[196:199], v[152:155], v[116:119]
	v_mfma_f32_16x16x32_bf16 v[112:115], v[204:207], v[152:155], v[112:115]
	v_mfma_f32_16x16x32_bf16 v[100:103], v[196:199], v[172:175], v[100:103]
	v_mfma_f32_16x16x32_bf16 v[96:99], v[204:207], v[172:175], v[96:99]
	v_mfma_f32_16x16x32_bf16 v[84:87], v[196:199], v[188:191], v[84:87]
	v_mfma_f32_16x16x32_bf16 v[80:83], v[204:207], v[188:191], v[80:83]
	v_mfma_f32_16x16x32_bf16 v[132:135], v[200:203], v[148:151], v[132:135]
	v_mfma_f32_16x16x32_bf16 v[128:131], v[208:211], v[148:151], v[128:131]
	v_mfma_f32_16x16x32_bf16 v[116:119], v[200:203], v[156:159], v[116:119]
	v_mfma_f32_16x16x32_bf16 v[112:115], v[208:211], v[156:159], v[112:115]
	v_mfma_f32_16x16x32_bf16 v[100:103], v[200:203], v[184:187], v[100:103]
	v_mfma_f32_16x16x32_bf16 v[96:99], v[208:211], v[184:187], v[96:99]
	v_mfma_f32_16x16x32_bf16 v[84:87], v[200:203], v[192:195], v[84:87]
	v_mfma_f32_16x16x32_bf16 v[80:83], v[208:211], v[192:195], v[80:83]
	s_mov_b32 m0, s64
	v_lshl_add_u64 v[212:213], v[216:217], 0, s[36:37]
	s_barrier
	s_setprio 0
	ds_read_b128 v[144:147], v182 offset:49152
	ds_read_b128 v[148:151], v182 offset:50176
	ds_read_b128 v[152:155], v182 offset:51200
	ds_read_b128 v[156:159], v182 offset:52224
	ds_read_b128 v[172:175], v182 offset:53248
	ds_read_b128 v[184:187], v182 offset:54272
	ds_read_b128 v[188:191], v182 offset:55296
	ds_read_b128 v[192:195], v182 offset:56320
	global_load_lds_dwordx4 v[212:213], off
	v_lshl_add_u64 v[212:213], v[218:219], 0, s[36:37]
	s_mov_b32 m0, s65
	s_nop 0
	global_load_lds_dwordx4 v[212:213], off
	s_setprio 1
	s_barrier
	s_waitcnt lgkmcnt(0)
	v_mfma_f32_16x16x32_bf16 v[64:67], v[56:59], v[144:147], v[64:67]
	v_mfma_f32_16x16x32_bf16 v[60:63], v[72:75], v[144:147], v[60:63]
	v_mfma_f32_16x16x32_bf16 v[44:47], v[56:59], v[152:155], v[44:47]
	v_mfma_f32_16x16x32_bf16 v[40:43], v[72:75], v[152:155], v[40:43]
	v_mfma_f32_16x16x32_bf16 v[28:31], v[56:59], v[172:175], v[28:31]
	v_mfma_f32_16x16x32_bf16 v[24:27], v[72:75], v[172:175], v[24:27]
	v_mfma_f32_16x16x32_bf16 v[12:15], v[56:59], v[188:191], v[12:15]
	v_mfma_f32_16x16x32_bf16 v[8:11], v[72:75], v[188:191], v[8:11]
	v_mfma_f32_16x16x32_bf16 v[64:67], v[68:71], v[148:151], v[64:67]
	v_mfma_f32_16x16x32_bf16 v[60:63], v[76:79], v[148:151], v[60:63]
	v_mfma_f32_16x16x32_bf16 v[44:47], v[68:71], v[156:159], v[44:47]
	v_mfma_f32_16x16x32_bf16 v[40:43], v[76:79], v[156:159], v[40:43]
	v_mfma_f32_16x16x32_bf16 v[28:31], v[68:71], v[184:187], v[28:31]
	v_mfma_f32_16x16x32_bf16 v[24:27], v[76:79], v[184:187], v[24:27]
	v_mfma_f32_16x16x32_bf16 v[12:15], v[68:71], v[192:195], v[12:15]
	v_mfma_f32_16x16x32_bf16 v[8:11], v[76:79], v[192:195], v[8:11]
	s_barrier
	s_setprio 0
	s_add_u32 s8, s8, 0xb0080
	s_addc_u32 s9, s9, 0
	s_add_i32 s10, s10, s52
	v_lshl_add_u64 v[56:57], s[8:9], 0, v[160:161]
	s_mov_b32 m0, s10
	s_nop 0
	global_load_lds_dwordx4 v[56:57], off
	v_lshl_add_u64 v[56:57], s[8:9], 0, v[162:163]
	s_add_i32 m0, s10, 0x2000
	s_nop 0
	global_load_lds_dwordx4 v[56:57], off
	s_waitcnt vmcnt(6)
	s_setprio 1
	s_barrier
	v_mfma_f32_16x16x32_bf16 v[52:55], v[196:199], v[144:147], v[52:55]
	v_mfma_f32_16x16x32_bf16 v[48:51], v[204:207], v[144:147], v[48:51]
	v_mfma_f32_16x16x32_bf16 v[36:39], v[196:199], v[152:155], v[36:39]
	v_mfma_f32_16x16x32_bf16 v[32:35], v[204:207], v[152:155], v[32:35]
	v_mfma_f32_16x16x32_bf16 v[20:23], v[196:199], v[172:175], v[20:23]
	v_mfma_f32_16x16x32_bf16 v[16:19], v[204:207], v[172:175], v[16:19]
	v_mfma_f32_16x16x32_bf16 v[4:7], v[196:199], v[188:191], v[4:7]
	v_mfma_f32_16x16x32_bf16 v[0:3], v[204:207], v[188:191], v[0:3]
	v_mfma_f32_16x16x32_bf16 v[52:55], v[200:203], v[148:151], v[52:55]
	v_mfma_f32_16x16x32_bf16 v[48:51], v[208:211], v[148:151], v[48:51]
	v_mfma_f32_16x16x32_bf16 v[36:39], v[200:203], v[156:159], v[36:39]
	v_mfma_f32_16x16x32_bf16 v[32:35], v[208:211], v[156:159], v[32:35]
	v_mfma_f32_16x16x32_bf16 v[20:23], v[200:203], v[184:187], v[20:23]
	v_mfma_f32_16x16x32_bf16 v[16:19], v[208:211], v[184:187], v[16:19]
	v_mfma_f32_16x16x32_bf16 v[4:7], v[200:203], v[192:195], v[4:7]
	v_mfma_f32_16x16x32_bf16 v[0:3], v[208:211], v[192:195], v[0:3]
	s_add_u32 s14, s14, 0x100
	s_addc_u32 s15, s15, 0
	s_cmp_lt_i32 s16, s62
	s_mov_b64 s[10:11], s[6:7]
	s_mov_b32 s8, s16
	s_barrier
	s_setprio 0
	s_cbranch_scc1 .LBB0_798
